# K-loops: also removed the redundant s_waitcnt lgkmcnt(0) at the head of every MFMA block (the inline-asm lgkmcnt(0) before the barrier already drained the ds_reads)
# baseline (speedup 1.0000x reference)
; #define PG8_STAGE(bufoff, gbase, voff) do { _Pragma("unroll") for (int _i = 0; _i < 2; ++_i) \
;         __builtin_amdgcn_global_load_lds((const unsigned*)((const char*)(gbase) + (voff)[_i]), (PG8_LAS unsigned*)(lds + (bufoff) + ldsw + _i * 8192), 16, 0, 0); } while (0)
; #define PG8_LDA(dst, b, h) do { _Pragma("unroll") for (int m = 0; m < 4; ++m) _Pragma("unroll") for (int k = 0; k < 2; ++k) dst[m][k] = *(const PG8_LAS bf16x8*)(lds + PG8_SA(b, h) + aoff + m * 2048 + k * 1024); } while (0)
; #define PG8_LDB(dst, b, h) do { _Pragma("unroll") for (int n = 0; n < 2; ++n) _Pragma("unroll") for (int k = 0; k < 2; ++k) dst[n][k] = *(const PG8_LAS bf16x8*)(lds + PG8_SB(b, h) + boff + n * 2048 + k * 1024); } while (0)
; #define PG8_MMA(ai, bj, At, Bt) do { __builtin_amdgcn_s_setprio(1); _Pragma("unroll") for (int m = 0; m < 4; ++m) _Pragma("unroll") for (int n = 0; n < 2; ++n) _Pragma("unroll") for (int k = 0; k < 2; ++k) \
;         acc[ai][bj][m][n] = __builtin_amdgcn_mfma_f32_16x16x32_bf16(Bt[n][k], At[m][k], acc[ai][bj][m][n], 0, 0, 0); __builtin_amdgcn_s_setprio(0); } while (0)
; #define PG8_WAIT_V(n) asm volatile("s_waitcnt vmcnt(" #n ")" ::: "memory")
; #define PG8_WAIT_L(n) asm volatile("s_waitcnt lgkmcnt(" #n ")" ::: "memory")
; template <class Epi, class Sched, bool ALIGN_EPI = false, bool SP2 = false>
; __device__ __forceinline__ void gemm_phase(PG8_LAS unsigned char* lds, const Gemm g, const Sched& S, const Epi& E) {
;     ...
;             const bool last = (t == nt - 2);
;             const char* a1 = cA + (size_t)(t + 1) * kstep;
;             const char* a2 = last ? nA : cA + (size_t)(t + 2) * kstep; const char* b2 = last ? nB : cB + (size_t)(t + 2) * kstep;
;             const char* a3 = a2 + kstep; const char* b3 = b2 + kstep;
;             if (last && has_next) S.a_ready(nxt);
;             if constexpr (SP2) {
;             PG8_LDB(B0, 0, 0); PG8_LDB(B1, 0, 1); PG8_SCHED; PG8_LDA(At, 0, 0); PG8_STAGE(PG8_SA(1, 1), a1 + hstep, voffA);
;             PG8_WAIT_V(8); PG8_WAIT_L(0); PG8_BAR; PG8_MMA(0, 0, At, B0); PG8_MMA(0, 1, At, B1); PG8_BAR; PG8_SCHED;
;             PG8_LDA(At, 0, 1); PG8_STAGE(PG8_SB(0, 0), b2, voffB); PG8_STAGE(PG8_SB(0, 1), b2 + hstep, voffB); PG8_STAGE(PG8_SA(0, 0), a2, voffA);
;             PG8_WAIT_V(8); PG8_WAIT_L(0); PG8_BAR; PG8_MMA(1, 0, At, B0); PG8_MMA(1, 1, At, B1); PG8_BAR; PG8_SCHED;
.LBB0_283:
	ds_read_b128 v[148:151], v187
	ds_read_b128 v[152:155], v187 offset:1024
	ds_read_b128 v[156:159], v187 offset:2048
	ds_read_b128 v[160:163], v187 offset:3072
	ds_read_b128 v[164:167], v183
	ds_read_b128 v[168:171], v183 offset:1024
	ds_read_b128 v[192:195], v183 offset:2048
	ds_read_b128 v[196:199], v183 offset:3072
	s_add_u32 s6, s10, s4
	s_addc_u32 s7, s11, s5
	s_add_u32 s6, s6, 0xc000100
	s_addc_u32 s7, s7, 0
	s_add_u32 s53, s35, s4
	s_addc_u32 s54, s36, s5
	s_cmpk_eq_i32 s4, 0x700
	s_cselect_b32 s9, s19, s7
	s_cselect_b32 s8, s18, s6
	s_cselect_b32 s7, s29, s54
	s_cselect_b32 s6, s34, s53
	v_lshl_add_u64 v[172:173], v[144:145], 0, s[4:5]
	s_add_i32 m0, s3, 0xc000
	ds_read_b128 v[200:203], v184
	ds_read_b128 v[204:207], v184 offset:1024
	ds_read_b128 v[208:211], v184 offset:2048
	ds_read_b128 v[212:215], v184 offset:3072
	ds_read_b128 v[216:219], v184 offset:4096
	ds_read_b128 v[220:223], v184 offset:5120
	ds_read_b128 v[224:227], v184 offset:6144
	ds_read_b128 v[228:231], v184 offset:7168
	global_load_lds_dwordx4 v[172:173], off
	v_lshl_add_u64 v[172:173], v[146:147], 0, s[4:5]
	s_add_i32 m0, s3, 0xe000
	s_nop 0
	global_load_lds_dwordx4 v[172:173], off
	s_waitcnt vmcnt(8)
	s_waitcnt lgkmcnt(0)
	s_barrier
	s_setprio 1
	v_mfma_f32_16x16x32_bf16 v[124:127], v[148:151], v[200:203], v[124:127]
	v_mfma_f32_16x16x32_bf16 v[120:123], v[156:159], v[200:203], v[120:123]
	v_mfma_f32_16x16x32_bf16 v[108:111], v[148:151], v[208:211], v[108:111]
	v_mfma_f32_16x16x32_bf16 v[104:107], v[156:159], v[208:211], v[104:107]
	v_mfma_f32_16x16x32_bf16 v[92:95], v[148:151], v[216:219], v[92:95]
	v_mfma_f32_16x16x32_bf16 v[88:91], v[156:159], v[216:219], v[88:91]
	v_mfma_f32_16x16x32_bf16 v[76:79], v[148:151], v[224:227], v[76:79]
	v_mfma_f32_16x16x32_bf16 v[72:75], v[156:159], v[224:227], v[72:75]
	v_mfma_f32_16x16x32_bf16 v[124:127], v[152:155], v[204:207], v[124:127]
	v_mfma_f32_16x16x32_bf16 v[120:123], v[160:163], v[204:207], v[120:123]
	v_mfma_f32_16x16x32_bf16 v[108:111], v[152:155], v[212:215], v[108:111]
	v_mfma_f32_16x16x32_bf16 v[104:107], v[160:163], v[212:215], v[104:107]
	v_mfma_f32_16x16x32_bf16 v[92:95], v[152:155], v[220:223], v[92:95]
	v_mfma_f32_16x16x32_bf16 v[88:91], v[160:163], v[220:223], v[88:91]
	v_mfma_f32_16x16x32_bf16 v[76:79], v[152:155], v[228:231], v[76:79]
	v_mfma_f32_16x16x32_bf16 v[72:75], v[160:163], v[228:231], v[72:75]
	v_mfma_f32_16x16x32_bf16 v[116:119], v[164:167], v[200:203], v[116:119]
	v_mfma_f32_16x16x32_bf16 v[112:115], v[192:195], v[200:203], v[112:115]
	v_mfma_f32_16x16x32_bf16 v[100:103], v[164:167], v[208:211], v[100:103]
	v_mfma_f32_16x16x32_bf16 v[96:99], v[192:195], v[208:211], v[96:99]
	v_mfma_f32_16x16x32_bf16 v[84:87], v[164:167], v[216:219], v[84:87]
	v_mfma_f32_16x16x32_bf16 v[80:83], v[192:195], v[216:219], v[80:83]
	v_mfma_f32_16x16x32_bf16 v[68:71], v[164:167], v[224:227], v[68:71]
	v_mfma_f32_16x16x32_bf16 v[64:67], v[192:195], v[224:227], v[64:67]
	v_mfma_f32_16x16x32_bf16 v[116:119], v[168:171], v[204:207], v[116:119]
	v_mfma_f32_16x16x32_bf16 v[112:115], v[196:199], v[204:207], v[112:115]
	v_mfma_f32_16x16x32_bf16 v[100:103], v[168:171], v[212:215], v[100:103]
	v_mfma_f32_16x16x32_bf16 v[96:99], v[196:199], v[212:215], v[96:99]
	v_mfma_f32_16x16x32_bf16 v[84:87], v[168:171], v[220:223], v[84:87]
	v_mfma_f32_16x16x32_bf16 v[80:83], v[196:199], v[220:223], v[80:83]
	v_mfma_f32_16x16x32_bf16 v[68:71], v[168:171], v[228:231], v[68:71]
	v_mfma_f32_16x16x32_bf16 v[64:67], v[196:199], v[228:231], v[64:67]
	s_setprio 0
	s_barrier
	s_add_i32 s53, s51, s38
	v_lshl_add_u64 v[172:173], s[6:7], 0, v[138:139]
	s_mov_b32 m0, s53
	ds_read_b128 v[200:203], v184 offset:16384
	ds_read_b128 v[204:207], v184 offset:17408
	ds_read_b128 v[208:211], v184 offset:18432
	ds_read_b128 v[212:215], v184 offset:19456
	ds_read_b128 v[216:219], v184 offset:20480
	ds_read_b128 v[220:223], v184 offset:21504
	ds_read_b128 v[224:227], v184 offset:22528
	ds_read_b128 v[228:231], v184 offset:23552
	global_load_lds_dwordx4 v[172:173], off
	s_add_i32 m0, s53, 0x2000
	s_add_u32 s54, s6, 0x40000
	v_lshl_add_u64 v[188:189], s[6:7], 0, v[134:135]
	s_addc_u32 s55, s7, 0
	s_add_i32 s53, s48, s38
	global_load_lds_dwordx4 v[188:189], off
	v_lshl_add_u64 v[232:233], s[54:55], 0, v[138:139]
	s_mov_b32 m0, s53
	v_lshl_add_u64 v[234:235], s[8:9], 0, v[136:137]
	global_load_lds_dwordx4 v[232:233], off
	v_lshl_add_u64 v[232:233], s[54:55], 0, v[134:135]
	s_add_i32 m0, s53, 0x2000
	s_nop 0
	global_load_lds_dwordx4 v[232:233], off
	v_lshl_add_u64 v[232:233], s[8:9], 0, v[140:141]
	s_mov_b32 m0, s3
	s_nop 0
	global_load_lds_dwordx4 v[232:233], off
	s_mov_b32 m0, s39
	s_nop 0
	global_load_lds_dwordx4 v[234:235], off
	s_waitcnt vmcnt(8)
	s_waitcnt lgkmcnt(0)
	s_barrier
; #define PG8_STAGE(bufoff, gbase, voff) do { _Pragma("unroll") for (int _i = 0; _i < 2; ++_i) \
;         __builtin_amdgcn_global_load_lds((const unsigned*)((const char*)(gbase) + (voff)[_i]), (PG8_LAS unsigned*)(lds + (bufoff) + ldsw + _i * 8192), 16, 0, 0); } while (0)
; #define PG8_LDA(dst, b, h) do { _Pragma("unroll") for (int m = 0; m < 4; ++m) _Pragma("unroll") for (int k = 0; k < 2; ++k) dst[m][k] = *(const PG8_LAS bf16x8*)(lds + PG8_SA(b, h) + aoff + m * 2048 + k * 1024); } while (0)
; #define PG8_LDB(dst, b, h) do { _Pragma("unroll") for (int n = 0; n < 2; ++n) _Pragma("unroll") for (int k = 0; k < 2; ++k) dst[n][k] = *(const PG8_LAS bf16x8*)(lds + PG8_SB(b, h) + boff + n * 2048 + k * 1024); } while (0)
; #define PG8_MMA(ai, bj, At, Bt) do { __builtin_amdgcn_s_setprio(1); _Pragma("unroll") for (int m = 0; m < 4; ++m) _Pragma("unroll") for (int n = 0; n < 2; ++n) _Pragma("unroll") for (int k = 0; k < 2; ++k) \
;         acc[ai][bj][m][n] = __builtin_amdgcn_mfma_f32_16x16x32_bf16(Bt[n][k], At[m][k], acc[ai][bj][m][n], 0, 0, 0); __builtin_amdgcn_s_setprio(0); } while (0)
; #define PG8_WAIT_V(n) asm volatile("s_waitcnt vmcnt(" #n ")" ::: "memory")
; #define PG8_WAIT_L(n) asm volatile("s_waitcnt lgkmcnt(" #n ")" ::: "memory")
; #define PG8_BAR __builtin_amdgcn_s_barrier()
; #define PG8_SCHED __builtin_amdgcn_sched_barrier(0)
; template <class Epi, class Sched, bool ALIGN_EPI = false, bool SP2 = false>
; __device__ __forceinline__ void gemm_phase(PG8_LAS unsigned char* lds, const Gemm g, const Sched& S, const Epi& E) {
;     ...
;             PG8_WAIT_V(8); PG8_WAIT_L(0); PG8_BAR; PG8_MMA(1, 0, At, B0); PG8_MMA(1, 1, At, B1); PG8_BAR; PG8_SCHED;
;             PG8_LDB(B0, 1, 0); PG8_LDB(B1, 1, 1); PG8_SCHED; PG8_LDA(At, 1, 0); PG8_STAGE(PG8_SA(0, 1), a2 + hstep, voffA);
;             PG8_WAIT_V(8); PG8_WAIT_L(0); PG8_BAR; PG8_MMA(0, 0, At, B0); PG8_MMA(0, 1, At, B1); PG8_BAR; PG8_SCHED;
	s_setprio 1
	v_mfma_f32_16x16x32_bf16 v[60:63], v[148:151], v[200:203], v[60:63]
	v_mfma_f32_16x16x32_bf16 v[56:59], v[156:159], v[200:203], v[56:59]
	v_mfma_f32_16x16x32_bf16 v[44:47], v[148:151], v[208:211], v[44:47]
	v_mfma_f32_16x16x32_bf16 v[40:43], v[156:159], v[208:211], v[40:43]
	v_mfma_f32_16x16x32_bf16 v[28:31], v[148:151], v[216:219], v[28:31]
	v_mfma_f32_16x16x32_bf16 v[24:27], v[156:159], v[216:219], v[24:27]
	v_mfma_f32_16x16x32_bf16 v[12:15], v[148:151], v[224:227], v[12:15]
	v_mfma_f32_16x16x32_bf16 v[8:11], v[156:159], v[224:227], v[8:11]
	v_mfma_f32_16x16x32_bf16 v[60:63], v[152:155], v[204:207], v[60:63]
	v_mfma_f32_16x16x32_bf16 v[56:59], v[160:163], v[204:207], v[56:59]
	v_mfma_f32_16x16x32_bf16 v[44:47], v[152:155], v[212:215], v[44:47]
	v_mfma_f32_16x16x32_bf16 v[40:43], v[160:163], v[212:215], v[40:43]
	v_mfma_f32_16x16x32_bf16 v[28:31], v[152:155], v[220:223], v[28:31]
	v_mfma_f32_16x16x32_bf16 v[24:27], v[160:163], v[220:223], v[24:27]
	v_mfma_f32_16x16x32_bf16 v[12:15], v[152:155], v[228:231], v[12:15]
	v_mfma_f32_16x16x32_bf16 v[8:11], v[160:163], v[228:231], v[8:11]
	v_mfma_f32_16x16x32_bf16 v[52:55], v[164:167], v[200:203], v[52:55]
	v_mfma_f32_16x16x32_bf16 v[48:51], v[192:195], v[200:203], v[48:51]
	v_mfma_f32_16x16x32_bf16 v[36:39], v[164:167], v[208:211], v[36:39]
	v_mfma_f32_16x16x32_bf16 v[32:35], v[192:195], v[208:211], v[32:35]
	v_mfma_f32_16x16x32_bf16 v[20:23], v[164:167], v[216:219], v[20:23]
	v_mfma_f32_16x16x32_bf16 v[16:19], v[192:195], v[216:219], v[16:19]
	v_mfma_f32_16x16x32_bf16 v[4:7], v[164:167], v[224:227], v[4:7]
	v_mfma_f32_16x16x32_bf16 v[0:3], v[192:195], v[224:227], v[0:3]
	v_mfma_f32_16x16x32_bf16 v[52:55], v[168:171], v[204:207], v[52:55]
	v_mfma_f32_16x16x32_bf16 v[48:51], v[196:199], v[204:207], v[48:51]
	v_mfma_f32_16x16x32_bf16 v[36:39], v[168:171], v[212:215], v[36:39]
	v_mfma_f32_16x16x32_bf16 v[32:35], v[196:199], v[212:215], v[32:35]
	v_mfma_f32_16x16x32_bf16 v[20:23], v[168:171], v[220:223], v[20:23]
	v_mfma_f32_16x16x32_bf16 v[16:19], v[196:199], v[220:223], v[16:19]
	v_mfma_f32_16x16x32_bf16 v[4:7], v[168:171], v[228:231], v[4:7]
	v_mfma_f32_16x16x32_bf16 v[0:3], v[196:199], v[228:231], v[0:3]
	s_setprio 0
	s_barrier
	s_add_i32 s53, 0, 0x18000
	s_add_i32 s54, 0, 0x1c000
	v_add_u32_e32 v160, s53, v133
	v_add_u32_e32 v191, s54, v133
	ds_read_b128 v[148:151], v160
	ds_read_b128 v[152:155], v160 offset:1024
	ds_read_b128 v[156:159], v160 offset:2048
	ds_read_b128 v[160:163], v160 offset:3072
	ds_read_b128 v[164:167], v191
	ds_read_b128 v[168:171], v191 offset:1024
	ds_read_b128 v[192:195], v191 offset:2048
	ds_read_b128 v[196:199], v191 offset:3072
	s_add_u32 s8, s8, 0x40000
	s_addc_u32 s9, s9, 0
	s_mov_b32 m0, s40
	v_lshl_add_u64 v[236:237], s[8:9], 0, v[140:141]
	ds_read_b128 v[200:203], v184 offset:32768
	ds_read_b128 v[204:207], v184 offset:33792
	ds_read_b128 v[208:211], v184 offset:34816
	ds_read_b128 v[212:215], v184 offset:35840
	ds_read_b128 v[216:219], v184 offset:36864
	ds_read_b128 v[220:223], v184 offset:37888
	ds_read_b128 v[224:227], v184 offset:38912
	ds_read_b128 v[228:231], v184 offset:39936
	global_load_lds_dwordx4 v[236:237], off
	v_lshl_add_u64 v[236:237], s[8:9], 0, v[136:137]
	s_mov_b32 m0, s41
	s_nop 0
	global_load_lds_dwordx4 v[236:237], off
	s_waitcnt vmcnt(8)
	s_waitcnt lgkmcnt(0)
	s_barrier
	s_setprio 1
	v_mfma_f32_16x16x32_bf16 v[124:127], v[148:151], v[200:203], v[124:127]
	v_mfma_f32_16x16x32_bf16 v[120:123], v[156:159], v[200:203], v[120:123]
	v_mfma_f32_16x16x32_bf16 v[108:111], v[148:151], v[208:211], v[108:111]
	v_mfma_f32_16x16x32_bf16 v[104:107], v[156:159], v[208:211], v[104:107]
	v_mfma_f32_16x16x32_bf16 v[92:95], v[148:151], v[216:219], v[92:95]
	v_mfma_f32_16x16x32_bf16 v[88:91], v[156:159], v[216:219], v[88:91]
	v_mfma_f32_16x16x32_bf16 v[76:79], v[148:151], v[224:227], v[76:79]
	v_mfma_f32_16x16x32_bf16 v[72:75], v[156:159], v[224:227], v[72:75]
	v_mfma_f32_16x16x32_bf16 v[124:127], v[152:155], v[204:207], v[124:127]
	v_mfma_f32_16x16x32_bf16 v[120:123], v[160:163], v[204:207], v[120:123]
	v_mfma_f32_16x16x32_bf16 v[108:111], v[152:155], v[212:215], v[108:111]
	v_mfma_f32_16x16x32_bf16 v[104:107], v[160:163], v[212:215], v[104:107]
	v_mfma_f32_16x16x32_bf16 v[92:95], v[152:155], v[220:223], v[92:95]
	v_mfma_f32_16x16x32_bf16 v[88:91], v[160:163], v[220:223], v[88:91]
	v_mfma_f32_16x16x32_bf16 v[76:79], v[152:155], v[228:231], v[76:79]
	v_mfma_f32_16x16x32_bf16 v[72:75], v[160:163], v[228:231], v[72:75]
	v_mfma_f32_16x16x32_bf16 v[116:119], v[164:167], v[200:203], v[116:119]
	v_mfma_f32_16x16x32_bf16 v[112:115], v[192:195], v[200:203], v[112:115]
	v_mfma_f32_16x16x32_bf16 v[100:103], v[164:167], v[208:211], v[100:103]
	v_mfma_f32_16x16x32_bf16 v[96:99], v[192:195], v[208:211], v[96:99]
	v_mfma_f32_16x16x32_bf16 v[84:87], v[164:167], v[216:219], v[84:87]
	v_mfma_f32_16x16x32_bf16 v[80:83], v[192:195], v[216:219], v[80:83]
	v_mfma_f32_16x16x32_bf16 v[68:71], v[164:167], v[224:227], v[68:71]
	v_mfma_f32_16x16x32_bf16 v[64:67], v[192:195], v[224:227], v[64:67]
	v_mfma_f32_16x16x32_bf16 v[116:119], v[168:171], v[204:207], v[116:119]
	v_mfma_f32_16x16x32_bf16 v[112:115], v[196:199], v[204:207], v[112:115]
	v_mfma_f32_16x16x32_bf16 v[100:103], v[168:171], v[212:215], v[100:103]
	v_mfma_f32_16x16x32_bf16 v[96:99], v[196:199], v[212:215], v[96:99]
	v_mfma_f32_16x16x32_bf16 v[84:87], v[168:171], v[220:223], v[84:87]
	v_mfma_f32_16x16x32_bf16 v[80:83], v[196:199], v[220:223], v[80:83]
	v_mfma_f32_16x16x32_bf16 v[68:71], v[168:171], v[228:231], v[68:71]
	v_mfma_f32_16x16x32_bf16 v[64:67], v[196:199], v[228:231], v[64:67]
	s_setprio 0
	s_barrier
; #define PG8_STAGE(bufoff, gbase, voff) do { _Pragma("unroll") for (int _i = 0; _i < 2; ++_i) \
;         __builtin_amdgcn_global_load_lds((const unsigned*)((const char*)(gbase) + (voff)[_i]), (PG8_LAS unsigned*)(lds + (bufoff) + ldsw + _i * 8192), 16, 0, 0); } while (0)
; #define PG8_LDA(dst, b, h) do { _Pragma("unroll") for (int m = 0; m < 4; ++m) _Pragma("unroll") for (int k = 0; k < 2; ++k) dst[m][k] = *(const PG8_LAS bf16x8*)(lds + PG8_SA(b, h) + aoff + m * 2048 + k * 1024); } while (0)
; #define PG8_MMA(ai, bj, At, Bt) do { __builtin_amdgcn_s_setprio(1); _Pragma("unroll") for (int m = 0; m < 4; ++m) _Pragma("unroll") for (int n = 0; n < 2; ++n) _Pragma("unroll") for (int k = 0; k < 2; ++k) \
;         acc[ai][bj][m][n] = __builtin_amdgcn_mfma_f32_16x16x32_bf16(Bt[n][k], At[m][k], acc[ai][bj][m][n], 0, 0, 0); __builtin_amdgcn_s_setprio(0); } while (0)
; #define PG8_WAIT_V(n) asm volatile("s_waitcnt vmcnt(" #n ")" ::: "memory")
; #define PG8_WAIT_L(n) asm volatile("s_waitcnt lgkmcnt(" #n ")" ::: "memory")
; #define PG8_BAR __builtin_amdgcn_s_barrier()
; #define PG8_SCHED __builtin_amdgcn_sched_barrier(0)
; template <class Epi, class Sched, bool ALIGN_EPI = false, bool SP2 = false>
; __device__ __forceinline__ void gemm_phase(PG8_LAS unsigned char* lds, const Gemm g, const Sched& S, const Epi& E) {
;     ...
;             PG8_LDA(At, 1, 1); PG8_STAGE(PG8_SB(1, 0), b3, voffB); PG8_STAGE(PG8_SB(1, 1), b3 + hstep, voffB); PG8_STAGE(PG8_SA(1, 0), a3, voffA);
;             PG8_WAIT_V(8); PG8_WAIT_L(0); PG8_BAR; PG8_MMA(1, 0, At, B0); PG8_MMA(1, 1, At, B1); PG8_BAR; PG8_SCHED;
;     ...
;         }
;         if constexpr (ALIGN_EPI) { if (wr == 0) PG8_BAR; }
	s_add_i32 s8, s53, s38
	v_lshl_add_u64 v[172:173], v[172:173], 0, s[24:25]
	s_mov_b32 m0, s8
	ds_read_b128 v[200:203], v184 offset:49152
	ds_read_b128 v[204:207], v184 offset:50176
	ds_read_b128 v[208:211], v184 offset:51200
	ds_read_b128 v[212:215], v184 offset:52224
	ds_read_b128 v[216:219], v184 offset:53248
	ds_read_b128 v[220:223], v184 offset:54272
	ds_read_b128 v[224:227], v184 offset:55296
	ds_read_b128 v[228:231], v184 offset:56320
	global_load_lds_dwordx4 v[172:173], off
	s_add_i32 m0, s8, 0x2000
	s_add_u32 s6, s6, 0x40080
	v_lshl_add_u64 v[172:173], v[188:189], 0, s[24:25]
	s_addc_u32 s7, s7, 0
	s_add_i32 s8, s54, s38
	global_load_lds_dwordx4 v[172:173], off
	v_lshl_add_u64 v[172:173], s[6:7], 0, v[138:139]
	s_mov_b32 m0, s8
	s_nop 0
	global_load_lds_dwordx4 v[172:173], off
	v_lshl_add_u64 v[172:173], s[6:7], 0, v[134:135]
	s_add_i32 m0, s8, 0x2000
	s_nop 0
	global_load_lds_dwordx4 v[172:173], off
	v_lshl_add_u64 v[172:173], v[232:233], 0, s[24:25]
	s_mov_b32 m0, s43
	s_nop 0
	global_load_lds_dwordx4 v[172:173], off
	v_lshl_add_u64 v[172:173], v[234:235], 0, s[24:25]
	s_mov_b32 m0, s44
	s_nop 0
	global_load_lds_dwordx4 v[172:173], off
	s_waitcnt vmcnt(8)
	s_waitcnt lgkmcnt(0)
	s_barrier
	s_setprio 1
	v_mfma_f32_16x16x32_bf16 v[60:63], v[148:151], v[200:203], v[60:63]
	v_mfma_f32_16x16x32_bf16 v[56:59], v[156:159], v[200:203], v[56:59]
	v_mfma_f32_16x16x32_bf16 v[44:47], v[148:151], v[208:211], v[44:47]
	v_mfma_f32_16x16x32_bf16 v[40:43], v[156:159], v[208:211], v[40:43]
	v_mfma_f32_16x16x32_bf16 v[28:31], v[148:151], v[216:219], v[28:31]
	v_mfma_f32_16x16x32_bf16 v[24:27], v[156:159], v[216:219], v[24:27]
	v_mfma_f32_16x16x32_bf16 v[12:15], v[148:151], v[224:227], v[12:15]
	v_mfma_f32_16x16x32_bf16 v[8:11], v[156:159], v[224:227], v[8:11]
	v_mfma_f32_16x16x32_bf16 v[60:63], v[152:155], v[204:207], v[60:63]
	v_mfma_f32_16x16x32_bf16 v[56:59], v[160:163], v[204:207], v[56:59]
	v_mfma_f32_16x16x32_bf16 v[44:47], v[152:155], v[212:215], v[44:47]
	v_mfma_f32_16x16x32_bf16 v[40:43], v[160:163], v[212:215], v[40:43]
	v_mfma_f32_16x16x32_bf16 v[28:31], v[152:155], v[220:223], v[28:31]
	v_mfma_f32_16x16x32_bf16 v[24:27], v[160:163], v[220:223], v[24:27]
	v_mfma_f32_16x16x32_bf16 v[12:15], v[152:155], v[228:231], v[12:15]
	v_mfma_f32_16x16x32_bf16 v[8:11], v[160:163], v[228:231], v[8:11]
	v_mfma_f32_16x16x32_bf16 v[52:55], v[164:167], v[200:203], v[52:55]
	v_mfma_f32_16x16x32_bf16 v[48:51], v[192:195], v[200:203], v[48:51]
	v_mfma_f32_16x16x32_bf16 v[36:39], v[164:167], v[208:211], v[36:39]
	v_mfma_f32_16x16x32_bf16 v[32:35], v[192:195], v[208:211], v[32:35]
	v_mfma_f32_16x16x32_bf16 v[20:23], v[164:167], v[216:219], v[20:23]
	v_mfma_f32_16x16x32_bf16 v[16:19], v[192:195], v[216:219], v[16:19]
	v_mfma_f32_16x16x32_bf16 v[4:7], v[164:167], v[224:227], v[4:7]
	v_mfma_f32_16x16x32_bf16 v[0:3], v[192:195], v[224:227], v[0:3]
	v_mfma_f32_16x16x32_bf16 v[52:55], v[168:171], v[204:207], v[52:55]
	v_mfma_f32_16x16x32_bf16 v[48:51], v[196:199], v[204:207], v[48:51]
	v_mfma_f32_16x16x32_bf16 v[36:39], v[168:171], v[212:215], v[36:39]
	v_mfma_f32_16x16x32_bf16 v[32:35], v[196:199], v[212:215], v[32:35]
	v_mfma_f32_16x16x32_bf16 v[20:23], v[168:171], v[220:223], v[20:23]
	v_mfma_f32_16x16x32_bf16 v[16:19], v[196:199], v[220:223], v[16:19]
	v_mfma_f32_16x16x32_bf16 v[4:7], v[168:171], v[228:231], v[4:7]
	v_mfma_f32_16x16x32_bf16 v[0:3], v[196:199], v[228:231], v[0:3]
	s_setprio 0
	s_barrier
	s_add_i32 s37, s37, 2
	s_add_u32 s4, s4, 0x100
	s_addc_u32 s5, s5, 0
	s_cmp_gt_u32 s37, 13
	s_cbranch_scc0 .LBB0_283
	s_and_b64 vcc, exec, s[26:27]
	s_cbranch_vccz .LBB0_286
	s_barrier

; #define PG8_STAGE(bufoff, gbase, voff) do { _Pragma("unroll") for (int _i = 0; _i < 2; ++_i) \
;         __builtin_amdgcn_global_load_lds((const unsigned*)((const char*)(gbase) + (voff)[_i]), (PG8_LAS unsigned*)(lds + (bufoff) + ldsw + _i * 8192), 16, 0, 0); } while (0)
; #define PG8_LDA(dst, b, h) do { _Pragma("unroll") for (int m = 0; m < 4; ++m) _Pragma("unroll") for (int k = 0; k < 2; ++k) dst[m][k] = *(const PG8_LAS bf16x8*)(lds + PG8_SA(b, h) + aoff + m * 2048 + k * 1024); } while (0)
; #define PG8_LDB(dst, b, h) do { _Pragma("unroll") for (int n = 0; n < 2; ++n) _Pragma("unroll") for (int k = 0; k < 2; ++k) dst[n][k] = *(const PG8_LAS bf16x8*)(lds + PG8_SB(b, h) + boff + n * 2048 + k * 1024); } while (0)
; #define PG8_MMA(ai, bj, At, Bt) do { __builtin_amdgcn_s_setprio(1); _Pragma("unroll") for (int m = 0; m < 4; ++m) _Pragma("unroll") for (int n = 0; n < 2; ++n) _Pragma("unroll") for (int k = 0; k < 2; ++k) \
;         acc[ai][bj][m][n] = __builtin_amdgcn_mfma_f32_16x16x32_bf16(Bt[n][k], At[m][k], acc[ai][bj][m][n], 0, 0, 0); __builtin_amdgcn_s_setprio(0); } while (0)
; #define PG8_WAIT_V(n) asm volatile("s_waitcnt vmcnt(" #n ")" ::: "memory")
; #define PG8_WAIT_L(n) asm volatile("s_waitcnt lgkmcnt(" #n ")" ::: "memory")
; template <class Epi, class Sched, bool ALIGN_EPI = false, bool SP2 = false>
; __device__ __forceinline__ void gemm_phase(PG8_LAS unsigned char* lds, const Gemm g, const Sched& S, const Epi& E) {
;     ...
;             const bool last = (t == nt - 2);
;             const char* a1 = cA + (size_t)(t + 1) * kstep;
;             const char* a2 = last ? nA : cA + (size_t)(t + 2) * kstep; const char* b2 = last ? nB : cB + (size_t)(t + 2) * kstep;
;             const char* a3 = a2 + kstep; const char* b3 = b2 + kstep;
;             if (last && has_next) S.a_ready(nxt);
;             if constexpr (SP2) {
;             PG8_LDB(B0, 0, 0); PG8_LDB(B1, 0, 1); PG8_SCHED; PG8_LDA(At, 0, 0); PG8_STAGE(PG8_SA(1, 1), a1 + hstep, voffA);
;             PG8_WAIT_V(8); PG8_WAIT_L(0); PG8_BAR; PG8_MMA(0, 0, At, B0); PG8_MMA(0, 1, At, B1); PG8_BAR; PG8_SCHED;
;             PG8_LDA(At, 0, 1); PG8_STAGE(PG8_SB(0, 0), b2, voffB); PG8_STAGE(PG8_SB(0, 1), b2 + hstep, voffB); PG8_STAGE(PG8_SA(0, 0), a2, voffA);
;             PG8_WAIT_V(8); PG8_WAIT_L(0); PG8_BAR; PG8_MMA(1, 0, At, B0); PG8_MMA(1, 1, At, B1); PG8_BAR; PG8_SCHED;
.LBB0_592:
	s_add_u32 s4, s10, 0xfffc0080
	s_addc_u32 s5, s11, -1
	s_add_i32 s18, 0, 0x10000
	s_cmp_eq_u32 s64, 12
	s_cselect_b32 s15, s29, s5
	s_cselect_b32 s14, s38, s4
	s_cselect_b32 s13, s27, s55
	s_cselect_b32 s12, s39, s54
	s_add_i32 s4, 0, 0x14000
	v_add_u32_e32 v176, s18, v202
	v_add_u32_e32 v188, s4, v202
	ds_read_b128 v[164:167], v176
	ds_read_b128 v[168:171], v176 offset:1024
	ds_read_b128 v[172:175], v176 offset:2048
	ds_read_b128 v[176:179], v176 offset:3072
	ds_read_b128 v[180:183], v188
	ds_read_b128 v[184:187], v188 offset:1024
	ds_read_b128 v[206:209], v188 offset:2048
	ds_read_b128 v[210:213], v188 offset:3072
	v_lshl_add_u64 v[188:189], s[10:11], 0, v[160:161]
	s_add_i32 m0, s43, 0xc000
	ds_read_b128 v[214:217], v204
	ds_read_b128 v[218:221], v204 offset:1024
	ds_read_b128 v[222:225], v204 offset:2048
	ds_read_b128 v[226:229], v204 offset:3072
	ds_read_b128 v[230:233], v204 offset:4096
	ds_read_b128 v[234:237], v204 offset:5120
	ds_read_b128 v[238:241], v204 offset:6144
	ds_read_b128 v[242:245], v204 offset:7168
	global_load_lds_dwordx4 v[188:189], off
	v_lshl_add_u64 v[188:189], s[10:11], 0, v[162:163]
	s_add_i32 m0, s43, 0xe000
	s_nop 0
	global_load_lds_dwordx4 v[188:189], off
	s_waitcnt vmcnt(8)
	s_waitcnt lgkmcnt(0)
	s_barrier
	s_setprio 1
	v_mfma_f32_16x16x32_bf16 v[126:129], v[164:167], v[214:217], v[126:129]
	v_mfma_f32_16x16x32_bf16 v[122:125], v[172:175], v[214:217], v[122:125]
	v_mfma_f32_16x16x32_bf16 v[110:113], v[164:167], v[222:225], v[110:113]
	v_mfma_f32_16x16x32_bf16 v[106:109], v[172:175], v[222:225], v[106:109]
	v_mfma_f32_16x16x32_bf16 v[94:97], v[164:167], v[230:233], v[94:97]
	v_mfma_f32_16x16x32_bf16 v[90:93], v[172:175], v[230:233], v[90:93]
	v_mfma_f32_16x16x32_bf16 v[78:81], v[164:167], v[238:241], v[78:81]
	v_mfma_f32_16x16x32_bf16 v[74:77], v[172:175], v[238:241], v[74:77]
	v_mfma_f32_16x16x32_bf16 v[126:129], v[168:171], v[218:221], v[126:129]
	v_mfma_f32_16x16x32_bf16 v[122:125], v[176:179], v[218:221], v[122:125]
	v_mfma_f32_16x16x32_bf16 v[110:113], v[168:171], v[226:229], v[110:113]
	v_mfma_f32_16x16x32_bf16 v[106:109], v[176:179], v[226:229], v[106:109]
	v_mfma_f32_16x16x32_bf16 v[94:97], v[168:171], v[234:237], v[94:97]
	v_mfma_f32_16x16x32_bf16 v[90:93], v[176:179], v[234:237], v[90:93]
	v_mfma_f32_16x16x32_bf16 v[78:81], v[168:171], v[242:245], v[78:81]
	v_mfma_f32_16x16x32_bf16 v[74:77], v[176:179], v[242:245], v[74:77]
	v_mfma_f32_16x16x32_bf16 v[118:121], v[180:183], v[214:217], v[118:121]
	v_mfma_f32_16x16x32_bf16 v[114:117], v[206:209], v[214:217], v[114:117]
	v_mfma_f32_16x16x32_bf16 v[102:105], v[180:183], v[222:225], v[102:105]
	v_mfma_f32_16x16x32_bf16 v[98:101], v[206:209], v[222:225], v[98:101]
	v_mfma_f32_16x16x32_bf16 v[86:89], v[180:183], v[230:233], v[86:89]
	v_mfma_f32_16x16x32_bf16 v[82:85], v[206:209], v[230:233], v[82:85]
	v_mfma_f32_16x16x32_bf16 v[70:73], v[180:183], v[238:241], v[70:73]
	v_mfma_f32_16x16x32_bf16 v[66:69], v[206:209], v[238:241], v[66:69]
	v_mfma_f32_16x16x32_bf16 v[118:121], v[184:187], v[218:221], v[118:121]
	v_mfma_f32_16x16x32_bf16 v[114:117], v[210:213], v[218:221], v[114:117]
	v_mfma_f32_16x16x32_bf16 v[102:105], v[184:187], v[226:229], v[102:105]
	v_mfma_f32_16x16x32_bf16 v[98:101], v[210:213], v[226:229], v[98:101]
	v_mfma_f32_16x16x32_bf16 v[86:89], v[184:187], v[234:237], v[86:89]
	v_mfma_f32_16x16x32_bf16 v[82:85], v[210:213], v[234:237], v[82:85]
	v_mfma_f32_16x16x32_bf16 v[70:73], v[184:187], v[242:245], v[70:73]
	v_mfma_f32_16x16x32_bf16 v[66:69], v[210:213], v[242:245], v[66:69]
	s_setprio 0
	s_barrier
	s_add_i32 s5, s18, s42
	v_lshl_add_u64 v[188:189], s[12:13], 0, v[154:155]
	s_mov_b32 m0, s5
	ds_read_b128 v[214:217], v204 offset:16384
	ds_read_b128 v[218:221], v204 offset:17408
	ds_read_b128 v[222:225], v204 offset:18432
	ds_read_b128 v[226:229], v204 offset:19456
	ds_read_b128 v[230:233], v204 offset:20480
	ds_read_b128 v[234:237], v204 offset:21504
	ds_read_b128 v[238:241], v204 offset:22528
	ds_read_b128 v[242:245], v204 offset:23552
	global_load_lds_dwordx4 v[188:189], off
	s_add_i32 m0, s5, 0x2000
	s_add_u32 s78, s12, 0x40000
	v_lshl_add_u64 v[246:247], s[12:13], 0, v[150:151]
	s_addc_u32 s79, s13, 0
	s_add_i32 s4, s4, s42
	global_load_lds_dwordx4 v[246:247], off
	v_lshl_add_u64 v[248:249], s[78:79], 0, v[154:155]
	s_mov_b32 m0, s4
	v_lshl_add_u64 v[250:251], s[14:15], 0, v[152:153]
	global_load_lds_dwordx4 v[248:249], off
	v_lshl_add_u64 v[248:249], s[78:79], 0, v[150:151]
	s_add_i32 m0, s4, 0x2000
	s_nop 0
	global_load_lds_dwordx4 v[248:249], off
	v_lshl_add_u64 v[248:249], s[14:15], 0, v[156:157]
	s_mov_b32 m0, s43
	s_nop 0
	global_load_lds_dwordx4 v[248:249], off
	s_mov_b32 m0, s44
	s_nop 0
	global_load_lds_dwordx4 v[250:251], off
	s_waitcnt vmcnt(8)
	s_waitcnt lgkmcnt(0)
	s_barrier
; #define PG8_STAGE(bufoff, gbase, voff) do { _Pragma("unroll") for (int _i = 0; _i < 2; ++_i) \
;         __builtin_amdgcn_global_load_lds((const unsigned*)((const char*)(gbase) + (voff)[_i]), (PG8_LAS unsigned*)(lds + (bufoff) + ldsw + _i * 8192), 16, 0, 0); } while (0)
; #define PG8_LDA(dst, b, h) do { _Pragma("unroll") for (int m = 0; m < 4; ++m) _Pragma("unroll") for (int k = 0; k < 2; ++k) dst[m][k] = *(const PG8_LAS bf16x8*)(lds + PG8_SA(b, h) + aoff + m * 2048 + k * 1024); } while (0)
; #define PG8_LDB(dst, b, h) do { _Pragma("unroll") for (int n = 0; n < 2; ++n) _Pragma("unroll") for (int k = 0; k < 2; ++k) dst[n][k] = *(const PG8_LAS bf16x8*)(lds + PG8_SB(b, h) + boff + n * 2048 + k * 1024); } while (0)
; #define PG8_MMA(ai, bj, At, Bt) do { __builtin_amdgcn_s_setprio(1); _Pragma("unroll") for (int m = 0; m < 4; ++m) _Pragma("unroll") for (int n = 0; n < 2; ++n) _Pragma("unroll") for (int k = 0; k < 2; ++k) \
;         acc[ai][bj][m][n] = __builtin_amdgcn_mfma_f32_16x16x32_bf16(Bt[n][k], At[m][k], acc[ai][bj][m][n], 0, 0, 0); __builtin_amdgcn_s_setprio(0); } while (0)
; #define PG8_WAIT_V(n) asm volatile("s_waitcnt vmcnt(" #n ")" ::: "memory")
; #define PG8_WAIT_L(n) asm volatile("s_waitcnt lgkmcnt(" #n ")" ::: "memory")
; #define PG8_BAR __builtin_amdgcn_s_barrier()
; #define PG8_SCHED __builtin_amdgcn_sched_barrier(0)
; template <class Epi, class Sched, bool ALIGN_EPI = false, bool SP2 = false>
; __device__ __forceinline__ void gemm_phase(PG8_LAS unsigned char* lds, const Gemm g, const Sched& S, const Epi& E) {
;     ...
;             PG8_WAIT_V(8); PG8_WAIT_L(0); PG8_BAR; PG8_MMA(1, 0, At, B0); PG8_MMA(1, 1, At, B1); PG8_BAR; PG8_SCHED;
;             PG8_LDB(B0, 1, 0); PG8_LDB(B1, 1, 1); PG8_SCHED; PG8_LDA(At, 1, 0); PG8_STAGE(PG8_SA(0, 1), a2 + hstep, voffA);
;             PG8_WAIT_V(8); PG8_WAIT_L(0); PG8_BAR; PG8_MMA(0, 0, At, B0); PG8_MMA(0, 1, At, B1); PG8_BAR; PG8_SCHED;
	s_setprio 1
	v_mfma_f32_16x16x32_bf16 v[62:65], v[164:167], v[214:217], v[62:65]
	v_mfma_f32_16x16x32_bf16 v[58:61], v[172:175], v[214:217], v[58:61]
	v_mfma_f32_16x16x32_bf16 v[46:49], v[164:167], v[222:225], v[46:49]
	v_mfma_f32_16x16x32_bf16 v[42:45], v[172:175], v[222:225], v[42:45]
	v_mfma_f32_16x16x32_bf16 v[30:33], v[164:167], v[230:233], v[30:33]
	v_mfma_f32_16x16x32_bf16 v[26:29], v[172:175], v[230:233], v[26:29]
	v_mfma_f32_16x16x32_bf16 v[14:17], v[164:167], v[238:241], v[14:17]
	v_mfma_f32_16x16x32_bf16 v[10:13], v[172:175], v[238:241], v[10:13]
	v_mfma_f32_16x16x32_bf16 v[62:65], v[168:171], v[218:221], v[62:65]
	v_mfma_f32_16x16x32_bf16 v[58:61], v[176:179], v[218:221], v[58:61]
	v_mfma_f32_16x16x32_bf16 v[46:49], v[168:171], v[226:229], v[46:49]
	v_mfma_f32_16x16x32_bf16 v[42:45], v[176:179], v[226:229], v[42:45]
	v_mfma_f32_16x16x32_bf16 v[30:33], v[168:171], v[234:237], v[30:33]
	v_mfma_f32_16x16x32_bf16 v[26:29], v[176:179], v[234:237], v[26:29]
	v_mfma_f32_16x16x32_bf16 v[14:17], v[168:171], v[242:245], v[14:17]
	v_mfma_f32_16x16x32_bf16 v[10:13], v[176:179], v[242:245], v[10:13]
	v_mfma_f32_16x16x32_bf16 v[54:57], v[180:183], v[214:217], v[54:57]
	v_mfma_f32_16x16x32_bf16 v[50:53], v[206:209], v[214:217], v[50:53]
	v_mfma_f32_16x16x32_bf16 v[38:41], v[180:183], v[222:225], v[38:41]
	v_mfma_f32_16x16x32_bf16 v[34:37], v[206:209], v[222:225], v[34:37]
	v_mfma_f32_16x16x32_bf16 v[22:25], v[180:183], v[230:233], v[22:25]
	v_mfma_f32_16x16x32_bf16 v[18:21], v[206:209], v[230:233], v[18:21]
	v_mfma_f32_16x16x32_bf16 v[6:9], v[180:183], v[238:241], v[6:9]
	v_mfma_f32_16x16x32_bf16 v[2:5], v[206:209], v[238:241], v[2:5]
	v_mfma_f32_16x16x32_bf16 v[54:57], v[184:187], v[218:221], v[54:57]
	v_mfma_f32_16x16x32_bf16 v[50:53], v[210:213], v[218:221], v[50:53]
	v_mfma_f32_16x16x32_bf16 v[38:41], v[184:187], v[226:229], v[38:41]
	v_mfma_f32_16x16x32_bf16 v[34:37], v[210:213], v[226:229], v[34:37]
	v_mfma_f32_16x16x32_bf16 v[22:25], v[184:187], v[234:237], v[22:25]
	v_mfma_f32_16x16x32_bf16 v[18:21], v[210:213], v[234:237], v[18:21]
	v_mfma_f32_16x16x32_bf16 v[6:9], v[184:187], v[242:245], v[6:9]
	v_mfma_f32_16x16x32_bf16 v[2:5], v[210:213], v[242:245], v[2:5]
	s_setprio 0
	s_barrier
	s_add_i32 s4, 0, 0x18000
	s_add_i32 s5, 0, 0x1c000
	v_add_u32_e32 v176, s4, v202
	v_add_u32_e32 v205, s5, v202
	ds_read_b128 v[164:167], v176
	ds_read_b128 v[168:171], v176 offset:1024
	ds_read_b128 v[172:175], v176 offset:2048
	ds_read_b128 v[176:179], v176 offset:3072
	ds_read_b128 v[180:183], v205
	ds_read_b128 v[184:187], v205 offset:1024
	ds_read_b128 v[206:209], v205 offset:2048
	ds_read_b128 v[210:213], v205 offset:3072
	s_add_u32 s14, s14, 0x40000
	s_addc_u32 s15, s15, 0
	s_mov_b32 m0, s45
	v_lshl_add_u64 v[252:253], s[14:15], 0, v[156:157]
	ds_read_b128 v[214:217], v204 offset:32768
	ds_read_b128 v[218:221], v204 offset:33792
	ds_read_b128 v[222:225], v204 offset:34816
	ds_read_b128 v[226:229], v204 offset:35840
	ds_read_b128 v[230:233], v204 offset:36864
	ds_read_b128 v[234:237], v204 offset:37888
	ds_read_b128 v[238:241], v204 offset:38912
	ds_read_b128 v[242:245], v204 offset:39936
	global_load_lds_dwordx4 v[252:253], off
	v_lshl_add_u64 v[252:253], s[14:15], 0, v[152:153]
	s_mov_b32 m0, s46
	s_nop 0
	global_load_lds_dwordx4 v[252:253], off
	s_waitcnt vmcnt(8)
	s_waitcnt lgkmcnt(0)
	s_barrier
	s_setprio 1
	v_mfma_f32_16x16x32_bf16 v[126:129], v[164:167], v[214:217], v[126:129]
	v_mfma_f32_16x16x32_bf16 v[122:125], v[172:175], v[214:217], v[122:125]
	v_mfma_f32_16x16x32_bf16 v[110:113], v[164:167], v[222:225], v[110:113]
	v_mfma_f32_16x16x32_bf16 v[106:109], v[172:175], v[222:225], v[106:109]
	v_mfma_f32_16x16x32_bf16 v[94:97], v[164:167], v[230:233], v[94:97]
	v_mfma_f32_16x16x32_bf16 v[90:93], v[172:175], v[230:233], v[90:93]
	v_mfma_f32_16x16x32_bf16 v[78:81], v[164:167], v[238:241], v[78:81]
	v_mfma_f32_16x16x32_bf16 v[74:77], v[172:175], v[238:241], v[74:77]
	v_mfma_f32_16x16x32_bf16 v[126:129], v[168:171], v[218:221], v[126:129]
	v_mfma_f32_16x16x32_bf16 v[122:125], v[176:179], v[218:221], v[122:125]
	v_mfma_f32_16x16x32_bf16 v[110:113], v[168:171], v[226:229], v[110:113]
	v_mfma_f32_16x16x32_bf16 v[106:109], v[176:179], v[226:229], v[106:109]
	v_mfma_f32_16x16x32_bf16 v[94:97], v[168:171], v[234:237], v[94:97]
	v_mfma_f32_16x16x32_bf16 v[90:93], v[176:179], v[234:237], v[90:93]
	v_mfma_f32_16x16x32_bf16 v[78:81], v[168:171], v[242:245], v[78:81]
	v_mfma_f32_16x16x32_bf16 v[74:77], v[176:179], v[242:245], v[74:77]
	v_mfma_f32_16x16x32_bf16 v[118:121], v[180:183], v[214:217], v[118:121]
	v_mfma_f32_16x16x32_bf16 v[114:117], v[206:209], v[214:217], v[114:117]
	v_mfma_f32_16x16x32_bf16 v[102:105], v[180:183], v[222:225], v[102:105]
	v_mfma_f32_16x16x32_bf16 v[98:101], v[206:209], v[222:225], v[98:101]
	v_mfma_f32_16x16x32_bf16 v[86:89], v[180:183], v[230:233], v[86:89]
	v_mfma_f32_16x16x32_bf16 v[82:85], v[206:209], v[230:233], v[82:85]
	v_mfma_f32_16x16x32_bf16 v[70:73], v[180:183], v[238:241], v[70:73]
	v_mfma_f32_16x16x32_bf16 v[66:69], v[206:209], v[238:241], v[66:69]
	v_mfma_f32_16x16x32_bf16 v[118:121], v[184:187], v[218:221], v[118:121]
	v_mfma_f32_16x16x32_bf16 v[114:117], v[210:213], v[218:221], v[114:117]
	v_mfma_f32_16x16x32_bf16 v[102:105], v[184:187], v[226:229], v[102:105]
	v_mfma_f32_16x16x32_bf16 v[98:101], v[210:213], v[226:229], v[98:101]
	v_mfma_f32_16x16x32_bf16 v[86:89], v[184:187], v[234:237], v[86:89]
	v_mfma_f32_16x16x32_bf16 v[82:85], v[210:213], v[234:237], v[82:85]
	v_mfma_f32_16x16x32_bf16 v[70:73], v[184:187], v[242:245], v[70:73]
	v_mfma_f32_16x16x32_bf16 v[66:69], v[210:213], v[242:245], v[66:69]
	s_setprio 0
	s_barrier
; #define PG8_STAGE(bufoff, gbase, voff) do { _Pragma("unroll") for (int _i = 0; _i < 2; ++_i) \
;         __builtin_amdgcn_global_load_lds((const unsigned*)((const char*)(gbase) + (voff)[_i]), (PG8_LAS unsigned*)(lds + (bufoff) + ldsw + _i * 8192), 16, 0, 0); } while (0)
; #define PG8_LDA(dst, b, h) do { _Pragma("unroll") for (int m = 0; m < 4; ++m) _Pragma("unroll") for (int k = 0; k < 2; ++k) dst[m][k] = *(const PG8_LAS bf16x8*)(lds + PG8_SA(b, h) + aoff + m * 2048 + k * 1024); } while (0)
; #define PG8_MMA(ai, bj, At, Bt) do { __builtin_amdgcn_s_setprio(1); _Pragma("unroll") for (int m = 0; m < 4; ++m) _Pragma("unroll") for (int n = 0; n < 2; ++n) _Pragma("unroll") for (int k = 0; k < 2; ++k) \
;         acc[ai][bj][m][n] = __builtin_amdgcn_mfma_f32_16x16x32_bf16(Bt[n][k], At[m][k], acc[ai][bj][m][n], 0, 0, 0); __builtin_amdgcn_s_setprio(0); } while (0)
; #define PG8_WAIT_V(n) asm volatile("s_waitcnt vmcnt(" #n ")" ::: "memory")
; #define PG8_WAIT_L(n) asm volatile("s_waitcnt lgkmcnt(" #n ")" ::: "memory")
; #define PG8_BAR __builtin_amdgcn_s_barrier()
; #define PG8_SCHED __builtin_amdgcn_sched_barrier(0)
; template <class Epi, class Sched, bool ALIGN_EPI = false, bool SP2 = false>
; __device__ __forceinline__ void gemm_phase(PG8_LAS unsigned char* lds, const Gemm g, const Sched& S, const Epi& E) {
;     ...
;             PG8_LDA(At, 1, 1); PG8_STAGE(PG8_SB(1, 0), b3, voffB); PG8_STAGE(PG8_SB(1, 1), b3 + hstep, voffB); PG8_STAGE(PG8_SA(1, 0), a3, voffA);
;             PG8_WAIT_V(8); PG8_WAIT_L(0); PG8_BAR; PG8_MMA(1, 0, At, B0); PG8_MMA(1, 1, At, B1); PG8_BAR; PG8_SCHED;
;     ...
;         }
;         if constexpr (ALIGN_EPI) { if (wr == 0) PG8_BAR; }
	s_add_i32 s4, s4, s42
	v_lshl_add_u64 v[188:189], v[188:189], 0, s[62:63]
	s_mov_b32 m0, s4
	ds_read_b128 v[214:217], v204 offset:49152
	ds_read_b128 v[218:221], v204 offset:50176
	ds_read_b128 v[222:225], v204 offset:51200
	ds_read_b128 v[226:229], v204 offset:52224
	ds_read_b128 v[230:233], v204 offset:53248
	ds_read_b128 v[234:237], v204 offset:54272
	ds_read_b128 v[238:241], v204 offset:55296
	ds_read_b128 v[242:245], v204 offset:56320
	global_load_lds_dwordx4 v[188:189], off
	s_add_i32 m0, s4, 0x2000
	s_add_u32 s12, s12, 0x40080
	v_lshl_add_u64 v[188:189], v[246:247], 0, s[62:63]
	s_addc_u32 s13, s13, 0
	s_add_i32 s4, s5, s42
	global_load_lds_dwordx4 v[188:189], off
	v_lshl_add_u64 v[188:189], s[12:13], 0, v[154:155]
	s_mov_b32 m0, s4
	s_nop 0
	global_load_lds_dwordx4 v[188:189], off
	v_lshl_add_u64 v[188:189], s[12:13], 0, v[150:151]
	s_add_i32 m0, s4, 0x2000
	s_nop 0
	global_load_lds_dwordx4 v[188:189], off
	v_lshl_add_u64 v[188:189], v[248:249], 0, s[62:63]
	s_mov_b32 m0, s48
	s_nop 0
	global_load_lds_dwordx4 v[188:189], off
	v_lshl_add_u64 v[188:189], v[250:251], 0, s[62:63]
	s_mov_b32 m0, s49
	s_nop 0
	global_load_lds_dwordx4 v[188:189], off
	s_waitcnt vmcnt(8)
	s_waitcnt lgkmcnt(0)
	s_barrier
	s_setprio 1
	v_mfma_f32_16x16x32_bf16 v[62:65], v[164:167], v[214:217], v[62:65]
	v_mfma_f32_16x16x32_bf16 v[58:61], v[172:175], v[214:217], v[58:61]
	v_mfma_f32_16x16x32_bf16 v[46:49], v[164:167], v[222:225], v[46:49]
	v_mfma_f32_16x16x32_bf16 v[42:45], v[172:175], v[222:225], v[42:45]
	v_mfma_f32_16x16x32_bf16 v[30:33], v[164:167], v[230:233], v[30:33]
	v_mfma_f32_16x16x32_bf16 v[26:29], v[172:175], v[230:233], v[26:29]
	v_mfma_f32_16x16x32_bf16 v[14:17], v[164:167], v[238:241], v[14:17]
	v_mfma_f32_16x16x32_bf16 v[10:13], v[172:175], v[238:241], v[10:13]
	v_mfma_f32_16x16x32_bf16 v[62:65], v[168:171], v[218:221], v[62:65]
	v_mfma_f32_16x16x32_bf16 v[58:61], v[176:179], v[218:221], v[58:61]
	v_mfma_f32_16x16x32_bf16 v[46:49], v[168:171], v[226:229], v[46:49]
	v_mfma_f32_16x16x32_bf16 v[42:45], v[176:179], v[226:229], v[42:45]
	v_mfma_f32_16x16x32_bf16 v[30:33], v[168:171], v[234:237], v[30:33]
	v_mfma_f32_16x16x32_bf16 v[26:29], v[176:179], v[234:237], v[26:29]
	v_mfma_f32_16x16x32_bf16 v[14:17], v[168:171], v[242:245], v[14:17]
	v_mfma_f32_16x16x32_bf16 v[10:13], v[176:179], v[242:245], v[10:13]
	v_mfma_f32_16x16x32_bf16 v[54:57], v[180:183], v[214:217], v[54:57]
	v_mfma_f32_16x16x32_bf16 v[50:53], v[206:209], v[214:217], v[50:53]
	v_mfma_f32_16x16x32_bf16 v[38:41], v[180:183], v[222:225], v[38:41]
	v_mfma_f32_16x16x32_bf16 v[34:37], v[206:209], v[222:225], v[34:37]
	v_mfma_f32_16x16x32_bf16 v[22:25], v[180:183], v[230:233], v[22:25]
	v_mfma_f32_16x16x32_bf16 v[18:21], v[206:209], v[230:233], v[18:21]
	v_mfma_f32_16x16x32_bf16 v[6:9], v[180:183], v[238:241], v[6:9]
	v_mfma_f32_16x16x32_bf16 v[2:5], v[206:209], v[238:241], v[2:5]
	v_mfma_f32_16x16x32_bf16 v[54:57], v[184:187], v[218:221], v[54:57]
	v_mfma_f32_16x16x32_bf16 v[50:53], v[210:213], v[218:221], v[50:53]
	v_mfma_f32_16x16x32_bf16 v[38:41], v[184:187], v[226:229], v[38:41]
	v_mfma_f32_16x16x32_bf16 v[34:37], v[210:213], v[226:229], v[34:37]
	v_mfma_f32_16x16x32_bf16 v[22:25], v[184:187], v[234:237], v[22:25]
	v_mfma_f32_16x16x32_bf16 v[18:21], v[210:213], v[234:237], v[18:21]
	v_mfma_f32_16x16x32_bf16 v[6:9], v[184:187], v[242:245], v[6:9]
	v_mfma_f32_16x16x32_bf16 v[2:5], v[210:213], v[242:245], v[2:5]
	s_setprio 0
	s_barrier
	s_add_i32 s64, s64, 2
	s_add_u32 s10, s10, 0x100
	s_addc_u32 s11, s11, 0
	s_add_u32 s54, s54, 0x100
	s_addc_u32 s55, s55, 0
	s_cmp_gt_u32 s64, 13
	s_cbranch_scc0 .LBB0_592
	s_and_b64 vcc, exec, s[24:25]
	s_cbranch_vccz .LBB0_595
	s_barrier

; #define PG8_STAGE(bufoff, gbase, voff) do { _Pragma("unroll") for (int _i = 0; _i < 2; ++_i) \
;         __builtin_amdgcn_global_load_lds((const unsigned*)((const char*)(gbase) + (voff)[_i]), (PG8_LAS unsigned*)(lds + (bufoff) + ldsw + _i * 8192), 16, 0, 0); } while (0)
; #define PG8_LDA(dst, b, h) do { _Pragma("unroll") for (int m = 0; m < 4; ++m) _Pragma("unroll") for (int k = 0; k < 2; ++k) dst[m][k] = *(const PG8_LAS bf16x8*)(lds + PG8_SA(b, h) + aoff + m * 2048 + k * 1024); } while (0)
; #define PG8_LDB(dst, b, h) do { _Pragma("unroll") for (int n = 0; n < 2; ++n) _Pragma("unroll") for (int k = 0; k < 2; ++k) dst[n][k] = *(const PG8_LAS bf16x8*)(lds + PG8_SB(b, h) + boff + n * 2048 + k * 1024); } while (0)
; #define PG8_MMA(ai, bj, At, Bt) do { __builtin_amdgcn_s_setprio(1); _Pragma("unroll") for (int m = 0; m < 4; ++m) _Pragma("unroll") for (int n = 0; n < 2; ++n) _Pragma("unroll") for (int k = 0; k < 2; ++k) \
;         acc[ai][bj][m][n] = __builtin_amdgcn_mfma_f32_16x16x32_bf16(Bt[n][k], At[m][k], acc[ai][bj][m][n], 0, 0, 0); __builtin_amdgcn_s_setprio(0); } while (0)
; #define PG8_WAIT_V(n) asm volatile("s_waitcnt vmcnt(" #n ")" ::: "memory")
; #define PG8_WAIT_L(n) asm volatile("s_waitcnt lgkmcnt(" #n ")" ::: "memory")
; template <class Epi, class Sched, bool ALIGN_EPI = false, bool SP2 = false>
; __device__ __forceinline__ void gemm_phase(PG8_LAS unsigned char* lds, const Gemm g, const Sched& S, const Epi& E) {
;     ...
;             const bool last = (t == nt - 2);
;             const char* a1 = cA + (size_t)(t + 1) * kstep;
;             const char* a2 = last ? nA : cA + (size_t)(t + 2) * kstep; const char* b2 = last ? nB : cB + (size_t)(t + 2) * kstep;
;             const char* a3 = a2 + kstep; const char* b3 = b2 + kstep;
;             if (last && has_next) S.a_ready(nxt);
;             if constexpr (SP2) {
;             PG8_LDB(B0, 0, 0); PG8_LDB(B1, 0, 1); PG8_SCHED; PG8_LDA(At, 0, 0); PG8_STAGE(PG8_SA(1, 1), a1 + hstep, voffA);
;             PG8_WAIT_V(8); PG8_WAIT_L(0); PG8_BAR; PG8_MMA(0, 0, At, B0); PG8_MMA(0, 1, At, B1); PG8_BAR; PG8_SCHED;
;             PG8_LDA(At, 0, 1); PG8_STAGE(PG8_SB(0, 0), b2, voffB); PG8_STAGE(PG8_SB(0, 1), b2 + hstep, voffB); PG8_STAGE(PG8_SA(0, 0), a2, voffA);
;             PG8_WAIT_V(8); PG8_WAIT_L(0); PG8_BAR; PG8_MMA(1, 0, At, B0); PG8_MMA(1, 1, At, B1); PG8_BAR; PG8_SCHED;
.LBB0_878:
	s_add_u32 s4, s14, s8
	s_addc_u32 s5, s15, s9
	s_add_u32 s4, s4, 0xc000100
	s_addc_u32 s5, s5, 0
	s_add_u32 s10, s35, s8
	s_addc_u32 s11, s49, s9
	s_add_i32 s18, 0, 0x10000
	s_cmpk_eq_i32 s8, 0x700
	s_cselect_b32 s13, s21, s5
	s_cselect_b32 s12, s20, s4
	s_cselect_b32 s11, s31, s11
	s_cselect_b32 s10, s34, s10
	s_add_i32 s4, 0, 0x14000
	v_add_u32_e32 v176, s18, v202
	v_add_u32_e32 v188, s4, v202
	ds_read_b128 v[164:167], v176
	ds_read_b128 v[168:171], v176 offset:1024
	ds_read_b128 v[172:175], v176 offset:2048
	ds_read_b128 v[176:179], v176 offset:3072
	ds_read_b128 v[180:183], v188
	ds_read_b128 v[184:187], v188 offset:1024
	ds_read_b128 v[206:209], v188 offset:2048
	ds_read_b128 v[210:213], v188 offset:3072
	v_lshl_add_u64 v[188:189], v[160:161], 0, s[8:9]
	s_add_i32 m0, s38, 0xc000
	ds_read_b128 v[214:217], v204
	ds_read_b128 v[218:221], v204 offset:1024
	ds_read_b128 v[222:225], v204 offset:2048
	ds_read_b128 v[226:229], v204 offset:3072
	ds_read_b128 v[230:233], v204 offset:4096
	ds_read_b128 v[234:237], v204 offset:5120
	ds_read_b128 v[238:241], v204 offset:6144
	ds_read_b128 v[242:245], v204 offset:7168
	global_load_lds_dwordx4 v[188:189], off
	v_lshl_add_u64 v[188:189], v[162:163], 0, s[8:9]
	s_add_i32 m0, s38, 0xe000
	s_nop 0
	global_load_lds_dwordx4 v[188:189], off
	s_waitcnt vmcnt(8)
	s_waitcnt lgkmcnt(0)
	s_barrier
	s_setprio 1
	v_mfma_f32_16x16x32_bf16 v[126:129], v[164:167], v[214:217], v[126:129]
	v_mfma_f32_16x16x32_bf16 v[122:125], v[172:175], v[214:217], v[122:125]
	v_mfma_f32_16x16x32_bf16 v[110:113], v[164:167], v[222:225], v[110:113]
	v_mfma_f32_16x16x32_bf16 v[106:109], v[172:175], v[222:225], v[106:109]
	v_mfma_f32_16x16x32_bf16 v[94:97], v[164:167], v[230:233], v[94:97]
	v_mfma_f32_16x16x32_bf16 v[90:93], v[172:175], v[230:233], v[90:93]
	v_mfma_f32_16x16x32_bf16 v[78:81], v[164:167], v[238:241], v[78:81]
	v_mfma_f32_16x16x32_bf16 v[74:77], v[172:175], v[238:241], v[74:77]
	v_mfma_f32_16x16x32_bf16 v[126:129], v[168:171], v[218:221], v[126:129]
	v_mfma_f32_16x16x32_bf16 v[122:125], v[176:179], v[218:221], v[122:125]
	v_mfma_f32_16x16x32_bf16 v[110:113], v[168:171], v[226:229], v[110:113]
	v_mfma_f32_16x16x32_bf16 v[106:109], v[176:179], v[226:229], v[106:109]
	v_mfma_f32_16x16x32_bf16 v[94:97], v[168:171], v[234:237], v[94:97]
	v_mfma_f32_16x16x32_bf16 v[90:93], v[176:179], v[234:237], v[90:93]
	v_mfma_f32_16x16x32_bf16 v[78:81], v[168:171], v[242:245], v[78:81]
	v_mfma_f32_16x16x32_bf16 v[74:77], v[176:179], v[242:245], v[74:77]
	v_mfma_f32_16x16x32_bf16 v[118:121], v[180:183], v[214:217], v[118:121]
	v_mfma_f32_16x16x32_bf16 v[114:117], v[206:209], v[214:217], v[114:117]
	v_mfma_f32_16x16x32_bf16 v[102:105], v[180:183], v[222:225], v[102:105]
	v_mfma_f32_16x16x32_bf16 v[98:101], v[206:209], v[222:225], v[98:101]
	v_mfma_f32_16x16x32_bf16 v[86:89], v[180:183], v[230:233], v[86:89]
	v_mfma_f32_16x16x32_bf16 v[82:85], v[206:209], v[230:233], v[82:85]
	v_mfma_f32_16x16x32_bf16 v[70:73], v[180:183], v[238:241], v[70:73]
	v_mfma_f32_16x16x32_bf16 v[66:69], v[206:209], v[238:241], v[66:69]
	v_mfma_f32_16x16x32_bf16 v[118:121], v[184:187], v[218:221], v[118:121]
	v_mfma_f32_16x16x32_bf16 v[114:117], v[210:213], v[218:221], v[114:117]
	v_mfma_f32_16x16x32_bf16 v[102:105], v[184:187], v[226:229], v[102:105]
	v_mfma_f32_16x16x32_bf16 v[98:101], v[210:213], v[226:229], v[98:101]
	v_mfma_f32_16x16x32_bf16 v[86:89], v[184:187], v[234:237], v[86:89]
	v_mfma_f32_16x16x32_bf16 v[82:85], v[210:213], v[234:237], v[82:85]
	v_mfma_f32_16x16x32_bf16 v[70:73], v[184:187], v[242:245], v[70:73]
	v_mfma_f32_16x16x32_bf16 v[66:69], v[210:213], v[242:245], v[66:69]
	s_setprio 0
	s_barrier
	s_add_i32 s5, s18, s37
	v_lshl_add_u64 v[188:189], s[10:11], 0, v[154:155]
	s_mov_b32 m0, s5
	ds_read_b128 v[214:217], v204 offset:16384
	ds_read_b128 v[218:221], v204 offset:17408
	ds_read_b128 v[222:225], v204 offset:18432
	ds_read_b128 v[226:229], v204 offset:19456
	ds_read_b128 v[230:233], v204 offset:20480
	ds_read_b128 v[234:237], v204 offset:21504
	ds_read_b128 v[238:241], v204 offset:22528
	ds_read_b128 v[242:245], v204 offset:23552
	global_load_lds_dwordx4 v[188:189], off
	s_add_i32 m0, s5, 0x2000
	s_add_u32 s52, s10, 0x40000
	v_lshl_add_u64 v[246:247], s[10:11], 0, v[150:151]
	s_addc_u32 s53, s11, 0
	s_add_i32 s4, s4, s37
	global_load_lds_dwordx4 v[246:247], off
	v_lshl_add_u64 v[248:249], s[52:53], 0, v[154:155]
	s_mov_b32 m0, s4
	v_lshl_add_u64 v[250:251], s[12:13], 0, v[152:153]
	global_load_lds_dwordx4 v[248:249], off
	v_lshl_add_u64 v[248:249], s[52:53], 0, v[150:151]
	s_add_i32 m0, s4, 0x2000
	s_nop 0
	global_load_lds_dwordx4 v[248:249], off
	v_lshl_add_u64 v[248:249], s[12:13], 0, v[156:157]
	s_mov_b32 m0, s38
	s_nop 0
	global_load_lds_dwordx4 v[248:249], off
	s_mov_b32 m0, s39
	s_nop 0
	global_load_lds_dwordx4 v[250:251], off
	s_waitcnt vmcnt(8)
	s_waitcnt lgkmcnt(0)
	s_barrier
; #define PG8_STAGE(bufoff, gbase, voff) do { _Pragma("unroll") for (int _i = 0; _i < 2; ++_i) \
;         __builtin_amdgcn_global_load_lds((const unsigned*)((const char*)(gbase) + (voff)[_i]), (PG8_LAS unsigned*)(lds + (bufoff) + ldsw + _i * 8192), 16, 0, 0); } while (0)
; #define PG8_LDA(dst, b, h) do { _Pragma("unroll") for (int m = 0; m < 4; ++m) _Pragma("unroll") for (int k = 0; k < 2; ++k) dst[m][k] = *(const PG8_LAS bf16x8*)(lds + PG8_SA(b, h) + aoff + m * 2048 + k * 1024); } while (0)
; #define PG8_LDB(dst, b, h) do { _Pragma("unroll") for (int n = 0; n < 2; ++n) _Pragma("unroll") for (int k = 0; k < 2; ++k) dst[n][k] = *(const PG8_LAS bf16x8*)(lds + PG8_SB(b, h) + boff + n * 2048 + k * 1024); } while (0)
; #define PG8_MMA(ai, bj, At, Bt) do { __builtin_amdgcn_s_setprio(1); _Pragma("unroll") for (int m = 0; m < 4; ++m) _Pragma("unroll") for (int n = 0; n < 2; ++n) _Pragma("unroll") for (int k = 0; k < 2; ++k) \
;         acc[ai][bj][m][n] = __builtin_amdgcn_mfma_f32_16x16x32_bf16(Bt[n][k], At[m][k], acc[ai][bj][m][n], 0, 0, 0); __builtin_amdgcn_s_setprio(0); } while (0)
; #define PG8_WAIT_V(n) asm volatile("s_waitcnt vmcnt(" #n ")" ::: "memory")
; #define PG8_WAIT_L(n) asm volatile("s_waitcnt lgkmcnt(" #n ")" ::: "memory")
; #define PG8_BAR __builtin_amdgcn_s_barrier()
; #define PG8_SCHED __builtin_amdgcn_sched_barrier(0)
; template <class Epi, class Sched, bool ALIGN_EPI = false, bool SP2 = false>
; __device__ __forceinline__ void gemm_phase(PG8_LAS unsigned char* lds, const Gemm g, const Sched& S, const Epi& E) {
;     ...
;             PG8_WAIT_V(8); PG8_WAIT_L(0); PG8_BAR; PG8_MMA(1, 0, At, B0); PG8_MMA(1, 1, At, B1); PG8_BAR; PG8_SCHED;
;             PG8_LDB(B0, 1, 0); PG8_LDB(B1, 1, 1); PG8_SCHED; PG8_LDA(At, 1, 0); PG8_STAGE(PG8_SA(0, 1), a2 + hstep, voffA);
;             PG8_WAIT_V(8); PG8_WAIT_L(0); PG8_BAR; PG8_MMA(0, 0, At, B0); PG8_MMA(0, 1, At, B1); PG8_BAR; PG8_SCHED;
	s_setprio 1
	v_mfma_f32_16x16x32_bf16 v[62:65], v[164:167], v[214:217], v[62:65]
	v_mfma_f32_16x16x32_bf16 v[58:61], v[172:175], v[214:217], v[58:61]
	v_mfma_f32_16x16x32_bf16 v[46:49], v[164:167], v[222:225], v[46:49]
	v_mfma_f32_16x16x32_bf16 v[42:45], v[172:175], v[222:225], v[42:45]
	v_mfma_f32_16x16x32_bf16 v[30:33], v[164:167], v[230:233], v[30:33]
	v_mfma_f32_16x16x32_bf16 v[26:29], v[172:175], v[230:233], v[26:29]
	v_mfma_f32_16x16x32_bf16 v[14:17], v[164:167], v[238:241], v[14:17]
	v_mfma_f32_16x16x32_bf16 v[10:13], v[172:175], v[238:241], v[10:13]
	v_mfma_f32_16x16x32_bf16 v[62:65], v[168:171], v[218:221], v[62:65]
	v_mfma_f32_16x16x32_bf16 v[58:61], v[176:179], v[218:221], v[58:61]
	v_mfma_f32_16x16x32_bf16 v[46:49], v[168:171], v[226:229], v[46:49]
	v_mfma_f32_16x16x32_bf16 v[42:45], v[176:179], v[226:229], v[42:45]
	v_mfma_f32_16x16x32_bf16 v[30:33], v[168:171], v[234:237], v[30:33]
	v_mfma_f32_16x16x32_bf16 v[26:29], v[176:179], v[234:237], v[26:29]
	v_mfma_f32_16x16x32_bf16 v[14:17], v[168:171], v[242:245], v[14:17]
	v_mfma_f32_16x16x32_bf16 v[10:13], v[176:179], v[242:245], v[10:13]
	v_mfma_f32_16x16x32_bf16 v[54:57], v[180:183], v[214:217], v[54:57]
	v_mfma_f32_16x16x32_bf16 v[50:53], v[206:209], v[214:217], v[50:53]
	v_mfma_f32_16x16x32_bf16 v[38:41], v[180:183], v[222:225], v[38:41]
	v_mfma_f32_16x16x32_bf16 v[34:37], v[206:209], v[222:225], v[34:37]
	v_mfma_f32_16x16x32_bf16 v[22:25], v[180:183], v[230:233], v[22:25]
	v_mfma_f32_16x16x32_bf16 v[18:21], v[206:209], v[230:233], v[18:21]
	v_mfma_f32_16x16x32_bf16 v[6:9], v[180:183], v[238:241], v[6:9]
	v_mfma_f32_16x16x32_bf16 v[2:5], v[206:209], v[238:241], v[2:5]
	v_mfma_f32_16x16x32_bf16 v[54:57], v[184:187], v[218:221], v[54:57]
	v_mfma_f32_16x16x32_bf16 v[50:53], v[210:213], v[218:221], v[50:53]
	v_mfma_f32_16x16x32_bf16 v[38:41], v[184:187], v[226:229], v[38:41]
	v_mfma_f32_16x16x32_bf16 v[34:37], v[210:213], v[226:229], v[34:37]
	v_mfma_f32_16x16x32_bf16 v[22:25], v[184:187], v[234:237], v[22:25]
	v_mfma_f32_16x16x32_bf16 v[18:21], v[210:213], v[234:237], v[18:21]
	v_mfma_f32_16x16x32_bf16 v[6:9], v[184:187], v[242:245], v[6:9]
	v_mfma_f32_16x16x32_bf16 v[2:5], v[210:213], v[242:245], v[2:5]
	s_setprio 0
	s_barrier
	s_add_i32 s4, 0, 0x18000
	s_add_i32 s5, 0, 0x1c000
	v_add_u32_e32 v176, s4, v202
	v_add_u32_e32 v205, s5, v202
	ds_read_b128 v[164:167], v176
	ds_read_b128 v[168:171], v176 offset:1024
	ds_read_b128 v[172:175], v176 offset:2048
	ds_read_b128 v[176:179], v176 offset:3072
	ds_read_b128 v[180:183], v205
	ds_read_b128 v[184:187], v205 offset:1024
	ds_read_b128 v[206:209], v205 offset:2048
	ds_read_b128 v[210:213], v205 offset:3072
	s_add_u32 s12, s12, 0x40000
	s_addc_u32 s13, s13, 0
	s_mov_b32 m0, s40
	v_lshl_add_u64 v[252:253], s[12:13], 0, v[156:157]
	ds_read_b128 v[214:217], v204 offset:32768
	ds_read_b128 v[218:221], v204 offset:33792
	ds_read_b128 v[222:225], v204 offset:34816
	ds_read_b128 v[226:229], v204 offset:35840
	ds_read_b128 v[230:233], v204 offset:36864
	ds_read_b128 v[234:237], v204 offset:37888
	ds_read_b128 v[238:241], v204 offset:38912
	ds_read_b128 v[242:245], v204 offset:39936
	global_load_lds_dwordx4 v[252:253], off
	v_lshl_add_u64 v[252:253], s[12:13], 0, v[152:153]
	s_mov_b32 m0, s41
	s_nop 0
	global_load_lds_dwordx4 v[252:253], off
	s_waitcnt vmcnt(8)
	s_waitcnt lgkmcnt(0)
	s_barrier
	s_setprio 1
	v_mfma_f32_16x16x32_bf16 v[126:129], v[164:167], v[214:217], v[126:129]
	v_mfma_f32_16x16x32_bf16 v[122:125], v[172:175], v[214:217], v[122:125]
	v_mfma_f32_16x16x32_bf16 v[110:113], v[164:167], v[222:225], v[110:113]
	v_mfma_f32_16x16x32_bf16 v[106:109], v[172:175], v[222:225], v[106:109]
	v_mfma_f32_16x16x32_bf16 v[94:97], v[164:167], v[230:233], v[94:97]
	v_mfma_f32_16x16x32_bf16 v[90:93], v[172:175], v[230:233], v[90:93]
	v_mfma_f32_16x16x32_bf16 v[78:81], v[164:167], v[238:241], v[78:81]
	v_mfma_f32_16x16x32_bf16 v[74:77], v[172:175], v[238:241], v[74:77]
	v_mfma_f32_16x16x32_bf16 v[126:129], v[168:171], v[218:221], v[126:129]
	v_mfma_f32_16x16x32_bf16 v[122:125], v[176:179], v[218:221], v[122:125]
	v_mfma_f32_16x16x32_bf16 v[110:113], v[168:171], v[226:229], v[110:113]
	v_mfma_f32_16x16x32_bf16 v[106:109], v[176:179], v[226:229], v[106:109]
	v_mfma_f32_16x16x32_bf16 v[94:97], v[168:171], v[234:237], v[94:97]
	v_mfma_f32_16x16x32_bf16 v[90:93], v[176:179], v[234:237], v[90:93]
	v_mfma_f32_16x16x32_bf16 v[78:81], v[168:171], v[242:245], v[78:81]
	v_mfma_f32_16x16x32_bf16 v[74:77], v[176:179], v[242:245], v[74:77]
	v_mfma_f32_16x16x32_bf16 v[118:121], v[180:183], v[214:217], v[118:121]
	v_mfma_f32_16x16x32_bf16 v[114:117], v[206:209], v[214:217], v[114:117]
	v_mfma_f32_16x16x32_bf16 v[102:105], v[180:183], v[222:225], v[102:105]
	v_mfma_f32_16x16x32_bf16 v[98:101], v[206:209], v[222:225], v[98:101]
	v_mfma_f32_16x16x32_bf16 v[86:89], v[180:183], v[230:233], v[86:89]
	v_mfma_f32_16x16x32_bf16 v[82:85], v[206:209], v[230:233], v[82:85]
	v_mfma_f32_16x16x32_bf16 v[70:73], v[180:183], v[238:241], v[70:73]
	v_mfma_f32_16x16x32_bf16 v[66:69], v[206:209], v[238:241], v[66:69]
	v_mfma_f32_16x16x32_bf16 v[118:121], v[184:187], v[218:221], v[118:121]
	v_mfma_f32_16x16x32_bf16 v[114:117], v[210:213], v[218:221], v[114:117]
	v_mfma_f32_16x16x32_bf16 v[102:105], v[184:187], v[226:229], v[102:105]
	v_mfma_f32_16x16x32_bf16 v[98:101], v[210:213], v[226:229], v[98:101]
	v_mfma_f32_16x16x32_bf16 v[86:89], v[184:187], v[234:237], v[86:89]
	v_mfma_f32_16x16x32_bf16 v[82:85], v[210:213], v[234:237], v[82:85]
	v_mfma_f32_16x16x32_bf16 v[70:73], v[184:187], v[242:245], v[70:73]
	v_mfma_f32_16x16x32_bf16 v[66:69], v[210:213], v[242:245], v[66:69]
	s_setprio 0
	s_barrier
; #define PG8_STAGE(bufoff, gbase, voff) do { _Pragma("unroll") for (int _i = 0; _i < 2; ++_i) \
;         __builtin_amdgcn_global_load_lds((const unsigned*)((const char*)(gbase) + (voff)[_i]), (PG8_LAS unsigned*)(lds + (bufoff) + ldsw + _i * 8192), 16, 0, 0); } while (0)
; #define PG8_LDA(dst, b, h) do { _Pragma("unroll") for (int m = 0; m < 4; ++m) _Pragma("unroll") for (int k = 0; k < 2; ++k) dst[m][k] = *(const PG8_LAS bf16x8*)(lds + PG8_SA(b, h) + aoff + m * 2048 + k * 1024); } while (0)
; #define PG8_MMA(ai, bj, At, Bt) do { __builtin_amdgcn_s_setprio(1); _Pragma("unroll") for (int m = 0; m < 4; ++m) _Pragma("unroll") for (int n = 0; n < 2; ++n) _Pragma("unroll") for (int k = 0; k < 2; ++k) \
;         acc[ai][bj][m][n] = __builtin_amdgcn_mfma_f32_16x16x32_bf16(Bt[n][k], At[m][k], acc[ai][bj][m][n], 0, 0, 0); __builtin_amdgcn_s_setprio(0); } while (0)
; #define PG8_WAIT_V(n) asm volatile("s_waitcnt vmcnt(" #n ")" ::: "memory")
; #define PG8_WAIT_L(n) asm volatile("s_waitcnt lgkmcnt(" #n ")" ::: "memory")
; #define PG8_BAR __builtin_amdgcn_s_barrier()
; #define PG8_SCHED __builtin_amdgcn_sched_barrier(0)
; template <class Epi, class Sched, bool ALIGN_EPI = false, bool SP2 = false>
; __device__ __forceinline__ void gemm_phase(PG8_LAS unsigned char* lds, const Gemm g, const Sched& S, const Epi& E) {
;     ...
;             PG8_LDA(At, 1, 1); PG8_STAGE(PG8_SB(1, 0), b3, voffB); PG8_STAGE(PG8_SB(1, 1), b3 + hstep, voffB); PG8_STAGE(PG8_SA(1, 0), a3, voffA);
;             PG8_WAIT_V(8); PG8_WAIT_L(0); PG8_BAR; PG8_MMA(1, 0, At, B0); PG8_MMA(1, 1, At, B1); PG8_BAR; PG8_SCHED;
;     ...
;         }
;         if constexpr (ALIGN_EPI) { if (wr == 0) PG8_BAR; }
	s_add_i32 s4, s4, s37
	v_lshl_add_u64 v[188:189], v[188:189], 0, s[62:63]
	s_mov_b32 m0, s4
	ds_read_b128 v[214:217], v204 offset:49152
	ds_read_b128 v[218:221], v204 offset:50176
	ds_read_b128 v[222:225], v204 offset:51200
	ds_read_b128 v[226:229], v204 offset:52224
	ds_read_b128 v[230:233], v204 offset:53248
	ds_read_b128 v[234:237], v204 offset:54272
	ds_read_b128 v[238:241], v204 offset:55296
	ds_read_b128 v[242:245], v204 offset:56320
	global_load_lds_dwordx4 v[188:189], off
	s_add_i32 m0, s4, 0x2000
	s_add_u32 s10, s10, 0x40080
	v_lshl_add_u64 v[188:189], v[246:247], 0, s[62:63]
	s_addc_u32 s11, s11, 0
	s_add_i32 s4, s5, s37
	global_load_lds_dwordx4 v[188:189], off
	v_lshl_add_u64 v[188:189], s[10:11], 0, v[154:155]
	s_mov_b32 m0, s4
	s_nop 0
	global_load_lds_dwordx4 v[188:189], off
	v_lshl_add_u64 v[188:189], s[10:11], 0, v[150:151]
	s_add_i32 m0, s4, 0x2000
	s_nop 0
	global_load_lds_dwordx4 v[188:189], off
	v_lshl_add_u64 v[188:189], v[248:249], 0, s[62:63]
	s_mov_b32 m0, s42
	s_nop 0
	global_load_lds_dwordx4 v[188:189], off
	v_lshl_add_u64 v[188:189], v[250:251], 0, s[62:63]
	s_mov_b32 m0, s43
	s_nop 0
	global_load_lds_dwordx4 v[188:189], off
	s_waitcnt vmcnt(8)
	s_waitcnt lgkmcnt(0)
	s_barrier
	s_setprio 1
	v_mfma_f32_16x16x32_bf16 v[62:65], v[164:167], v[214:217], v[62:65]
	v_mfma_f32_16x16x32_bf16 v[58:61], v[172:175], v[214:217], v[58:61]
	v_mfma_f32_16x16x32_bf16 v[46:49], v[164:167], v[222:225], v[46:49]
	v_mfma_f32_16x16x32_bf16 v[42:45], v[172:175], v[222:225], v[42:45]
	v_mfma_f32_16x16x32_bf16 v[30:33], v[164:167], v[230:233], v[30:33]
	v_mfma_f32_16x16x32_bf16 v[26:29], v[172:175], v[230:233], v[26:29]
	v_mfma_f32_16x16x32_bf16 v[14:17], v[164:167], v[238:241], v[14:17]
	v_mfma_f32_16x16x32_bf16 v[10:13], v[172:175], v[238:241], v[10:13]
	v_mfma_f32_16x16x32_bf16 v[62:65], v[168:171], v[218:221], v[62:65]
	v_mfma_f32_16x16x32_bf16 v[58:61], v[176:179], v[218:221], v[58:61]
	v_mfma_f32_16x16x32_bf16 v[46:49], v[168:171], v[226:229], v[46:49]
	v_mfma_f32_16x16x32_bf16 v[42:45], v[176:179], v[226:229], v[42:45]
	v_mfma_f32_16x16x32_bf16 v[30:33], v[168:171], v[234:237], v[30:33]
	v_mfma_f32_16x16x32_bf16 v[26:29], v[176:179], v[234:237], v[26:29]
	v_mfma_f32_16x16x32_bf16 v[14:17], v[168:171], v[242:245], v[14:17]
	v_mfma_f32_16x16x32_bf16 v[10:13], v[176:179], v[242:245], v[10:13]
	v_mfma_f32_16x16x32_bf16 v[54:57], v[180:183], v[214:217], v[54:57]
	v_mfma_f32_16x16x32_bf16 v[50:53], v[206:209], v[214:217], v[50:53]
	v_mfma_f32_16x16x32_bf16 v[38:41], v[180:183], v[222:225], v[38:41]
	v_mfma_f32_16x16x32_bf16 v[34:37], v[206:209], v[222:225], v[34:37]
	v_mfma_f32_16x16x32_bf16 v[22:25], v[180:183], v[230:233], v[22:25]
	v_mfma_f32_16x16x32_bf16 v[18:21], v[206:209], v[230:233], v[18:21]
	v_mfma_f32_16x16x32_bf16 v[6:9], v[180:183], v[238:241], v[6:9]
	v_mfma_f32_16x16x32_bf16 v[2:5], v[206:209], v[238:241], v[2:5]
	v_mfma_f32_16x16x32_bf16 v[54:57], v[184:187], v[218:221], v[54:57]
	v_mfma_f32_16x16x32_bf16 v[50:53], v[210:213], v[218:221], v[50:53]
	v_mfma_f32_16x16x32_bf16 v[38:41], v[184:187], v[226:229], v[38:41]
	v_mfma_f32_16x16x32_bf16 v[34:37], v[210:213], v[226:229], v[34:37]
	v_mfma_f32_16x16x32_bf16 v[22:25], v[184:187], v[234:237], v[22:25]
	v_mfma_f32_16x16x32_bf16 v[18:21], v[210:213], v[234:237], v[18:21]
	v_mfma_f32_16x16x32_bf16 v[6:9], v[184:187], v[242:245], v[6:9]
	v_mfma_f32_16x16x32_bf16 v[2:5], v[210:213], v[242:245], v[2:5]
	s_setprio 0
	s_barrier
	s_add_i32 s50, s50, 2
	s_add_u32 s8, s8, 0x100
	s_addc_u32 s9, s9, 0
	s_cmp_gt_u32 s50, 13
	s_cbranch_scc0 .LBB0_878
	s_and_b64 vcc, exec, s[26:27]
	s_cbranch_vccz .LBB0_881
	s_barrier

; #define PG8_STAGE(bufoff, gbase, voff) do { _Pragma("unroll") for (int _i = 0; _i < 2; ++_i) \
;         __builtin_amdgcn_global_load_lds((const unsigned*)((const char*)(gbase) + (voff)[_i]), (PG8_LAS unsigned*)(lds + (bufoff) + ldsw + _i * 8192), 16, 0, 0); } while (0)
; #define PG8_LDA(dst, b, h) do { _Pragma("unroll") for (int m = 0; m < 4; ++m) _Pragma("unroll") for (int k = 0; k < 2; ++k) dst[m][k] = *(const PG8_LAS bf16x8*)(lds + PG8_SA(b, h) + aoff + m * 2048 + k * 1024); } while (0)
; #define PG8_LDB(dst, b, h) do { _Pragma("unroll") for (int n = 0; n < 2; ++n) _Pragma("unroll") for (int k = 0; k < 2; ++k) dst[n][k] = *(const PG8_LAS bf16x8*)(lds + PG8_SB(b, h) + boff + n * 2048 + k * 1024); } while (0)
; #define PG8_MMA(ai, bj, At, Bt) do { __builtin_amdgcn_s_setprio(1); _Pragma("unroll") for (int m = 0; m < 4; ++m) _Pragma("unroll") for (int n = 0; n < 2; ++n) _Pragma("unroll") for (int k = 0; k < 2; ++k) \
;         acc[ai][bj][m][n] = __builtin_amdgcn_mfma_f32_16x16x32_bf16(Bt[n][k], At[m][k], acc[ai][bj][m][n], 0, 0, 0); __builtin_amdgcn_s_setprio(0); } while (0)
; #define PG8_WAIT_V(n) asm volatile("s_waitcnt vmcnt(" #n ")" ::: "memory")
; #define PG8_WAIT_L(n) asm volatile("s_waitcnt lgkmcnt(" #n ")" ::: "memory")
; template <class Epi, class Sched, bool ALIGN_EPI = false, bool SP2 = false>
; __device__ __forceinline__ void gemm_phase(PG8_LAS unsigned char* lds, const Gemm g, const Sched& S, const Epi& E) {
;     ...
;             const bool last = (t == nt - 2);
;             const char* a1 = cA + (size_t)(t + 1) * kstep;
;             const char* a2 = last ? nA : cA + (size_t)(t + 2) * kstep; const char* b2 = last ? nB : cB + (size_t)(t + 2) * kstep;
;             const char* a3 = a2 + kstep; const char* b3 = b2 + kstep;
;             if (last && has_next) S.a_ready(nxt);
;             if constexpr (SP2) {
;             PG8_LDB(B0, 0, 0); PG8_LDB(B1, 0, 1); PG8_SCHED; PG8_LDA(At, 0, 0); PG8_STAGE(PG8_SA(1, 1), a1 + hstep, voffA);
;             PG8_WAIT_V(8); PG8_WAIT_L(0); PG8_BAR; PG8_MMA(0, 0, At, B0); PG8_MMA(0, 1, At, B1); PG8_BAR; PG8_SCHED;
;             PG8_LDA(At, 0, 1); PG8_STAGE(PG8_SB(0, 0), b2, voffB); PG8_STAGE(PG8_SB(0, 1), b2 + hstep, voffB); PG8_STAGE(PG8_SA(0, 0), a2, voffA);
;             PG8_WAIT_V(8); PG8_WAIT_L(0); PG8_BAR; PG8_MMA(1, 0, At, B0); PG8_MMA(1, 1, At, B1); PG8_BAR; PG8_SCHED;
.LBB0_1341:
	s_add_u32 s4, s1, s24
	s_addc_u32 s5, s30, s25
	s_add_u32 s4, s4, 0x34300100
	s_addc_u32 s5, s5, 0
	s_add_u32 s18, s49, s24
	s_addc_u32 s19, s50, s25
	s_add_i32 s52, 0, 0x10000
	s_cmpk_eq_i32 s24, 0x700
	s_cselect_b32 s29, s11, s5
	s_cselect_b32 s28, s10, s4
	v_add_u32_e32 v165, s52, v162
	s_cselect_b32 s27, s47, s19
	s_cselect_b32 s26, s48, s18
	s_add_i32 s18, 0, 0x14000
	ds_read_b128 v[158:161], v165
	ds_read_b128 v[166:169], v165 offset:1024
	ds_read_b128 v[170:173], v165 offset:2048
	ds_read_b128 v[174:177], v165 offset:3072
	v_add_u32_e32 v165, s18, v162
	ds_read_b128 v[178:181], v165
	ds_read_b128 v[182:185], v165 offset:1024
	ds_read_b128 v[186:189], v165 offset:2048
	ds_read_b128 v[202:205], v165 offset:3072
	v_lshl_add_u64 v[238:239], v[154:155], 0, s[24:25]
	s_add_i32 m0, s36, 0xc000
	ds_read_b128 v[206:209], v164
	ds_read_b128 v[210:213], v164 offset:1024
	ds_read_b128 v[214:217], v164 offset:2048
	ds_read_b128 v[218:221], v164 offset:3072
	ds_read_b128 v[222:225], v164 offset:4096
	ds_read_b128 v[226:229], v164 offset:5120
	ds_read_b128 v[230:233], v164 offset:6144
	ds_read_b128 v[234:237], v164 offset:7168
	global_load_lds_dwordx4 v[238:239], off
	v_lshl_add_u64 v[238:239], v[156:157], 0, s[24:25]
	s_add_i32 m0, s36, 0xe000
	s_nop 0
	global_load_lds_dwordx4 v[238:239], off
	s_waitcnt vmcnt(8)
	s_waitcnt lgkmcnt(0)
	s_barrier
	s_setprio 1
	v_mfma_f32_16x16x32_bf16 v[126:129], v[158:161], v[206:209], v[126:129]
	v_mfma_f32_16x16x32_bf16 v[122:125], v[170:173], v[206:209], v[122:125]
	v_mfma_f32_16x16x32_bf16 v[110:113], v[158:161], v[214:217], v[110:113]
	v_mfma_f32_16x16x32_bf16 v[106:109], v[170:173], v[214:217], v[106:109]
	v_mfma_f32_16x16x32_bf16 v[94:97], v[158:161], v[222:225], v[94:97]
	v_mfma_f32_16x16x32_bf16 v[90:93], v[170:173], v[222:225], v[90:93]
	v_mfma_f32_16x16x32_bf16 v[78:81], v[158:161], v[230:233], v[78:81]
	v_mfma_f32_16x16x32_bf16 v[74:77], v[170:173], v[230:233], v[74:77]
	v_mfma_f32_16x16x32_bf16 v[126:129], v[166:169], v[210:213], v[126:129]
	v_mfma_f32_16x16x32_bf16 v[122:125], v[174:177], v[210:213], v[122:125]
	v_mfma_f32_16x16x32_bf16 v[110:113], v[166:169], v[218:221], v[110:113]
	v_mfma_f32_16x16x32_bf16 v[106:109], v[174:177], v[218:221], v[106:109]
	v_mfma_f32_16x16x32_bf16 v[94:97], v[166:169], v[226:229], v[94:97]
	v_mfma_f32_16x16x32_bf16 v[90:93], v[174:177], v[226:229], v[90:93]
	v_mfma_f32_16x16x32_bf16 v[78:81], v[166:169], v[234:237], v[78:81]
	v_mfma_f32_16x16x32_bf16 v[74:77], v[174:177], v[234:237], v[74:77]
	v_mfma_f32_16x16x32_bf16 v[118:121], v[178:181], v[206:209], v[118:121]
	v_mfma_f32_16x16x32_bf16 v[114:117], v[186:189], v[206:209], v[114:117]
	v_mfma_f32_16x16x32_bf16 v[102:105], v[178:181], v[214:217], v[102:105]
	v_mfma_f32_16x16x32_bf16 v[98:101], v[186:189], v[214:217], v[98:101]
	v_mfma_f32_16x16x32_bf16 v[86:89], v[178:181], v[222:225], v[86:89]
	v_mfma_f32_16x16x32_bf16 v[82:85], v[186:189], v[222:225], v[82:85]
	v_mfma_f32_16x16x32_bf16 v[70:73], v[178:181], v[230:233], v[70:73]
	v_mfma_f32_16x16x32_bf16 v[66:69], v[186:189], v[230:233], v[66:69]
	v_mfma_f32_16x16x32_bf16 v[118:121], v[182:185], v[210:213], v[118:121]
	v_mfma_f32_16x16x32_bf16 v[114:117], v[202:205], v[210:213], v[114:117]
	v_mfma_f32_16x16x32_bf16 v[102:105], v[182:185], v[218:221], v[102:105]
	v_mfma_f32_16x16x32_bf16 v[98:101], v[202:205], v[218:221], v[98:101]
	v_mfma_f32_16x16x32_bf16 v[86:89], v[182:185], v[226:229], v[86:89]
	v_mfma_f32_16x16x32_bf16 v[82:85], v[202:205], v[226:229], v[82:85]
	v_mfma_f32_16x16x32_bf16 v[70:73], v[182:185], v[234:237], v[70:73]
	v_mfma_f32_16x16x32_bf16 v[66:69], v[202:205], v[234:237], v[66:69]
	s_setprio 0
	s_barrier
	s_add_i32 s4, s52, s35
	v_lshl_add_u64 v[238:239], s[26:27], 0, v[152:153]
	s_mov_b32 m0, s4
	ds_read_b128 v[206:209], v164 offset:16384
	ds_read_b128 v[210:213], v164 offset:17408
	ds_read_b128 v[214:217], v164 offset:18432
	ds_read_b128 v[218:221], v164 offset:19456
	ds_read_b128 v[222:225], v164 offset:20480
	ds_read_b128 v[226:229], v164 offset:21504
	ds_read_b128 v[230:233], v164 offset:22528
	ds_read_b128 v[234:237], v164 offset:23552
	global_load_lds_dwordx4 v[238:239], off
	s_add_i32 m0, s4, 0x2000
	s_add_u32 s4, s26, 0x40000
	v_lshl_add_u64 v[240:241], s[26:27], 0, v[150:151]
	s_addc_u32 s5, s27, 0
	s_add_i32 s18, s18, s35
	global_load_lds_dwordx4 v[240:241], off
	v_lshl_add_u64 v[242:243], s[4:5], 0, v[152:153]
	s_mov_b32 m0, s18
	v_lshl_add_u64 v[244:245], s[28:29], 0, v[150:151]
	global_load_lds_dwordx4 v[242:243], off
	v_lshl_add_u64 v[242:243], s[4:5], 0, v[150:151]
	s_add_i32 m0, s18, 0x2000
	s_nop 0
	global_load_lds_dwordx4 v[242:243], off
	v_lshl_add_u64 v[242:243], s[28:29], 0, v[152:153]
	s_mov_b32 m0, s36
	s_nop 0
	global_load_lds_dwordx4 v[242:243], off
	s_mov_b32 m0, s37
	s_nop 0
	global_load_lds_dwordx4 v[244:245], off
	s_waitcnt vmcnt(8)
	s_waitcnt lgkmcnt(0)
	s_barrier
; #define PG8_STAGE(bufoff, gbase, voff) do { _Pragma("unroll") for (int _i = 0; _i < 2; ++_i) \
;         __builtin_amdgcn_global_load_lds((const unsigned*)((const char*)(gbase) + (voff)[_i]), (PG8_LAS unsigned*)(lds + (bufoff) + ldsw + _i * 8192), 16, 0, 0); } while (0)
; #define PG8_LDA(dst, b, h) do { _Pragma("unroll") for (int m = 0; m < 4; ++m) _Pragma("unroll") for (int k = 0; k < 2; ++k) dst[m][k] = *(const PG8_LAS bf16x8*)(lds + PG8_SA(b, h) + aoff + m * 2048 + k * 1024); } while (0)
; #define PG8_LDB(dst, b, h) do { _Pragma("unroll") for (int n = 0; n < 2; ++n) _Pragma("unroll") for (int k = 0; k < 2; ++k) dst[n][k] = *(const PG8_LAS bf16x8*)(lds + PG8_SB(b, h) + boff + n * 2048 + k * 1024); } while (0)
; #define PG8_MMA(ai, bj, At, Bt) do { __builtin_amdgcn_s_setprio(1); _Pragma("unroll") for (int m = 0; m < 4; ++m) _Pragma("unroll") for (int n = 0; n < 2; ++n) _Pragma("unroll") for (int k = 0; k < 2; ++k) \
;         acc[ai][bj][m][n] = __builtin_amdgcn_mfma_f32_16x16x32_bf16(Bt[n][k], At[m][k], acc[ai][bj][m][n], 0, 0, 0); __builtin_amdgcn_s_setprio(0); } while (0)
; #define PG8_WAIT_V(n) asm volatile("s_waitcnt vmcnt(" #n ")" ::: "memory")
; #define PG8_WAIT_L(n) asm volatile("s_waitcnt lgkmcnt(" #n ")" ::: "memory")
; #define PG8_BAR __builtin_amdgcn_s_barrier()
; #define PG8_SCHED __builtin_amdgcn_sched_barrier(0)
; template <class Epi, class Sched, bool ALIGN_EPI = false, bool SP2 = false>
; __device__ __forceinline__ void gemm_phase(PG8_LAS unsigned char* lds, const Gemm g, const Sched& S, const Epi& E) {
;     ...
;             PG8_WAIT_V(8); PG8_WAIT_L(0); PG8_BAR; PG8_MMA(1, 0, At, B0); PG8_MMA(1, 1, At, B1); PG8_BAR; PG8_SCHED;
;             PG8_LDB(B0, 1, 0); PG8_LDB(B1, 1, 1); PG8_SCHED; PG8_LDA(At, 1, 0); PG8_STAGE(PG8_SA(0, 1), a2 + hstep, voffA);
;             PG8_WAIT_V(8); PG8_WAIT_L(0); PG8_BAR; PG8_MMA(0, 0, At, B0); PG8_MMA(0, 1, At, B1); PG8_BAR; PG8_SCHED;
	s_setprio 1
	v_mfma_f32_16x16x32_bf16 v[62:65], v[158:161], v[206:209], v[62:65]
	v_mfma_f32_16x16x32_bf16 v[58:61], v[170:173], v[206:209], v[58:61]
	v_mfma_f32_16x16x32_bf16 v[46:49], v[158:161], v[214:217], v[46:49]
	v_mfma_f32_16x16x32_bf16 v[42:45], v[170:173], v[214:217], v[42:45]
	v_mfma_f32_16x16x32_bf16 v[30:33], v[158:161], v[222:225], v[30:33]
	v_mfma_f32_16x16x32_bf16 v[26:29], v[170:173], v[222:225], v[26:29]
	v_mfma_f32_16x16x32_bf16 v[14:17], v[158:161], v[230:233], v[14:17]
	v_mfma_f32_16x16x32_bf16 v[10:13], v[170:173], v[230:233], v[10:13]
	v_mfma_f32_16x16x32_bf16 v[62:65], v[166:169], v[210:213], v[62:65]
	v_mfma_f32_16x16x32_bf16 v[58:61], v[174:177], v[210:213], v[58:61]
	v_mfma_f32_16x16x32_bf16 v[46:49], v[166:169], v[218:221], v[46:49]
	v_mfma_f32_16x16x32_bf16 v[42:45], v[174:177], v[218:221], v[42:45]
	v_mfma_f32_16x16x32_bf16 v[30:33], v[166:169], v[226:229], v[30:33]
	v_mfma_f32_16x16x32_bf16 v[26:29], v[174:177], v[226:229], v[26:29]
	v_mfma_f32_16x16x32_bf16 v[14:17], v[166:169], v[234:237], v[14:17]
	v_mfma_f32_16x16x32_bf16 v[10:13], v[174:177], v[234:237], v[10:13]
	v_mfma_f32_16x16x32_bf16 v[54:57], v[178:181], v[206:209], v[54:57]
	v_mfma_f32_16x16x32_bf16 v[50:53], v[186:189], v[206:209], v[50:53]
	v_mfma_f32_16x16x32_bf16 v[38:41], v[178:181], v[214:217], v[38:41]
	v_mfma_f32_16x16x32_bf16 v[34:37], v[186:189], v[214:217], v[34:37]
	v_mfma_f32_16x16x32_bf16 v[22:25], v[178:181], v[222:225], v[22:25]
	v_mfma_f32_16x16x32_bf16 v[18:21], v[186:189], v[222:225], v[18:21]
	v_mfma_f32_16x16x32_bf16 v[6:9], v[178:181], v[230:233], v[6:9]
	v_mfma_f32_16x16x32_bf16 v[2:5], v[186:189], v[230:233], v[2:5]
	v_mfma_f32_16x16x32_bf16 v[54:57], v[182:185], v[210:213], v[54:57]
	v_mfma_f32_16x16x32_bf16 v[50:53], v[202:205], v[210:213], v[50:53]
	v_mfma_f32_16x16x32_bf16 v[38:41], v[182:185], v[218:221], v[38:41]
	v_mfma_f32_16x16x32_bf16 v[34:37], v[202:205], v[218:221], v[34:37]
	v_mfma_f32_16x16x32_bf16 v[22:25], v[182:185], v[226:229], v[22:25]
	v_mfma_f32_16x16x32_bf16 v[18:21], v[202:205], v[226:229], v[18:21]
	v_mfma_f32_16x16x32_bf16 v[6:9], v[182:185], v[234:237], v[6:9]
	v_mfma_f32_16x16x32_bf16 v[2:5], v[202:205], v[234:237], v[2:5]
	s_setprio 0
	s_barrier
	s_add_i32 s18, 0, 0x18000
	v_add_u32_e32 v165, s18, v162
	s_add_i32 s19, 0, 0x1c000
	ds_read_b128 v[158:161], v165
	ds_read_b128 v[166:169], v165 offset:1024
	ds_read_b128 v[170:173], v165 offset:2048
	ds_read_b128 v[174:177], v165 offset:3072
	v_add_u32_e32 v165, s19, v162
	ds_read_b128 v[178:181], v165
	ds_read_b128 v[182:185], v165 offset:1024
	ds_read_b128 v[186:189], v165 offset:2048
	ds_read_b128 v[202:205], v165 offset:3072
	s_add_u32 s4, s28, 0x40000
	s_addc_u32 s5, s29, 0
	s_mov_b32 m0, s38
	v_lshl_add_u64 v[246:247], s[4:5], 0, v[152:153]
	ds_read_b128 v[206:209], v164 offset:32768
	ds_read_b128 v[210:213], v164 offset:33792
	ds_read_b128 v[214:217], v164 offset:34816
	ds_read_b128 v[218:221], v164 offset:35840
	ds_read_b128 v[222:225], v164 offset:36864
	ds_read_b128 v[226:229], v164 offset:37888
	ds_read_b128 v[230:233], v164 offset:38912
	ds_read_b128 v[234:237], v164 offset:39936
	global_load_lds_dwordx4 v[246:247], off
	v_lshl_add_u64 v[246:247], s[4:5], 0, v[150:151]
	s_mov_b32 m0, s39
	s_nop 0
	global_load_lds_dwordx4 v[246:247], off
	s_waitcnt vmcnt(8)
	s_waitcnt lgkmcnt(0)
	s_barrier
	s_setprio 1
	v_mfma_f32_16x16x32_bf16 v[126:129], v[158:161], v[206:209], v[126:129]
	v_mfma_f32_16x16x32_bf16 v[122:125], v[170:173], v[206:209], v[122:125]
	v_mfma_f32_16x16x32_bf16 v[110:113], v[158:161], v[214:217], v[110:113]
	v_mfma_f32_16x16x32_bf16 v[106:109], v[170:173], v[214:217], v[106:109]
	v_mfma_f32_16x16x32_bf16 v[94:97], v[158:161], v[222:225], v[94:97]
	v_mfma_f32_16x16x32_bf16 v[90:93], v[170:173], v[222:225], v[90:93]
	v_mfma_f32_16x16x32_bf16 v[78:81], v[158:161], v[230:233], v[78:81]
	v_mfma_f32_16x16x32_bf16 v[74:77], v[170:173], v[230:233], v[74:77]
	v_mfma_f32_16x16x32_bf16 v[126:129], v[166:169], v[210:213], v[126:129]
	v_mfma_f32_16x16x32_bf16 v[122:125], v[174:177], v[210:213], v[122:125]
	v_mfma_f32_16x16x32_bf16 v[110:113], v[166:169], v[218:221], v[110:113]
	v_mfma_f32_16x16x32_bf16 v[106:109], v[174:177], v[218:221], v[106:109]
	v_mfma_f32_16x16x32_bf16 v[94:97], v[166:169], v[226:229], v[94:97]
	v_mfma_f32_16x16x32_bf16 v[90:93], v[174:177], v[226:229], v[90:93]
	v_mfma_f32_16x16x32_bf16 v[78:81], v[166:169], v[234:237], v[78:81]
	v_mfma_f32_16x16x32_bf16 v[74:77], v[174:177], v[234:237], v[74:77]
	v_mfma_f32_16x16x32_bf16 v[118:121], v[178:181], v[206:209], v[118:121]
	v_mfma_f32_16x16x32_bf16 v[114:117], v[186:189], v[206:209], v[114:117]
	v_mfma_f32_16x16x32_bf16 v[102:105], v[178:181], v[214:217], v[102:105]
	v_mfma_f32_16x16x32_bf16 v[98:101], v[186:189], v[214:217], v[98:101]
	v_mfma_f32_16x16x32_bf16 v[86:89], v[178:181], v[222:225], v[86:89]
	v_mfma_f32_16x16x32_bf16 v[82:85], v[186:189], v[222:225], v[82:85]
	v_mfma_f32_16x16x32_bf16 v[70:73], v[178:181], v[230:233], v[70:73]
	v_mfma_f32_16x16x32_bf16 v[66:69], v[186:189], v[230:233], v[66:69]
	v_mfma_f32_16x16x32_bf16 v[118:121], v[182:185], v[210:213], v[118:121]
	v_mfma_f32_16x16x32_bf16 v[114:117], v[202:205], v[210:213], v[114:117]
	v_mfma_f32_16x16x32_bf16 v[102:105], v[182:185], v[218:221], v[102:105]
	v_mfma_f32_16x16x32_bf16 v[98:101], v[202:205], v[218:221], v[98:101]
	v_mfma_f32_16x16x32_bf16 v[86:89], v[182:185], v[226:229], v[86:89]
	v_mfma_f32_16x16x32_bf16 v[82:85], v[202:205], v[226:229], v[82:85]
	v_mfma_f32_16x16x32_bf16 v[70:73], v[182:185], v[234:237], v[70:73]
	v_mfma_f32_16x16x32_bf16 v[66:69], v[202:205], v[234:237], v[66:69]
	s_setprio 0
	s_barrier
; #define PG8_STAGE(bufoff, gbase, voff) do { _Pragma("unroll") for (int _i = 0; _i < 2; ++_i) \
;         __builtin_amdgcn_global_load_lds((const unsigned*)((const char*)(gbase) + (voff)[_i]), (PG8_LAS unsigned*)(lds + (bufoff) + ldsw + _i * 8192), 16, 0, 0); } while (0)
; #define PG8_LDA(dst, b, h) do { _Pragma("unroll") for (int m = 0; m < 4; ++m) _Pragma("unroll") for (int k = 0; k < 2; ++k) dst[m][k] = *(const PG8_LAS bf16x8*)(lds + PG8_SA(b, h) + aoff + m * 2048 + k * 1024); } while (0)
; #define PG8_WAIT_V(n) asm volatile("s_waitcnt vmcnt(" #n ")" ::: "memory")
; template <class Epi, class Sched, bool ALIGN_EPI = false, bool SP2 = false>
; __device__ __forceinline__ void gemm_phase(PG8_LAS unsigned char* lds, const Gemm g, const Sched& S, const Epi& E) {
;     ...
;             PG8_LDA(At, 1, 1); PG8_STAGE(PG8_SB(1, 0), b3, voffB); PG8_STAGE(PG8_SB(1, 1), b3 + hstep, voffB); PG8_STAGE(PG8_SA(1, 0), a3, voffA);
;             PG8_WAIT_V(8); PG8_WAIT_L(0); PG8_BAR; PG8_MMA(1, 0, At, B0); PG8_MMA(1, 1, At, B1); PG8_BAR; PG8_SCHED;
;             } else {
;             PG8_LDB(B0, 0, 0); PG8_SCHED; PG8_LDA(At, 0, 0); PG8_STAGE(PG8_SA(1, 1), a1 + hstep, voffA);
;             PG8_WAIT_L(8); PG8_BAR; PG8_WAIT_L(0); PG8_MMA(0, 0, At, B0); PG8_BAR; PG8_SCHED;
;             PG8_LDB(B1, 0, 1); PG8_STAGE(PG8_SB(0, 0), b2, voffB);
;             PG8_BAR; PG8_WAIT_L(0); PG8_MMA(0, 1, At, B1); PG8_BAR;
;             PG8_LDA(At, 0, 1); PG8_STAGE(PG8_SA(0, 0), a2, voffA);
;             PG8_BAR; PG8_WAIT_L(0); PG8_MMA(1, 0, At, B0); PG8_BAR; PG8_SCHED;
;             PG8_STAGE(PG8_SB(0, 1), b2 + hstep, voffB);
;             PG8_WAIT_V(6); PG8_BAR; PG8_MMA(1, 1, At, B1); PG8_BAR;
;             PG8_LDB(B0, 1, 0); PG8_SCHED; PG8_LDA(At, 1, 0); PG8_STAGE(PG8_SA(0, 1), a2 + hstep, voffA);
;             PG8_WAIT_L(8); PG8_BAR; PG8_WAIT_L(0); PG8_MMA(0, 0, At, B0); PG8_BAR; PG8_SCHED;
;             PG8_LDB(B1, 1, 1); PG8_STAGE(PG8_SB(1, 0), b3, voffB);
;             PG8_BAR; PG8_WAIT_L(0); PG8_MMA(0, 1, At, B1); PG8_BAR;
;             PG8_LDA(At, 1, 1); PG8_STAGE(PG8_SA(1, 0), a3, voffA);
;             PG8_BAR; PG8_WAIT_L(0); PG8_MMA(1, 0, At, B0); PG8_BAR; PG8_SCHED;
;             PG8_STAGE(PG8_SB(1, 1), b3 + hstep, voffB);
;             PG8_WAIT_V(6); PG8_BAR; PG8_MMA(1, 1, At, B1); PG8_BAR;
;             }
;         }
;         if constexpr (ALIGN_EPI) { if (wr == 0) PG8_BAR; }
	s_add_i32 s4, s18, s35
	v_lshl_add_u64 v[238:239], v[238:239], 0, s[62:63]
	s_mov_b32 m0, s4
	ds_read_b128 v[206:209], v164 offset:49152
	ds_read_b128 v[210:213], v164 offset:50176
	ds_read_b128 v[214:217], v164 offset:51200
	ds_read_b128 v[218:221], v164 offset:52224
	ds_read_b128 v[222:225], v164 offset:53248
	ds_read_b128 v[226:229], v164 offset:54272
	ds_read_b128 v[230:233], v164 offset:55296
	ds_read_b128 v[234:237], v164 offset:56320
	global_load_lds_dwordx4 v[238:239], off
	s_add_i32 m0, s4, 0x2000
	s_add_u32 s4, s26, 0x40080
	v_lshl_add_u64 v[238:239], v[240:241], 0, s[62:63]
	s_addc_u32 s5, s27, 0
	s_add_i32 s18, s19, s35
	global_load_lds_dwordx4 v[238:239], off
	v_lshl_add_u64 v[238:239], s[4:5], 0, v[152:153]
	s_mov_b32 m0, s18
	s_nop 0
	global_load_lds_dwordx4 v[238:239], off
	v_lshl_add_u64 v[238:239], s[4:5], 0, v[150:151]
	s_add_i32 m0, s18, 0x2000
	s_nop 0
	global_load_lds_dwordx4 v[238:239], off
	v_lshl_add_u64 v[238:239], v[242:243], 0, s[62:63]
	s_mov_b32 m0, s41
	s_nop 0
	global_load_lds_dwordx4 v[238:239], off
	v_lshl_add_u64 v[238:239], v[244:245], 0, s[62:63]
	s_mov_b32 m0, s42
	s_nop 0
	global_load_lds_dwordx4 v[238:239], off
	s_waitcnt vmcnt(8)
	s_waitcnt lgkmcnt(0)
	s_barrier
	s_setprio 1
	v_mfma_f32_16x16x32_bf16 v[62:65], v[158:161], v[206:209], v[62:65]
	v_mfma_f32_16x16x32_bf16 v[58:61], v[170:173], v[206:209], v[58:61]
	v_mfma_f32_16x16x32_bf16 v[46:49], v[158:161], v[214:217], v[46:49]
	v_mfma_f32_16x16x32_bf16 v[42:45], v[170:173], v[214:217], v[42:45]
	v_mfma_f32_16x16x32_bf16 v[30:33], v[158:161], v[222:225], v[30:33]
	v_mfma_f32_16x16x32_bf16 v[26:29], v[170:173], v[222:225], v[26:29]
	v_mfma_f32_16x16x32_bf16 v[14:17], v[158:161], v[230:233], v[14:17]
	v_mfma_f32_16x16x32_bf16 v[10:13], v[170:173], v[230:233], v[10:13]
	v_mfma_f32_16x16x32_bf16 v[62:65], v[166:169], v[210:213], v[62:65]
	v_mfma_f32_16x16x32_bf16 v[58:61], v[174:177], v[210:213], v[58:61]
	v_mfma_f32_16x16x32_bf16 v[46:49], v[166:169], v[218:221], v[46:49]
	v_mfma_f32_16x16x32_bf16 v[42:45], v[174:177], v[218:221], v[42:45]
	v_mfma_f32_16x16x32_bf16 v[30:33], v[166:169], v[226:229], v[30:33]
	v_mfma_f32_16x16x32_bf16 v[26:29], v[174:177], v[226:229], v[26:29]
	v_mfma_f32_16x16x32_bf16 v[14:17], v[166:169], v[234:237], v[14:17]
	v_mfma_f32_16x16x32_bf16 v[10:13], v[174:177], v[234:237], v[10:13]
	v_mfma_f32_16x16x32_bf16 v[54:57], v[178:181], v[206:209], v[54:57]
	v_mfma_f32_16x16x32_bf16 v[50:53], v[186:189], v[206:209], v[50:53]
	v_mfma_f32_16x16x32_bf16 v[38:41], v[178:181], v[214:217], v[38:41]
	v_mfma_f32_16x16x32_bf16 v[34:37], v[186:189], v[214:217], v[34:37]
	v_mfma_f32_16x16x32_bf16 v[22:25], v[178:181], v[222:225], v[22:25]
	v_mfma_f32_16x16x32_bf16 v[18:21], v[186:189], v[222:225], v[18:21]
	v_mfma_f32_16x16x32_bf16 v[6:9], v[178:181], v[230:233], v[6:9]
	v_mfma_f32_16x16x32_bf16 v[2:5], v[186:189], v[230:233], v[2:5]
	v_mfma_f32_16x16x32_bf16 v[54:57], v[182:185], v[210:213], v[54:57]
	v_mfma_f32_16x16x32_bf16 v[50:53], v[202:205], v[210:213], v[50:53]
	v_mfma_f32_16x16x32_bf16 v[38:41], v[182:185], v[218:221], v[38:41]
	v_mfma_f32_16x16x32_bf16 v[34:37], v[202:205], v[218:221], v[34:37]
	v_mfma_f32_16x16x32_bf16 v[22:25], v[182:185], v[226:229], v[22:25]
	v_mfma_f32_16x16x32_bf16 v[18:21], v[202:205], v[226:229], v[18:21]
	v_mfma_f32_16x16x32_bf16 v[6:9], v[182:185], v[234:237], v[6:9]
	v_mfma_f32_16x16x32_bf16 v[2:5], v[202:205], v[234:237], v[2:5]
	s_setprio 0
	s_barrier
	s_add_i32 s51, s51, 2
	s_add_u32 s24, s24, 0x100
	s_addc_u32 s25, s25, 0
	s_cmp_gt_u32 s51, 13
	s_cbranch_scc0 .LBB0_1341
	s_and_b64 vcc, exec, s[20:21]
	s_cbranch_vccz .LBB0_1344
	s_barrier

; #define PG8_STAGE(bufoff, gbase, voff) do { _Pragma("unroll") for (int _i = 0; _i < 2; ++_i) \
;         __builtin_amdgcn_global_load_lds((const unsigned*)((const char*)(gbase) + (voff)[_i]), (PG8_LAS unsigned*)(lds + (bufoff) + ldsw + _i * 8192), 16, 0, 0); } while (0)
; #define PG8_LDA(dst, b, h) do { _Pragma("unroll") for (int m = 0; m < 4; ++m) _Pragma("unroll") for (int k = 0; k < 2; ++k) dst[m][k] = *(const PG8_LAS bf16x8*)(lds + PG8_SA(b, h) + aoff + m * 2048 + k * 1024); } while (0)
; #define PG8_LDB(dst, b, h) do { _Pragma("unroll") for (int n = 0; n < 2; ++n) _Pragma("unroll") for (int k = 0; k < 2; ++k) dst[n][k] = *(const PG8_LAS bf16x8*)(lds + PG8_SB(b, h) + boff + n * 2048 + k * 1024); } while (0)
; #define PG8_MMA(ai, bj, At, Bt) do { __builtin_amdgcn_s_setprio(1); _Pragma("unroll") for (int m = 0; m < 4; ++m) _Pragma("unroll") for (int n = 0; n < 2; ++n) _Pragma("unroll") for (int k = 0; k < 2; ++k) \
;         acc[ai][bj][m][n] = __builtin_amdgcn_mfma_f32_16x16x32_bf16(Bt[n][k], At[m][k], acc[ai][bj][m][n], 0, 0, 0); __builtin_amdgcn_s_setprio(0); } while (0)
; #define PG8_WAIT_V(n) asm volatile("s_waitcnt vmcnt(" #n ")" ::: "memory")
; #define PG8_WAIT_L(n) asm volatile("s_waitcnt lgkmcnt(" #n ")" ::: "memory")
; template <class Epi, class Sched, bool ALIGN_EPI = false, bool SP2 = false>
; __device__ __forceinline__ void gemm_phase(PG8_LAS unsigned char* lds, const Gemm g, const Sched& S, const Epi& E) {
;     ...
;             const bool last = (t == nt - 2);
;             const char* a1 = cA + (size_t)(t + 1) * kstep;
;             const char* a2 = last ? nA : cA + (size_t)(t + 2) * kstep; const char* b2 = last ? nB : cB + (size_t)(t + 2) * kstep;
;             const char* a3 = a2 + kstep; const char* b3 = b2 + kstep;
;             if (last && has_next) S.a_ready(nxt);
;             if constexpr (SP2) {
;             PG8_LDB(B0, 0, 0); PG8_LDB(B1, 0, 1); PG8_SCHED; PG8_LDA(At, 0, 0); PG8_STAGE(PG8_SA(1, 1), a1 + hstep, voffA);
;             PG8_WAIT_V(8); PG8_WAIT_L(0); PG8_BAR; PG8_MMA(0, 0, At, B0); PG8_MMA(0, 1, At, B1); PG8_BAR; PG8_SCHED;
;             PG8_LDA(At, 0, 1); PG8_STAGE(PG8_SB(0, 0), b2, voffB); PG8_STAGE(PG8_SB(0, 1), b2 + hstep, voffB); PG8_STAGE(PG8_SA(0, 0), a2, voffA);
;             PG8_WAIT_V(8); PG8_WAIT_L(0); PG8_BAR; PG8_MMA(1, 0, At, B0); PG8_MMA(1, 1, At, B1); PG8_BAR; PG8_SCHED;
.LBB0_1387:
	s_add_u32 s1, s6, s20
	s_addc_u32 s4, s7, s21
	s_add_u32 s5, s1, 0xc000100
	s_addc_u32 s4, s4, 0
	s_add_u32 s18, s48, s20
	s_addc_u32 s19, s49, s21
	s_add_i32 s1, 0, 0x10000
	s_cmpk_eq_i32 s20, 0x700
	s_cselect_b32 s25, s11, s4
	s_cselect_b32 s24, s10, s5
	v_add_u32_e32 v164, s1, v166
	s_cselect_b32 s23, s46, s19
	s_cselect_b32 s22, s47, s18
	s_add_i32 s26, 0, 0x14000
	ds_read_b128 v[170:173], v164
	ds_read_b128 v[174:177], v164 offset:1024
	ds_read_b128 v[178:181], v164 offset:2048
	ds_read_b128 v[182:185], v164 offset:3072
	v_add_u32_e32 v164, s26, v166
	ds_read_b128 v[186:189], v164
	ds_read_b128 v[202:205], v164 offset:1024
	ds_read_b128 v[206:209], v164 offset:2048
	ds_read_b128 v[210:213], v164 offset:3072
	v_lshl_add_u64 v[164:165], v[160:161], 0, s[20:21]
	s_add_i32 m0, s34, 0xc000
	ds_read_b128 v[214:217], v168
	ds_read_b128 v[218:221], v168 offset:1024
	ds_read_b128 v[222:225], v168 offset:2048
	ds_read_b128 v[226:229], v168 offset:3072
	ds_read_b128 v[230:233], v168 offset:4096
	ds_read_b128 v[234:237], v168 offset:5120
	ds_read_b128 v[238:241], v168 offset:6144
	ds_read_b128 v[242:245], v168 offset:7168
	global_load_lds_dwordx4 v[164:165], off
	v_lshl_add_u64 v[164:165], v[162:163], 0, s[20:21]
	s_add_i32 m0, s34, 0xe000
	s_nop 0
	global_load_lds_dwordx4 v[164:165], off
	s_waitcnt vmcnt(8)
	s_waitcnt lgkmcnt(0)
	s_barrier
	s_setprio 1
	v_mfma_f32_16x16x32_bf16 v[126:129], v[170:173], v[214:217], v[126:129]
	v_mfma_f32_16x16x32_bf16 v[118:121], v[178:181], v[214:217], v[118:121]
	v_mfma_f32_16x16x32_bf16 v[110:113], v[170:173], v[222:225], v[110:113]
	v_mfma_f32_16x16x32_bf16 v[102:105], v[178:181], v[222:225], v[102:105]
	v_mfma_f32_16x16x32_bf16 v[94:97], v[170:173], v[230:233], v[94:97]
	v_mfma_f32_16x16x32_bf16 v[86:89], v[178:181], v[230:233], v[86:89]
	v_mfma_f32_16x16x32_bf16 v[78:81], v[170:173], v[238:241], v[78:81]
	v_mfma_f32_16x16x32_bf16 v[70:73], v[178:181], v[238:241], v[70:73]
	v_mfma_f32_16x16x32_bf16 v[126:129], v[174:177], v[218:221], v[126:129]
	v_mfma_f32_16x16x32_bf16 v[118:121], v[182:185], v[218:221], v[118:121]
	v_mfma_f32_16x16x32_bf16 v[110:113], v[174:177], v[226:229], v[110:113]
	v_mfma_f32_16x16x32_bf16 v[102:105], v[182:185], v[226:229], v[102:105]
	v_mfma_f32_16x16x32_bf16 v[94:97], v[174:177], v[234:237], v[94:97]
	v_mfma_f32_16x16x32_bf16 v[86:89], v[182:185], v[234:237], v[86:89]
	v_mfma_f32_16x16x32_bf16 v[78:81], v[174:177], v[242:245], v[78:81]
	v_mfma_f32_16x16x32_bf16 v[70:73], v[182:185], v[242:245], v[70:73]
	v_mfma_f32_16x16x32_bf16 v[122:125], v[186:189], v[214:217], v[122:125]
	v_mfma_f32_16x16x32_bf16 v[114:117], v[206:209], v[214:217], v[114:117]
	v_mfma_f32_16x16x32_bf16 v[106:109], v[186:189], v[222:225], v[106:109]
	v_mfma_f32_16x16x32_bf16 v[98:101], v[206:209], v[222:225], v[98:101]
	v_mfma_f32_16x16x32_bf16 v[90:93], v[186:189], v[230:233], v[90:93]
	v_mfma_f32_16x16x32_bf16 v[82:85], v[206:209], v[230:233], v[82:85]
	v_mfma_f32_16x16x32_bf16 v[74:77], v[186:189], v[238:241], v[74:77]
	v_mfma_f32_16x16x32_bf16 v[66:69], v[206:209], v[238:241], v[66:69]
	v_mfma_f32_16x16x32_bf16 v[122:125], v[202:205], v[218:221], v[122:125]
	v_mfma_f32_16x16x32_bf16 v[114:117], v[210:213], v[218:221], v[114:117]
	v_mfma_f32_16x16x32_bf16 v[106:109], v[202:205], v[226:229], v[106:109]
	v_mfma_f32_16x16x32_bf16 v[98:101], v[210:213], v[226:229], v[98:101]
	v_mfma_f32_16x16x32_bf16 v[90:93], v[202:205], v[234:237], v[90:93]
	v_mfma_f32_16x16x32_bf16 v[82:85], v[210:213], v[234:237], v[82:85]
	v_mfma_f32_16x16x32_bf16 v[74:77], v[202:205], v[242:245], v[74:77]
	v_mfma_f32_16x16x32_bf16 v[66:69], v[210:213], v[242:245], v[66:69]
	s_setprio 0
	s_barrier
	s_add_i32 s4, s1, s31
	v_lshl_add_u64 v[164:165], s[22:23], 0, v[154:155]
	s_mov_b32 m0, s4
	ds_read_b128 v[214:217], v168 offset:16384
	ds_read_b128 v[218:221], v168 offset:17408
	ds_read_b128 v[222:225], v168 offset:18432
	ds_read_b128 v[226:229], v168 offset:19456
	ds_read_b128 v[230:233], v168 offset:20480
	ds_read_b128 v[234:237], v168 offset:21504
	ds_read_b128 v[238:241], v168 offset:22528
	ds_read_b128 v[242:245], v168 offset:23552
	global_load_lds_dwordx4 v[164:165], off
	s_add_i32 m0, s4, 0x2000
	s_add_u32 s4, s22, 0x40000
	v_lshl_add_u64 v[246:247], s[22:23], 0, v[150:151]
	s_addc_u32 s5, s23, 0
	s_add_i32 s18, s26, s31
	global_load_lds_dwordx4 v[246:247], off
	v_lshl_add_u64 v[248:249], s[4:5], 0, v[154:155]
	s_mov_b32 m0, s18
	v_lshl_add_u64 v[250:251], s[24:25], 0, v[152:153]
	global_load_lds_dwordx4 v[248:249], off
	v_lshl_add_u64 v[248:249], s[4:5], 0, v[150:151]
	s_add_i32 m0, s18, 0x2000
	s_nop 0
	global_load_lds_dwordx4 v[248:249], off
	v_lshl_add_u64 v[248:249], s[24:25], 0, v[156:157]
	s_mov_b32 m0, s34
	s_nop 0
	global_load_lds_dwordx4 v[248:249], off
	s_mov_b32 m0, s35
	s_nop 0
	global_load_lds_dwordx4 v[250:251], off
	s_waitcnt vmcnt(8)
	s_waitcnt lgkmcnt(0)
	s_barrier
; #define PG8_STAGE(bufoff, gbase, voff) do { _Pragma("unroll") for (int _i = 0; _i < 2; ++_i) \
;         __builtin_amdgcn_global_load_lds((const unsigned*)((const char*)(gbase) + (voff)[_i]), (PG8_LAS unsigned*)(lds + (bufoff) + ldsw + _i * 8192), 16, 0, 0); } while (0)
; #define PG8_LDA(dst, b, h) do { _Pragma("unroll") for (int m = 0; m < 4; ++m) _Pragma("unroll") for (int k = 0; k < 2; ++k) dst[m][k] = *(const PG8_LAS bf16x8*)(lds + PG8_SA(b, h) + aoff + m * 2048 + k * 1024); } while (0)
; #define PG8_LDB(dst, b, h) do { _Pragma("unroll") for (int n = 0; n < 2; ++n) _Pragma("unroll") for (int k = 0; k < 2; ++k) dst[n][k] = *(const PG8_LAS bf16x8*)(lds + PG8_SB(b, h) + boff + n * 2048 + k * 1024); } while (0)
; #define PG8_MMA(ai, bj, At, Bt) do { __builtin_amdgcn_s_setprio(1); _Pragma("unroll") for (int m = 0; m < 4; ++m) _Pragma("unroll") for (int n = 0; n < 2; ++n) _Pragma("unroll") for (int k = 0; k < 2; ++k) \
;         acc[ai][bj][m][n] = __builtin_amdgcn_mfma_f32_16x16x32_bf16(Bt[n][k], At[m][k], acc[ai][bj][m][n], 0, 0, 0); __builtin_amdgcn_s_setprio(0); } while (0)
; #define PG8_WAIT_V(n) asm volatile("s_waitcnt vmcnt(" #n ")" ::: "memory")
; #define PG8_WAIT_L(n) asm volatile("s_waitcnt lgkmcnt(" #n ")" ::: "memory")
; #define PG8_BAR __builtin_amdgcn_s_barrier()
; #define PG8_SCHED __builtin_amdgcn_sched_barrier(0)
; template <class Epi, class Sched, bool ALIGN_EPI = false, bool SP2 = false>
; __device__ __forceinline__ void gemm_phase(PG8_LAS unsigned char* lds, const Gemm g, const Sched& S, const Epi& E) {
;     ...
;             PG8_WAIT_V(8); PG8_WAIT_L(0); PG8_BAR; PG8_MMA(1, 0, At, B0); PG8_MMA(1, 1, At, B1); PG8_BAR; PG8_SCHED;
;             PG8_LDB(B0, 1, 0); PG8_LDB(B1, 1, 1); PG8_SCHED; PG8_LDA(At, 1, 0); PG8_STAGE(PG8_SA(0, 1), a2 + hstep, voffA);
;             PG8_WAIT_V(8); PG8_WAIT_L(0); PG8_BAR; PG8_MMA(0, 0, At, B0); PG8_MMA(0, 1, At, B1); PG8_BAR; PG8_SCHED;
	s_setprio 1
	v_mfma_f32_16x16x32_bf16 v[62:65], v[170:173], v[214:217], v[62:65]
	v_mfma_f32_16x16x32_bf16 v[54:57], v[178:181], v[214:217], v[54:57]
	v_mfma_f32_16x16x32_bf16 v[46:49], v[170:173], v[222:225], v[46:49]
	v_mfma_f32_16x16x32_bf16 v[38:41], v[178:181], v[222:225], v[38:41]
	v_mfma_f32_16x16x32_bf16 v[30:33], v[170:173], v[230:233], v[30:33]
	v_mfma_f32_16x16x32_bf16 v[22:25], v[178:181], v[230:233], v[22:25]
	v_mfma_f32_16x16x32_bf16 v[14:17], v[170:173], v[238:241], v[14:17]
	v_mfma_f32_16x16x32_bf16 v[6:9], v[178:181], v[238:241], v[6:9]
	v_mfma_f32_16x16x32_bf16 v[62:65], v[174:177], v[218:221], v[62:65]
	v_mfma_f32_16x16x32_bf16 v[54:57], v[182:185], v[218:221], v[54:57]
	v_mfma_f32_16x16x32_bf16 v[46:49], v[174:177], v[226:229], v[46:49]
	v_mfma_f32_16x16x32_bf16 v[38:41], v[182:185], v[226:229], v[38:41]
	v_mfma_f32_16x16x32_bf16 v[30:33], v[174:177], v[234:237], v[30:33]
	v_mfma_f32_16x16x32_bf16 v[22:25], v[182:185], v[234:237], v[22:25]
	v_mfma_f32_16x16x32_bf16 v[14:17], v[174:177], v[242:245], v[14:17]
	v_mfma_f32_16x16x32_bf16 v[6:9], v[182:185], v[242:245], v[6:9]
	v_mfma_f32_16x16x32_bf16 v[58:61], v[186:189], v[214:217], v[58:61]
	v_mfma_f32_16x16x32_bf16 v[50:53], v[206:209], v[214:217], v[50:53]
	v_mfma_f32_16x16x32_bf16 v[42:45], v[186:189], v[222:225], v[42:45]
	v_mfma_f32_16x16x32_bf16 v[34:37], v[206:209], v[222:225], v[34:37]
	v_mfma_f32_16x16x32_bf16 v[26:29], v[186:189], v[230:233], v[26:29]
	v_mfma_f32_16x16x32_bf16 v[18:21], v[206:209], v[230:233], v[18:21]
	v_mfma_f32_16x16x32_bf16 v[10:13], v[186:189], v[238:241], v[10:13]
	v_mfma_f32_16x16x32_bf16 v[2:5], v[206:209], v[238:241], v[2:5]
	v_mfma_f32_16x16x32_bf16 v[58:61], v[202:205], v[218:221], v[58:61]
	v_mfma_f32_16x16x32_bf16 v[50:53], v[210:213], v[218:221], v[50:53]
	v_mfma_f32_16x16x32_bf16 v[42:45], v[202:205], v[226:229], v[42:45]
	v_mfma_f32_16x16x32_bf16 v[34:37], v[210:213], v[226:229], v[34:37]
	v_mfma_f32_16x16x32_bf16 v[26:29], v[202:205], v[234:237], v[26:29]
	v_mfma_f32_16x16x32_bf16 v[18:21], v[210:213], v[234:237], v[18:21]
	v_mfma_f32_16x16x32_bf16 v[10:13], v[202:205], v[242:245], v[10:13]
	v_mfma_f32_16x16x32_bf16 v[2:5], v[210:213], v[242:245], v[2:5]
	s_setprio 0
	s_barrier
	s_add_i32 s27, 0, 0x18000
	v_add_u32_e32 v169, s27, v166
	s_add_i32 s28, 0, 0x1c000
	ds_read_b128 v[170:173], v169
	ds_read_b128 v[174:177], v169 offset:1024
	ds_read_b128 v[178:181], v169 offset:2048
	ds_read_b128 v[182:185], v169 offset:3072
	v_add_u32_e32 v169, s28, v166
	ds_read_b128 v[186:189], v169
	ds_read_b128 v[202:205], v169 offset:1024
	ds_read_b128 v[206:209], v169 offset:2048
	ds_read_b128 v[210:213], v169 offset:3072
	s_add_u32 s4, s24, 0x40000
	s_addc_u32 s5, s25, 0
	s_mov_b32 m0, s36
	v_lshl_add_u64 v[252:253], s[4:5], 0, v[156:157]
	ds_read_b128 v[214:217], v168 offset:32768
	ds_read_b128 v[218:221], v168 offset:33792
	ds_read_b128 v[222:225], v168 offset:34816
	ds_read_b128 v[226:229], v168 offset:35840
	ds_read_b128 v[230:233], v168 offset:36864
	ds_read_b128 v[234:237], v168 offset:37888
	ds_read_b128 v[238:241], v168 offset:38912
	ds_read_b128 v[242:245], v168 offset:39936
	global_load_lds_dwordx4 v[252:253], off
	v_lshl_add_u64 v[252:253], s[4:5], 0, v[152:153]
	s_mov_b32 m0, s37
	s_nop 0
	global_load_lds_dwordx4 v[252:253], off
	s_waitcnt vmcnt(8)
	s_waitcnt lgkmcnt(0)
	s_barrier
	s_setprio 1
	v_mfma_f32_16x16x32_bf16 v[126:129], v[170:173], v[214:217], v[126:129]
	v_mfma_f32_16x16x32_bf16 v[118:121], v[178:181], v[214:217], v[118:121]
	v_mfma_f32_16x16x32_bf16 v[110:113], v[170:173], v[222:225], v[110:113]
	v_mfma_f32_16x16x32_bf16 v[102:105], v[178:181], v[222:225], v[102:105]
	v_mfma_f32_16x16x32_bf16 v[94:97], v[170:173], v[230:233], v[94:97]
	v_mfma_f32_16x16x32_bf16 v[86:89], v[178:181], v[230:233], v[86:89]
	v_mfma_f32_16x16x32_bf16 v[78:81], v[170:173], v[238:241], v[78:81]
	v_mfma_f32_16x16x32_bf16 v[70:73], v[178:181], v[238:241], v[70:73]
	v_mfma_f32_16x16x32_bf16 v[126:129], v[174:177], v[218:221], v[126:129]
	v_mfma_f32_16x16x32_bf16 v[118:121], v[182:185], v[218:221], v[118:121]
	v_mfma_f32_16x16x32_bf16 v[110:113], v[174:177], v[226:229], v[110:113]
	v_mfma_f32_16x16x32_bf16 v[102:105], v[182:185], v[226:229], v[102:105]
	v_mfma_f32_16x16x32_bf16 v[94:97], v[174:177], v[234:237], v[94:97]
	v_mfma_f32_16x16x32_bf16 v[86:89], v[182:185], v[234:237], v[86:89]
	v_mfma_f32_16x16x32_bf16 v[78:81], v[174:177], v[242:245], v[78:81]
	v_mfma_f32_16x16x32_bf16 v[70:73], v[182:185], v[242:245], v[70:73]
	v_mfma_f32_16x16x32_bf16 v[122:125], v[186:189], v[214:217], v[122:125]
	v_mfma_f32_16x16x32_bf16 v[114:117], v[206:209], v[214:217], v[114:117]
	v_mfma_f32_16x16x32_bf16 v[106:109], v[186:189], v[222:225], v[106:109]
	v_mfma_f32_16x16x32_bf16 v[98:101], v[206:209], v[222:225], v[98:101]
	v_mfma_f32_16x16x32_bf16 v[90:93], v[186:189], v[230:233], v[90:93]
	v_mfma_f32_16x16x32_bf16 v[82:85], v[206:209], v[230:233], v[82:85]
	v_mfma_f32_16x16x32_bf16 v[74:77], v[186:189], v[238:241], v[74:77]
	v_mfma_f32_16x16x32_bf16 v[66:69], v[206:209], v[238:241], v[66:69]
	v_mfma_f32_16x16x32_bf16 v[122:125], v[202:205], v[218:221], v[122:125]
	v_mfma_f32_16x16x32_bf16 v[114:117], v[210:213], v[218:221], v[114:117]
	v_mfma_f32_16x16x32_bf16 v[106:109], v[202:205], v[226:229], v[106:109]
	v_mfma_f32_16x16x32_bf16 v[98:101], v[210:213], v[226:229], v[98:101]
	v_mfma_f32_16x16x32_bf16 v[90:93], v[202:205], v[234:237], v[90:93]
	v_mfma_f32_16x16x32_bf16 v[82:85], v[210:213], v[234:237], v[82:85]
	v_mfma_f32_16x16x32_bf16 v[74:77], v[202:205], v[242:245], v[74:77]
	v_mfma_f32_16x16x32_bf16 v[66:69], v[210:213], v[242:245], v[66:69]
	s_setprio 0
	s_barrier
; #define PG8_STAGE(bufoff, gbase, voff) do { _Pragma("unroll") for (int _i = 0; _i < 2; ++_i) \
;         __builtin_amdgcn_global_load_lds((const unsigned*)((const char*)(gbase) + (voff)[_i]), (PG8_LAS unsigned*)(lds + (bufoff) + ldsw + _i * 8192), 16, 0, 0); } while (0)
; #define PG8_LDA(dst, b, h) do { _Pragma("unroll") for (int m = 0; m < 4; ++m) _Pragma("unroll") for (int k = 0; k < 2; ++k) dst[m][k] = *(const PG8_LAS bf16x8*)(lds + PG8_SA(b, h) + aoff + m * 2048 + k * 1024); } while (0)
; #define PG8_WAIT_V(n) asm volatile("s_waitcnt vmcnt(" #n ")" ::: "memory")
; template <class Epi, class Sched, bool ALIGN_EPI = false, bool SP2 = false>
; __device__ __forceinline__ void gemm_phase(PG8_LAS unsigned char* lds, const Gemm g, const Sched& S, const Epi& E) {
;     ...
;             PG8_LDA(At, 1, 1); PG8_STAGE(PG8_SB(1, 0), b3, voffB); PG8_STAGE(PG8_SB(1, 1), b3 + hstep, voffB); PG8_STAGE(PG8_SA(1, 0), a3, voffA);
;             PG8_WAIT_V(8); PG8_WAIT_L(0); PG8_BAR; PG8_MMA(1, 0, At, B0); PG8_MMA(1, 1, At, B1); PG8_BAR; PG8_SCHED;
;             } else {
;             PG8_LDB(B0, 0, 0); PG8_SCHED; PG8_LDA(At, 0, 0); PG8_STAGE(PG8_SA(1, 1), a1 + hstep, voffA);
;             PG8_WAIT_L(8); PG8_BAR; PG8_WAIT_L(0); PG8_MMA(0, 0, At, B0); PG8_BAR; PG8_SCHED;
;             PG8_LDB(B1, 0, 1); PG8_STAGE(PG8_SB(0, 0), b2, voffB);
;             PG8_BAR; PG8_WAIT_L(0); PG8_MMA(0, 1, At, B1); PG8_BAR;
;             PG8_LDA(At, 0, 1); PG8_STAGE(PG8_SA(0, 0), a2, voffA);
;             PG8_BAR; PG8_WAIT_L(0); PG8_MMA(1, 0, At, B0); PG8_BAR; PG8_SCHED;
;             PG8_STAGE(PG8_SB(0, 1), b2 + hstep, voffB);
;             PG8_WAIT_V(6); PG8_BAR; PG8_MMA(1, 1, At, B1); PG8_BAR;
;             PG8_LDB(B0, 1, 0); PG8_SCHED; PG8_LDA(At, 1, 0); PG8_STAGE(PG8_SA(0, 1), a2 + hstep, voffA);
;             PG8_WAIT_L(8); PG8_BAR; PG8_WAIT_L(0); PG8_MMA(0, 0, At, B0); PG8_BAR; PG8_SCHED;
;             PG8_LDB(B1, 1, 1); PG8_STAGE(PG8_SB(1, 0), b3, voffB);
;             PG8_BAR; PG8_WAIT_L(0); PG8_MMA(0, 1, At, B1); PG8_BAR;
;             PG8_LDA(At, 1, 1); PG8_STAGE(PG8_SA(1, 0), a3, voffA);
;             PG8_BAR; PG8_WAIT_L(0); PG8_MMA(1, 0, At, B0); PG8_BAR; PG8_SCHED;
;             PG8_STAGE(PG8_SB(1, 1), b3 + hstep, voffB);
;             PG8_WAIT_V(6); PG8_BAR; PG8_MMA(1, 1, At, B1); PG8_BAR;
;             }
;         }
;         if constexpr (ALIGN_EPI) { if (wr == 0) PG8_BAR; }
	s_add_i32 s4, s27, s31
	v_lshl_add_u64 v[164:165], v[164:165], 0, s[62:63]
	s_mov_b32 m0, s4
	ds_read_b128 v[214:217], v168 offset:49152
	ds_read_b128 v[218:221], v168 offset:50176
	ds_read_b128 v[222:225], v168 offset:51200
	ds_read_b128 v[226:229], v168 offset:52224
	ds_read_b128 v[230:233], v168 offset:53248
	ds_read_b128 v[234:237], v168 offset:54272
	ds_read_b128 v[238:241], v168 offset:55296
	ds_read_b128 v[242:245], v168 offset:56320
	global_load_lds_dwordx4 v[164:165], off
	s_add_i32 m0, s4, 0x2000
	s_add_u32 s4, s22, 0x40080
	v_lshl_add_u64 v[164:165], v[246:247], 0, s[62:63]
	s_addc_u32 s5, s23, 0
	s_add_i32 s18, s28, s31
	global_load_lds_dwordx4 v[164:165], off
	v_lshl_add_u64 v[164:165], s[4:5], 0, v[154:155]
	s_mov_b32 m0, s18
	s_nop 0
	global_load_lds_dwordx4 v[164:165], off
	v_lshl_add_u64 v[164:165], s[4:5], 0, v[150:151]
	s_add_i32 m0, s18, 0x2000
	s_nop 0
	global_load_lds_dwordx4 v[164:165], off
	v_lshl_add_u64 v[164:165], v[248:249], 0, s[62:63]
	s_mov_b32 m0, s41
	s_nop 0
	global_load_lds_dwordx4 v[164:165], off
	v_lshl_add_u64 v[164:165], v[250:251], 0, s[62:63]
	s_mov_b32 m0, s42
	s_nop 0
	global_load_lds_dwordx4 v[164:165], off
	s_waitcnt vmcnt(8)
	s_waitcnt lgkmcnt(0)
	s_barrier
	s_setprio 1
	v_mfma_f32_16x16x32_bf16 v[62:65], v[170:173], v[214:217], v[62:65]
	v_mfma_f32_16x16x32_bf16 v[54:57], v[178:181], v[214:217], v[54:57]
	v_mfma_f32_16x16x32_bf16 v[46:49], v[170:173], v[222:225], v[46:49]
	v_mfma_f32_16x16x32_bf16 v[38:41], v[178:181], v[222:225], v[38:41]
	v_mfma_f32_16x16x32_bf16 v[30:33], v[170:173], v[230:233], v[30:33]
	v_mfma_f32_16x16x32_bf16 v[22:25], v[178:181], v[230:233], v[22:25]
	v_mfma_f32_16x16x32_bf16 v[14:17], v[170:173], v[238:241], v[14:17]
	v_mfma_f32_16x16x32_bf16 v[6:9], v[178:181], v[238:241], v[6:9]
	v_mfma_f32_16x16x32_bf16 v[62:65], v[174:177], v[218:221], v[62:65]
	v_mfma_f32_16x16x32_bf16 v[54:57], v[182:185], v[218:221], v[54:57]
	v_mfma_f32_16x16x32_bf16 v[46:49], v[174:177], v[226:229], v[46:49]
	v_mfma_f32_16x16x32_bf16 v[38:41], v[182:185], v[226:229], v[38:41]
	v_mfma_f32_16x16x32_bf16 v[30:33], v[174:177], v[234:237], v[30:33]
	v_mfma_f32_16x16x32_bf16 v[22:25], v[182:185], v[234:237], v[22:25]
	v_mfma_f32_16x16x32_bf16 v[14:17], v[174:177], v[242:245], v[14:17]
	v_mfma_f32_16x16x32_bf16 v[6:9], v[182:185], v[242:245], v[6:9]
	v_mfma_f32_16x16x32_bf16 v[58:61], v[186:189], v[214:217], v[58:61]
	v_mfma_f32_16x16x32_bf16 v[50:53], v[206:209], v[214:217], v[50:53]
	v_mfma_f32_16x16x32_bf16 v[42:45], v[186:189], v[222:225], v[42:45]
	v_mfma_f32_16x16x32_bf16 v[34:37], v[206:209], v[222:225], v[34:37]
	v_mfma_f32_16x16x32_bf16 v[26:29], v[186:189], v[230:233], v[26:29]
	v_mfma_f32_16x16x32_bf16 v[18:21], v[206:209], v[230:233], v[18:21]
	v_mfma_f32_16x16x32_bf16 v[10:13], v[186:189], v[238:241], v[10:13]
	v_mfma_f32_16x16x32_bf16 v[2:5], v[206:209], v[238:241], v[2:5]
	v_mfma_f32_16x16x32_bf16 v[58:61], v[202:205], v[218:221], v[58:61]
	v_mfma_f32_16x16x32_bf16 v[50:53], v[210:213], v[218:221], v[50:53]
	v_mfma_f32_16x16x32_bf16 v[42:45], v[202:205], v[226:229], v[42:45]
	v_mfma_f32_16x16x32_bf16 v[34:37], v[210:213], v[226:229], v[34:37]
	v_mfma_f32_16x16x32_bf16 v[26:29], v[202:205], v[234:237], v[26:29]
	v_mfma_f32_16x16x32_bf16 v[18:21], v[210:213], v[234:237], v[18:21]
	v_mfma_f32_16x16x32_bf16 v[10:13], v[202:205], v[242:245], v[10:13]
	v_mfma_f32_16x16x32_bf16 v[2:5], v[210:213], v[242:245], v[2:5]
	s_setprio 0
	s_barrier
	s_add_i32 s50, s50, 2
	s_add_u32 s20, s20, 0x100
	s_addc_u32 s21, s21, 0
	s_cmp_gt_u32 s50, 13
	s_cbranch_scc0 .LBB0_1387
	s_and_b64 vcc, exec, s[14:15]
	s_cbranch_vccz .LBB0_1390
	s_barrier

; #define PG8_STAGE(bufoff, gbase, voff) do { _Pragma("unroll") for (int _i = 0; _i < 2; ++_i) \
;         __builtin_amdgcn_global_load_lds((const unsigned*)((const char*)(gbase) + (voff)[_i]), (PG8_LAS unsigned*)(lds + (bufoff) + ldsw + _i * 8192), 16, 0, 0); } while (0)
; #define PG8_LDA(dst, b, h) do { _Pragma("unroll") for (int m = 0; m < 4; ++m) _Pragma("unroll") for (int k = 0; k < 2; ++k) dst[m][k] = *(const PG8_LAS bf16x8*)(lds + PG8_SA(b, h) + aoff + m * 2048 + k * 1024); } while (0)
; #define PG8_LDB(dst, b, h) do { _Pragma("unroll") for (int n = 0; n < 2; ++n) _Pragma("unroll") for (int k = 0; k < 2; ++k) dst[n][k] = *(const PG8_LAS bf16x8*)(lds + PG8_SB(b, h) + boff + n * 2048 + k * 1024); } while (0)
; #define PG8_MMA(ai, bj, At, Bt) do { __builtin_amdgcn_s_setprio(1); _Pragma("unroll") for (int m = 0; m < 4; ++m) _Pragma("unroll") for (int n = 0; n < 2; ++n) _Pragma("unroll") for (int k = 0; k < 2; ++k) \
;         acc[ai][bj][m][n] = __builtin_amdgcn_mfma_f32_16x16x32_bf16(Bt[n][k], At[m][k], acc[ai][bj][m][n], 0, 0, 0); __builtin_amdgcn_s_setprio(0); } while (0)
; #define PG8_WAIT_V(n) asm volatile("s_waitcnt vmcnt(" #n ")" ::: "memory")
; #define PG8_WAIT_L(n) asm volatile("s_waitcnt lgkmcnt(" #n ")" ::: "memory")
; template <class Epi, class Sched, bool ALIGN_EPI = false, bool SP2 = false>
; __device__ __forceinline__ void gemm_phase(PG8_LAS unsigned char* lds, const Gemm g, const Sched& S, const Epi& E) {
;     ...
;             const bool last = (t == nt - 2);
;             const char* a1 = cA + (size_t)(t + 1) * kstep;
;             const char* a2 = last ? nA : cA + (size_t)(t + 2) * kstep; const char* b2 = last ? nB : cB + (size_t)(t + 2) * kstep;
;             const char* a3 = a2 + kstep; const char* b3 = b2 + kstep;
;             if (last && has_next) S.a_ready(nxt);
;             if constexpr (SP2) {
;             PG8_LDB(B0, 0, 0); PG8_LDB(B1, 0, 1); PG8_SCHED; PG8_LDA(At, 0, 0); PG8_STAGE(PG8_SA(1, 1), a1 + hstep, voffA);
;             PG8_WAIT_V(8); PG8_WAIT_L(0); PG8_BAR; PG8_MMA(0, 0, At, B0); PG8_MMA(0, 1, At, B1); PG8_BAR; PG8_SCHED;
;             PG8_LDA(At, 0, 1); PG8_STAGE(PG8_SB(0, 0), b2, voffB); PG8_STAGE(PG8_SB(0, 1), b2 + hstep, voffB); PG8_STAGE(PG8_SA(0, 0), a2, voffA);
;             PG8_WAIT_V(8); PG8_WAIT_L(0); PG8_BAR; PG8_MMA(1, 0, At, B0); PG8_MMA(1, 1, At, B1); PG8_BAR; PG8_SCHED;
.LBB0_1415:
	v_add_u32_e32 v161, s1, v159
	ds_read_b128 v[162:165], v161
	ds_read_b128 v[166:169], v161 offset:1024
	ds_read_b128 v[170:173], v161 offset:2048
	ds_read_b128 v[174:177], v161 offset:3072
	v_add_u32_e32 v161, s26, v159
	s_add_u32 s4, s31, s10
	ds_read_b128 v[178:181], v161
	ds_read_b128 v[182:185], v161 offset:1024
	ds_read_b128 v[186:189], v161 offset:2048
	ds_read_b128 v[202:205], v161 offset:3072
	s_addc_u32 s5, s34, s11
	s_add_u32 s4, s4, 0x3d00100
	s_addc_u32 s5, s5, 0
	s_add_u32 s12, s35, s10
	s_addc_u32 s13, s36, s11
	s_cmpk_eq_i32 s10, 0xa00
	s_cselect_b32 s15, s7, s5
	s_cselect_b32 s14, s6, s4
	s_cselect_b32 s13, s9, s13
	s_cselect_b32 s12, s8, s12
	v_lshl_add_u64 v[238:239], v[154:155], 0, s[10:11]
	s_add_i32 m0, s20, 0xc000
	ds_read_b128 v[206:209], v160
	ds_read_b128 v[210:213], v160 offset:1024
	ds_read_b128 v[214:217], v160 offset:2048
	ds_read_b128 v[218:221], v160 offset:3072
	ds_read_b128 v[222:225], v160 offset:4096
	ds_read_b128 v[226:229], v160 offset:5120
	ds_read_b128 v[230:233], v160 offset:6144
	ds_read_b128 v[234:237], v160 offset:7168
	global_load_lds_dwordx4 v[238:239], off
	v_lshl_add_u64 v[238:239], v[156:157], 0, s[10:11]
	s_add_i32 m0, s20, 0xe000
	s_nop 0
	global_load_lds_dwordx4 v[238:239], off
	s_waitcnt vmcnt(8)
	s_waitcnt lgkmcnt(0)
	s_barrier
	s_setprio 1
	v_mfma_f32_16x16x32_bf16 v[126:129], v[162:165], v[206:209], v[126:129]
	v_mfma_f32_16x16x32_bf16 v[122:125], v[170:173], v[206:209], v[122:125]
	v_mfma_f32_16x16x32_bf16 v[118:121], v[162:165], v[214:217], v[118:121]
	v_mfma_f32_16x16x32_bf16 v[114:117], v[170:173], v[214:217], v[114:117]
	v_mfma_f32_16x16x32_bf16 v[102:105], v[162:165], v[222:225], v[102:105]
	v_mfma_f32_16x16x32_bf16 v[98:101], v[170:173], v[222:225], v[98:101]
	v_mfma_f32_16x16x32_bf16 v[86:89], v[162:165], v[230:233], v[86:89]
	v_mfma_f32_16x16x32_bf16 v[82:85], v[170:173], v[230:233], v[82:85]
	v_mfma_f32_16x16x32_bf16 v[126:129], v[166:169], v[210:213], v[126:129]
	v_mfma_f32_16x16x32_bf16 v[122:125], v[174:177], v[210:213], v[122:125]
	v_mfma_f32_16x16x32_bf16 v[118:121], v[166:169], v[218:221], v[118:121]
	v_mfma_f32_16x16x32_bf16 v[114:117], v[174:177], v[218:221], v[114:117]
	v_mfma_f32_16x16x32_bf16 v[102:105], v[166:169], v[226:229], v[102:105]
	v_mfma_f32_16x16x32_bf16 v[98:101], v[174:177], v[226:229], v[98:101]
	v_mfma_f32_16x16x32_bf16 v[86:89], v[166:169], v[234:237], v[86:89]
	v_mfma_f32_16x16x32_bf16 v[82:85], v[174:177], v[234:237], v[82:85]
	v_mfma_f32_16x16x32_bf16 v[110:113], v[178:181], v[206:209], v[110:113]
	v_mfma_f32_16x16x32_bf16 v[106:109], v[186:189], v[206:209], v[106:109]
	v_mfma_f32_16x16x32_bf16 v[94:97], v[178:181], v[214:217], v[94:97]
	v_mfma_f32_16x16x32_bf16 v[90:93], v[186:189], v[214:217], v[90:93]
	v_mfma_f32_16x16x32_bf16 v[78:81], v[178:181], v[222:225], v[78:81]
	v_mfma_f32_16x16x32_bf16 v[74:77], v[186:189], v[222:225], v[74:77]
	v_mfma_f32_16x16x32_bf16 v[70:73], v[178:181], v[230:233], v[70:73]
	v_mfma_f32_16x16x32_bf16 v[66:69], v[186:189], v[230:233], v[66:69]
	v_mfma_f32_16x16x32_bf16 v[110:113], v[182:185], v[210:213], v[110:113]
	v_mfma_f32_16x16x32_bf16 v[106:109], v[202:205], v[210:213], v[106:109]
	v_mfma_f32_16x16x32_bf16 v[94:97], v[182:185], v[218:221], v[94:97]
	v_mfma_f32_16x16x32_bf16 v[90:93], v[202:205], v[218:221], v[90:93]
	v_mfma_f32_16x16x32_bf16 v[78:81], v[182:185], v[226:229], v[78:81]
	v_mfma_f32_16x16x32_bf16 v[74:77], v[202:205], v[226:229], v[74:77]
	v_mfma_f32_16x16x32_bf16 v[70:73], v[182:185], v[234:237], v[70:73]
	v_mfma_f32_16x16x32_bf16 v[66:69], v[202:205], v[234:237], v[66:69]
	s_setprio 0
	s_barrier
	s_add_i32 s4, s1, s19
	v_lshl_add_u64 v[238:239], s[12:13], 0, v[152:153]
	s_mov_b32 m0, s4
	ds_read_b128 v[206:209], v160 offset:16384
	ds_read_b128 v[210:213], v160 offset:17408
	ds_read_b128 v[214:217], v160 offset:18432
	ds_read_b128 v[218:221], v160 offset:19456
	ds_read_b128 v[222:225], v160 offset:20480
	ds_read_b128 v[226:229], v160 offset:21504
	ds_read_b128 v[230:233], v160 offset:22528
	ds_read_b128 v[234:237], v160 offset:23552
	global_load_lds_dwordx4 v[238:239], off
	s_add_i32 m0, s4, 0x2000
	s_add_u32 s4, s12, 0x58000
	v_lshl_add_u64 v[240:241], s[12:13], 0, v[150:151]
	s_addc_u32 s5, s13, 0
	s_add_i32 s38, s26, s19
	global_load_lds_dwordx4 v[240:241], off
	v_lshl_add_u64 v[242:243], s[4:5], 0, v[152:153]
	s_mov_b32 m0, s38
	v_lshl_add_u64 v[244:245], s[14:15], 0, v[150:151]
	global_load_lds_dwordx4 v[242:243], off
	v_lshl_add_u64 v[242:243], s[4:5], 0, v[150:151]
	s_add_i32 m0, s38, 0x2000
	s_nop 0
	global_load_lds_dwordx4 v[242:243], off
	v_lshl_add_u64 v[242:243], s[14:15], 0, v[152:153]
	s_mov_b32 m0, s20
	s_nop 0
	global_load_lds_dwordx4 v[242:243], off
	s_mov_b32 m0, s21
	s_nop 0
	global_load_lds_dwordx4 v[244:245], off
	s_waitcnt vmcnt(8)
	s_waitcnt lgkmcnt(0)
	s_barrier
; #define PG8_STAGE(bufoff, gbase, voff) do { _Pragma("unroll") for (int _i = 0; _i < 2; ++_i) \
;         __builtin_amdgcn_global_load_lds((const unsigned*)((const char*)(gbase) + (voff)[_i]), (PG8_LAS unsigned*)(lds + (bufoff) + ldsw + _i * 8192), 16, 0, 0); } while (0)
; #define PG8_LDA(dst, b, h) do { _Pragma("unroll") for (int m = 0; m < 4; ++m) _Pragma("unroll") for (int k = 0; k < 2; ++k) dst[m][k] = *(const PG8_LAS bf16x8*)(lds + PG8_SA(b, h) + aoff + m * 2048 + k * 1024); } while (0)
; #define PG8_LDB(dst, b, h) do { _Pragma("unroll") for (int n = 0; n < 2; ++n) _Pragma("unroll") for (int k = 0; k < 2; ++k) dst[n][k] = *(const PG8_LAS bf16x8*)(lds + PG8_SB(b, h) + boff + n * 2048 + k * 1024); } while (0)
; #define PG8_MMA(ai, bj, At, Bt) do { __builtin_amdgcn_s_setprio(1); _Pragma("unroll") for (int m = 0; m < 4; ++m) _Pragma("unroll") for (int n = 0; n < 2; ++n) _Pragma("unroll") for (int k = 0; k < 2; ++k) \
;         acc[ai][bj][m][n] = __builtin_amdgcn_mfma_f32_16x16x32_bf16(Bt[n][k], At[m][k], acc[ai][bj][m][n], 0, 0, 0); __builtin_amdgcn_s_setprio(0); } while (0)
; #define PG8_WAIT_V(n) asm volatile("s_waitcnt vmcnt(" #n ")" ::: "memory")
; #define PG8_WAIT_L(n) asm volatile("s_waitcnt lgkmcnt(" #n ")" ::: "memory")
; #define PG8_BAR __builtin_amdgcn_s_barrier()
; #define PG8_SCHED __builtin_amdgcn_sched_barrier(0)
; template <class Epi, class Sched, bool ALIGN_EPI = false, bool SP2 = false>
; __device__ __forceinline__ void gemm_phase(PG8_LAS unsigned char* lds, const Gemm g, const Sched& S, const Epi& E) {
;     ...
;             PG8_WAIT_V(8); PG8_WAIT_L(0); PG8_BAR; PG8_MMA(1, 0, At, B0); PG8_MMA(1, 1, At, B1); PG8_BAR; PG8_SCHED;
;             PG8_LDB(B0, 1, 0); PG8_LDB(B1, 1, 1); PG8_SCHED; PG8_LDA(At, 1, 0); PG8_STAGE(PG8_SA(0, 1), a2 + hstep, voffA);
;             PG8_WAIT_V(8); PG8_WAIT_L(0); PG8_BAR; PG8_MMA(0, 0, At, B0); PG8_MMA(0, 1, At, B1); PG8_BAR; PG8_SCHED;
	s_setprio 1
	v_mfma_f32_16x16x32_bf16 v[62:65], v[162:165], v[206:209], v[62:65]
	v_mfma_f32_16x16x32_bf16 v[58:61], v[170:173], v[206:209], v[58:61]
	v_mfma_f32_16x16x32_bf16 v[54:57], v[162:165], v[214:217], v[54:57]
	v_mfma_f32_16x16x32_bf16 v[50:53], v[170:173], v[214:217], v[50:53]
	v_mfma_f32_16x16x32_bf16 v[38:41], v[162:165], v[222:225], v[38:41]
	v_mfma_f32_16x16x32_bf16 v[34:37], v[170:173], v[222:225], v[34:37]
	v_mfma_f32_16x16x32_bf16 v[22:25], v[162:165], v[230:233], v[22:25]
	v_mfma_f32_16x16x32_bf16 v[18:21], v[170:173], v[230:233], v[18:21]
	v_mfma_f32_16x16x32_bf16 v[62:65], v[166:169], v[210:213], v[62:65]
	v_mfma_f32_16x16x32_bf16 v[58:61], v[174:177], v[210:213], v[58:61]
	v_mfma_f32_16x16x32_bf16 v[54:57], v[166:169], v[218:221], v[54:57]
	v_mfma_f32_16x16x32_bf16 v[50:53], v[174:177], v[218:221], v[50:53]
	v_mfma_f32_16x16x32_bf16 v[38:41], v[166:169], v[226:229], v[38:41]
	v_mfma_f32_16x16x32_bf16 v[34:37], v[174:177], v[226:229], v[34:37]
	v_mfma_f32_16x16x32_bf16 v[22:25], v[166:169], v[234:237], v[22:25]
	v_mfma_f32_16x16x32_bf16 v[18:21], v[174:177], v[234:237], v[18:21]
	v_mfma_f32_16x16x32_bf16 v[46:49], v[178:181], v[206:209], v[46:49]
	v_mfma_f32_16x16x32_bf16 v[42:45], v[186:189], v[206:209], v[42:45]
	v_mfma_f32_16x16x32_bf16 v[30:33], v[178:181], v[214:217], v[30:33]
	v_mfma_f32_16x16x32_bf16 v[26:29], v[186:189], v[214:217], v[26:29]
	v_mfma_f32_16x16x32_bf16 v[14:17], v[178:181], v[222:225], v[14:17]
	v_mfma_f32_16x16x32_bf16 v[10:13], v[186:189], v[222:225], v[10:13]
	v_mfma_f32_16x16x32_bf16 v[6:9], v[178:181], v[230:233], v[6:9]
	v_mfma_f32_16x16x32_bf16 v[2:5], v[186:189], v[230:233], v[2:5]
	v_mfma_f32_16x16x32_bf16 v[46:49], v[182:185], v[210:213], v[46:49]
	v_mfma_f32_16x16x32_bf16 v[42:45], v[202:205], v[210:213], v[42:45]
	v_mfma_f32_16x16x32_bf16 v[30:33], v[182:185], v[218:221], v[30:33]
	v_mfma_f32_16x16x32_bf16 v[26:29], v[202:205], v[218:221], v[26:29]
	v_mfma_f32_16x16x32_bf16 v[14:17], v[182:185], v[226:229], v[14:17]
	v_mfma_f32_16x16x32_bf16 v[10:13], v[202:205], v[226:229], v[10:13]
	v_mfma_f32_16x16x32_bf16 v[6:9], v[182:185], v[234:237], v[6:9]
	v_mfma_f32_16x16x32_bf16 v[2:5], v[202:205], v[234:237], v[2:5]
	s_setprio 0
	s_barrier
	v_add_u32_e32 v161, s27, v159
	ds_read_b128 v[162:165], v161
	ds_read_b128 v[166:169], v161 offset:1024
	ds_read_b128 v[170:173], v161 offset:2048
	ds_read_b128 v[174:177], v161 offset:3072
	v_add_u32_e32 v161, s28, v159
	ds_read_b128 v[178:181], v161
	ds_read_b128 v[182:185], v161 offset:1024
	ds_read_b128 v[186:189], v161 offset:2048
	ds_read_b128 v[202:205], v161 offset:3072
	s_add_u32 s4, s14, 0x58000
	s_addc_u32 s5, s15, 0
	s_mov_b32 m0, s22
	v_lshl_add_u64 v[246:247], s[4:5], 0, v[152:153]
	ds_read_b128 v[206:209], v160 offset:32768
	ds_read_b128 v[210:213], v160 offset:33792
	ds_read_b128 v[214:217], v160 offset:34816
	ds_read_b128 v[218:221], v160 offset:35840
	ds_read_b128 v[222:225], v160 offset:36864
	ds_read_b128 v[226:229], v160 offset:37888
	ds_read_b128 v[230:233], v160 offset:38912
	ds_read_b128 v[234:237], v160 offset:39936
	global_load_lds_dwordx4 v[246:247], off
	v_lshl_add_u64 v[246:247], s[4:5], 0, v[150:151]
	s_mov_b32 m0, s23
	s_nop 0
	global_load_lds_dwordx4 v[246:247], off
	s_waitcnt vmcnt(8)
	s_waitcnt lgkmcnt(0)
	s_barrier
	s_setprio 1
	v_mfma_f32_16x16x32_bf16 v[126:129], v[162:165], v[206:209], v[126:129]
	v_mfma_f32_16x16x32_bf16 v[122:125], v[170:173], v[206:209], v[122:125]
	v_mfma_f32_16x16x32_bf16 v[118:121], v[162:165], v[214:217], v[118:121]
	v_mfma_f32_16x16x32_bf16 v[114:117], v[170:173], v[214:217], v[114:117]
	v_mfma_f32_16x16x32_bf16 v[102:105], v[162:165], v[222:225], v[102:105]
	v_mfma_f32_16x16x32_bf16 v[98:101], v[170:173], v[222:225], v[98:101]
	v_mfma_f32_16x16x32_bf16 v[86:89], v[162:165], v[230:233], v[86:89]
	v_mfma_f32_16x16x32_bf16 v[82:85], v[170:173], v[230:233], v[82:85]
	v_mfma_f32_16x16x32_bf16 v[126:129], v[166:169], v[210:213], v[126:129]
	v_mfma_f32_16x16x32_bf16 v[122:125], v[174:177], v[210:213], v[122:125]
	v_mfma_f32_16x16x32_bf16 v[118:121], v[166:169], v[218:221], v[118:121]
	v_mfma_f32_16x16x32_bf16 v[114:117], v[174:177], v[218:221], v[114:117]
	v_mfma_f32_16x16x32_bf16 v[102:105], v[166:169], v[226:229], v[102:105]
	v_mfma_f32_16x16x32_bf16 v[98:101], v[174:177], v[226:229], v[98:101]
	v_mfma_f32_16x16x32_bf16 v[86:89], v[166:169], v[234:237], v[86:89]
	v_mfma_f32_16x16x32_bf16 v[82:85], v[174:177], v[234:237], v[82:85]
	v_mfma_f32_16x16x32_bf16 v[110:113], v[178:181], v[206:209], v[110:113]
	v_mfma_f32_16x16x32_bf16 v[106:109], v[186:189], v[206:209], v[106:109]
	v_mfma_f32_16x16x32_bf16 v[94:97], v[178:181], v[214:217], v[94:97]
	v_mfma_f32_16x16x32_bf16 v[90:93], v[186:189], v[214:217], v[90:93]
	v_mfma_f32_16x16x32_bf16 v[78:81], v[178:181], v[222:225], v[78:81]
	v_mfma_f32_16x16x32_bf16 v[74:77], v[186:189], v[222:225], v[74:77]
	v_mfma_f32_16x16x32_bf16 v[70:73], v[178:181], v[230:233], v[70:73]
	v_mfma_f32_16x16x32_bf16 v[66:69], v[186:189], v[230:233], v[66:69]
	v_mfma_f32_16x16x32_bf16 v[110:113], v[182:185], v[210:213], v[110:113]
	v_mfma_f32_16x16x32_bf16 v[106:109], v[202:205], v[210:213], v[106:109]
	v_mfma_f32_16x16x32_bf16 v[94:97], v[182:185], v[218:221], v[94:97]
	v_mfma_f32_16x16x32_bf16 v[90:93], v[202:205], v[218:221], v[90:93]
	v_mfma_f32_16x16x32_bf16 v[78:81], v[182:185], v[226:229], v[78:81]
	v_mfma_f32_16x16x32_bf16 v[74:77], v[202:205], v[226:229], v[74:77]
	v_mfma_f32_16x16x32_bf16 v[70:73], v[182:185], v[234:237], v[70:73]
	v_mfma_f32_16x16x32_bf16 v[66:69], v[202:205], v[234:237], v[66:69]
	s_setprio 0
	s_barrier
; #define PG8_STAGE(bufoff, gbase, voff) do { _Pragma("unroll") for (int _i = 0; _i < 2; ++_i) \
;         __builtin_amdgcn_global_load_lds((const unsigned*)((const char*)(gbase) + (voff)[_i]), (PG8_LAS unsigned*)(lds + (bufoff) + ldsw + _i * 8192), 16, 0, 0); } while (0)
; #define PG8_LDA(dst, b, h) do { _Pragma("unroll") for (int m = 0; m < 4; ++m) _Pragma("unroll") for (int k = 0; k < 2; ++k) dst[m][k] = *(const PG8_LAS bf16x8*)(lds + PG8_SA(b, h) + aoff + m * 2048 + k * 1024); } while (0)
; #define PG8_WAIT_V(n) asm volatile("s_waitcnt vmcnt(" #n ")" ::: "memory")
; template <class Epi, class Sched, bool ALIGN_EPI = false, bool SP2 = false>
; __device__ __forceinline__ void gemm_phase(PG8_LAS unsigned char* lds, const Gemm g, const Sched& S, const Epi& E) {
;     ...
;             PG8_LDA(At, 1, 1); PG8_STAGE(PG8_SB(1, 0), b3, voffB); PG8_STAGE(PG8_SB(1, 1), b3 + hstep, voffB); PG8_STAGE(PG8_SA(1, 0), a3, voffA);
;             PG8_WAIT_V(8); PG8_WAIT_L(0); PG8_BAR; PG8_MMA(1, 0, At, B0); PG8_MMA(1, 1, At, B1); PG8_BAR; PG8_SCHED;
;             } else {
;             PG8_LDB(B0, 0, 0); PG8_SCHED; PG8_LDA(At, 0, 0); PG8_STAGE(PG8_SA(1, 1), a1 + hstep, voffA);
;             PG8_WAIT_L(8); PG8_BAR; PG8_WAIT_L(0); PG8_MMA(0, 0, At, B0); PG8_BAR; PG8_SCHED;
;             PG8_LDB(B1, 0, 1); PG8_STAGE(PG8_SB(0, 0), b2, voffB);
;             PG8_BAR; PG8_WAIT_L(0); PG8_MMA(0, 1, At, B1); PG8_BAR;
;             PG8_LDA(At, 0, 1); PG8_STAGE(PG8_SA(0, 0), a2, voffA);
;             PG8_BAR; PG8_WAIT_L(0); PG8_MMA(1, 0, At, B0); PG8_BAR; PG8_SCHED;
;             PG8_STAGE(PG8_SB(0, 1), b2 + hstep, voffB);
;             PG8_WAIT_V(6); PG8_BAR; PG8_MMA(1, 1, At, B1); PG8_BAR;
;             PG8_LDB(B0, 1, 0); PG8_SCHED; PG8_LDA(At, 1, 0); PG8_STAGE(PG8_SA(0, 1), a2 + hstep, voffA);
;             PG8_WAIT_L(8); PG8_BAR; PG8_WAIT_L(0); PG8_MMA(0, 0, At, B0); PG8_BAR; PG8_SCHED;
;             PG8_LDB(B1, 1, 1); PG8_STAGE(PG8_SB(1, 0), b3, voffB);
;             PG8_BAR; PG8_WAIT_L(0); PG8_MMA(0, 1, At, B1); PG8_BAR;
;             PG8_LDA(At, 1, 1); PG8_STAGE(PG8_SA(1, 0), a3, voffA);
;             PG8_BAR; PG8_WAIT_L(0); PG8_MMA(1, 0, At, B0); PG8_BAR; PG8_SCHED;
;             PG8_STAGE(PG8_SB(1, 1), b3 + hstep, voffB);
;             PG8_WAIT_V(6); PG8_BAR; PG8_MMA(1, 1, At, B1); PG8_BAR;
;             }
;         }
;         if constexpr (ALIGN_EPI) { if (wr == 0) PG8_BAR; }
	s_add_i32 s4, s27, s19
	v_lshl_add_u64 v[238:239], v[238:239], 0, s[62:63]
	s_mov_b32 m0, s4
	ds_read_b128 v[206:209], v160 offset:49152
	ds_read_b128 v[210:213], v160 offset:50176
	ds_read_b128 v[214:217], v160 offset:51200
	ds_read_b128 v[218:221], v160 offset:52224
	ds_read_b128 v[222:225], v160 offset:53248
	ds_read_b128 v[226:229], v160 offset:54272
	ds_read_b128 v[230:233], v160 offset:55296
	ds_read_b128 v[234:237], v160 offset:56320
	global_load_lds_dwordx4 v[238:239], off
	s_add_i32 m0, s4, 0x2000
	s_add_u32 s4, s12, 0x58080
	v_lshl_add_u64 v[238:239], v[240:241], 0, s[62:63]
	s_addc_u32 s5, s13, 0
	s_add_i32 s12, s28, s19
	global_load_lds_dwordx4 v[238:239], off
	v_lshl_add_u64 v[238:239], s[4:5], 0, v[152:153]
	s_mov_b32 m0, s12
	s_nop 0
	global_load_lds_dwordx4 v[238:239], off
	v_lshl_add_u64 v[238:239], s[4:5], 0, v[150:151]
	s_add_i32 m0, s12, 0x2000
	s_nop 0
	global_load_lds_dwordx4 v[238:239], off
	v_lshl_add_u64 v[238:239], v[242:243], 0, s[62:63]
	s_mov_b32 m0, s29
	s_nop 0
	global_load_lds_dwordx4 v[238:239], off
	v_lshl_add_u64 v[238:239], v[244:245], 0, s[62:63]
	s_mov_b32 m0, s30
	s_nop 0
	global_load_lds_dwordx4 v[238:239], off
	s_waitcnt vmcnt(8)
	s_waitcnt lgkmcnt(0)
	s_barrier
	s_setprio 1
	v_mfma_f32_16x16x32_bf16 v[62:65], v[162:165], v[206:209], v[62:65]
	v_mfma_f32_16x16x32_bf16 v[58:61], v[170:173], v[206:209], v[58:61]
	v_mfma_f32_16x16x32_bf16 v[54:57], v[162:165], v[214:217], v[54:57]
	v_mfma_f32_16x16x32_bf16 v[50:53], v[170:173], v[214:217], v[50:53]
	v_mfma_f32_16x16x32_bf16 v[38:41], v[162:165], v[222:225], v[38:41]
	v_mfma_f32_16x16x32_bf16 v[34:37], v[170:173], v[222:225], v[34:37]
	v_mfma_f32_16x16x32_bf16 v[22:25], v[162:165], v[230:233], v[22:25]
	v_mfma_f32_16x16x32_bf16 v[18:21], v[170:173], v[230:233], v[18:21]
	v_mfma_f32_16x16x32_bf16 v[62:65], v[166:169], v[210:213], v[62:65]
	v_mfma_f32_16x16x32_bf16 v[58:61], v[174:177], v[210:213], v[58:61]
	v_mfma_f32_16x16x32_bf16 v[54:57], v[166:169], v[218:221], v[54:57]
	v_mfma_f32_16x16x32_bf16 v[50:53], v[174:177], v[218:221], v[50:53]
	v_mfma_f32_16x16x32_bf16 v[38:41], v[166:169], v[226:229], v[38:41]
	v_mfma_f32_16x16x32_bf16 v[34:37], v[174:177], v[226:229], v[34:37]
	v_mfma_f32_16x16x32_bf16 v[22:25], v[166:169], v[234:237], v[22:25]
	v_mfma_f32_16x16x32_bf16 v[18:21], v[174:177], v[234:237], v[18:21]
	v_mfma_f32_16x16x32_bf16 v[46:49], v[178:181], v[206:209], v[46:49]
	v_mfma_f32_16x16x32_bf16 v[42:45], v[186:189], v[206:209], v[42:45]
	v_mfma_f32_16x16x32_bf16 v[30:33], v[178:181], v[214:217], v[30:33]
	v_mfma_f32_16x16x32_bf16 v[26:29], v[186:189], v[214:217], v[26:29]
	v_mfma_f32_16x16x32_bf16 v[14:17], v[178:181], v[222:225], v[14:17]
	v_mfma_f32_16x16x32_bf16 v[10:13], v[186:189], v[222:225], v[10:13]
	v_mfma_f32_16x16x32_bf16 v[6:9], v[178:181], v[230:233], v[6:9]
	v_mfma_f32_16x16x32_bf16 v[2:5], v[186:189], v[230:233], v[2:5]
	v_mfma_f32_16x16x32_bf16 v[46:49], v[182:185], v[210:213], v[46:49]
	v_mfma_f32_16x16x32_bf16 v[42:45], v[202:205], v[210:213], v[42:45]
	v_mfma_f32_16x16x32_bf16 v[30:33], v[182:185], v[218:221], v[30:33]
	v_mfma_f32_16x16x32_bf16 v[26:29], v[202:205], v[218:221], v[26:29]
	v_mfma_f32_16x16x32_bf16 v[14:17], v[182:185], v[226:229], v[14:17]
	v_mfma_f32_16x16x32_bf16 v[10:13], v[202:205], v[226:229], v[10:13]
	v_mfma_f32_16x16x32_bf16 v[6:9], v[182:185], v[234:237], v[6:9]
	v_mfma_f32_16x16x32_bf16 v[2:5], v[202:205], v[234:237], v[2:5]
	s_setprio 0
	s_barrier
	s_add_i32 s37, s37, 2
	s_add_u32 s10, s10, 0x100
	s_addc_u32 s11, s11, 0
	s_cmp_gt_u32 s37, 19
	s_cbranch_scc0 .LBB0_1415
	s_cmpk_lt_u32 s18, 0x100
	s_cbranch_scc0 .LBB0_1418
	s_barrier

; #define PG8_STAGE(bufoff, gbase, voff) do { _Pragma("unroll") for (int _i = 0; _i < 2; ++_i) \
;         __builtin_amdgcn_global_load_lds((const unsigned*)((const char*)(gbase) + (voff)[_i]), (PG8_LAS unsigned*)(lds + (bufoff) + ldsw + _i * 8192), 16, 0, 0); } while (0)
; #define PG8_LDA(dst, b, h) do { _Pragma("unroll") for (int m = 0; m < 4; ++m) _Pragma("unroll") for (int k = 0; k < 2; ++k) dst[m][k] = *(const PG8_LAS bf16x8*)(lds + PG8_SA(b, h) + aoff + m * 2048 + k * 1024); } while (0)
; #define PG8_LDB(dst, b, h) do { _Pragma("unroll") for (int n = 0; n < 2; ++n) _Pragma("unroll") for (int k = 0; k < 2; ++k) dst[n][k] = *(const PG8_LAS bf16x8*)(lds + PG8_SB(b, h) + boff + n * 2048 + k * 1024); } while (0)
; #define PG8_MMA(ai, bj, At, Bt) do { __builtin_amdgcn_s_setprio(1); _Pragma("unroll") for (int m = 0; m < 4; ++m) _Pragma("unroll") for (int n = 0; n < 2; ++n) _Pragma("unroll") for (int k = 0; k < 2; ++k) \
;         acc[ai][bj][m][n] = __builtin_amdgcn_mfma_f32_16x16x32_bf16(Bt[n][k], At[m][k], acc[ai][bj][m][n], 0, 0, 0); __builtin_amdgcn_s_setprio(0); } while (0)
; #define PG8_WAIT_V(n) asm volatile("s_waitcnt vmcnt(" #n ")" ::: "memory")
; #define PG8_WAIT_L(n) asm volatile("s_waitcnt lgkmcnt(" #n ")" ::: "memory")
; template <class Epi, class Sched, bool ALIGN_EPI = false, bool SP2 = false>
; __device__ __forceinline__ void gemm_phase(PG8_LAS unsigned char* lds, const Gemm g, const Sched& S, const Epi& E) {
;     ...
;             const bool last = (t == nt - 2);
;             const char* a1 = cA + (size_t)(t + 1) * kstep;
;             const char* a2 = last ? nA : cA + (size_t)(t + 2) * kstep; const char* b2 = last ? nB : cB + (size_t)(t + 2) * kstep;
;             const char* a3 = a2 + kstep; const char* b3 = b2 + kstep;
;             if (last && has_next) S.a_ready(nxt);
;             if constexpr (SP2) {
;             PG8_LDB(B0, 0, 0); PG8_LDB(B1, 0, 1); PG8_SCHED; PG8_LDA(At, 0, 0); PG8_STAGE(PG8_SA(1, 1), a1 + hstep, voffA);
;             PG8_WAIT_V(8); PG8_WAIT_L(0); PG8_BAR; PG8_MMA(0, 0, At, B0); PG8_MMA(0, 1, At, B1); PG8_BAR; PG8_SCHED;
;             PG8_LDA(At, 0, 1); PG8_STAGE(PG8_SB(0, 0), b2, voffB); PG8_STAGE(PG8_SB(0, 1), b2 + hstep, voffB); PG8_STAGE(PG8_SA(0, 0), a2, voffA);
;             PG8_WAIT_V(8); PG8_WAIT_L(0); PG8_BAR; PG8_MMA(1, 0, At, B0); PG8_MMA(1, 1, At, B1); PG8_BAR; PG8_SCHED;
.LBB0_1680:
	s_add_u32 s30, s28, 0x100
	s_addc_u32 s31, s29, 0
	s_add_i32 s4, 0, 0x10000
	s_cmp_eq_u32 s64, 12
	s_cselect_b32 s37, s23, s31
	s_cselect_b32 s36, s52, s30
	v_add_u32_e32 v165, s4, v162
	s_cselect_b32 s35, s21, s55
	s_cselect_b32 s34, s53, s54
	s_add_i32 s65, 0, 0x14000
	ds_read_b128 v[158:161], v165
	ds_read_b128 v[166:169], v165 offset:1024
	ds_read_b128 v[170:173], v165 offset:2048
	ds_read_b128 v[174:177], v165 offset:3072
	v_add_u32_e32 v165, s65, v162
	ds_read_b128 v[178:181], v165
	ds_read_b128 v[182:185], v165 offset:1024
	ds_read_b128 v[186:189], v165 offset:2048
	ds_read_b128 v[202:205], v165 offset:3072
	v_lshl_add_u64 v[238:239], s[28:29], 0, v[154:155]
	s_add_i32 m0, s41, 0xc000
	ds_read_b128 v[206:209], v164
	ds_read_b128 v[210:213], v164 offset:1024
	ds_read_b128 v[214:217], v164 offset:2048
	ds_read_b128 v[218:221], v164 offset:3072
	ds_read_b128 v[222:225], v164 offset:4096
	ds_read_b128 v[226:229], v164 offset:5120
	ds_read_b128 v[230:233], v164 offset:6144
	ds_read_b128 v[234:237], v164 offset:7168
	global_load_lds_dwordx4 v[238:239], off
	v_lshl_add_u64 v[238:239], s[28:29], 0, v[156:157]
	s_add_i32 m0, s41, 0xe000
	s_nop 0
	global_load_lds_dwordx4 v[238:239], off
	s_bfe_u32 s100, s64, 0x30001
	s_lshl_b32 s100, s100, 16
	v_add_u32_e32 v250, s100, v249
	global_load_dword v248, v250, s[14:15]
	s_waitcnt vmcnt(9)
	s_waitcnt lgkmcnt(0)
	s_barrier
	s_setprio 1
	v_mfma_f32_16x16x32_bf16 v[126:129], v[158:161], v[206:209], v[126:129]
	v_mfma_f32_16x16x32_bf16 v[122:125], v[170:173], v[206:209], v[122:125]
	v_mfma_f32_16x16x32_bf16 v[110:113], v[158:161], v[214:217], v[110:113]
	v_mfma_f32_16x16x32_bf16 v[106:109], v[170:173], v[214:217], v[106:109]
	v_mfma_f32_16x16x32_bf16 v[94:97], v[158:161], v[222:225], v[94:97]
	v_mfma_f32_16x16x32_bf16 v[90:93], v[170:173], v[222:225], v[90:93]
	v_mfma_f32_16x16x32_bf16 v[78:81], v[158:161], v[230:233], v[78:81]
	v_mfma_f32_16x16x32_bf16 v[74:77], v[170:173], v[230:233], v[74:77]
	v_mfma_f32_16x16x32_bf16 v[126:129], v[166:169], v[210:213], v[126:129]
	v_mfma_f32_16x16x32_bf16 v[122:125], v[174:177], v[210:213], v[122:125]
	v_mfma_f32_16x16x32_bf16 v[110:113], v[166:169], v[218:221], v[110:113]
	v_mfma_f32_16x16x32_bf16 v[106:109], v[174:177], v[218:221], v[106:109]
	v_mfma_f32_16x16x32_bf16 v[94:97], v[166:169], v[226:229], v[94:97]
	v_mfma_f32_16x16x32_bf16 v[90:93], v[174:177], v[226:229], v[90:93]
	v_mfma_f32_16x16x32_bf16 v[78:81], v[166:169], v[234:237], v[78:81]
	v_mfma_f32_16x16x32_bf16 v[74:77], v[174:177], v[234:237], v[74:77]
	v_mfma_f32_16x16x32_bf16 v[118:121], v[178:181], v[206:209], v[118:121]
	v_mfma_f32_16x16x32_bf16 v[114:117], v[186:189], v[206:209], v[114:117]
	v_mfma_f32_16x16x32_bf16 v[102:105], v[178:181], v[214:217], v[102:105]
	v_mfma_f32_16x16x32_bf16 v[98:101], v[186:189], v[214:217], v[98:101]
	v_mfma_f32_16x16x32_bf16 v[86:89], v[178:181], v[222:225], v[86:89]
	v_mfma_f32_16x16x32_bf16 v[82:85], v[186:189], v[222:225], v[82:85]
	v_mfma_f32_16x16x32_bf16 v[70:73], v[178:181], v[230:233], v[70:73]
	v_mfma_f32_16x16x32_bf16 v[66:69], v[186:189], v[230:233], v[66:69]
	v_mfma_f32_16x16x32_bf16 v[118:121], v[182:185], v[210:213], v[118:121]
	v_mfma_f32_16x16x32_bf16 v[114:117], v[202:205], v[210:213], v[114:117]
	v_mfma_f32_16x16x32_bf16 v[102:105], v[182:185], v[218:221], v[102:105]
	v_mfma_f32_16x16x32_bf16 v[98:101], v[202:205], v[218:221], v[98:101]
	v_mfma_f32_16x16x32_bf16 v[86:89], v[182:185], v[226:229], v[86:89]
	v_mfma_f32_16x16x32_bf16 v[82:85], v[202:205], v[226:229], v[82:85]
	v_mfma_f32_16x16x32_bf16 v[70:73], v[182:185], v[234:237], v[70:73]
	v_mfma_f32_16x16x32_bf16 v[66:69], v[202:205], v[234:237], v[66:69]
	s_setprio 0
	s_barrier
	s_add_i32 s4, s4, s40
	v_lshl_add_u64 v[238:239], s[34:35], 0, v[152:153]
	s_mov_b32 m0, s4
	ds_read_b128 v[206:209], v164 offset:16384
	ds_read_b128 v[210:213], v164 offset:17408
	ds_read_b128 v[214:217], v164 offset:18432
	ds_read_b128 v[218:221], v164 offset:19456
	ds_read_b128 v[222:225], v164 offset:20480
	ds_read_b128 v[226:229], v164 offset:21504
	ds_read_b128 v[230:233], v164 offset:22528
	ds_read_b128 v[234:237], v164 offset:23552
	global_load_lds_dwordx4 v[238:239], off
	s_add_i32 m0, s4, 0x2000
	s_add_u32 s4, s34, 0x40000
	v_lshl_add_u64 v[240:241], s[34:35], 0, v[150:151]
	s_addc_u32 s5, s35, 0
	s_add_i32 s28, s65, s40
	global_load_lds_dwordx4 v[240:241], off
	v_lshl_add_u64 v[242:243], s[4:5], 0, v[152:153]
	s_mov_b32 m0, s28
	v_lshl_add_u64 v[244:245], s[36:37], 0, v[150:151]
	global_load_lds_dwordx4 v[242:243], off
	v_lshl_add_u64 v[242:243], s[4:5], 0, v[150:151]
	s_add_i32 m0, s28, 0x2000
	s_nop 0
	global_load_lds_dwordx4 v[242:243], off
	v_lshl_add_u64 v[242:243], s[36:37], 0, v[152:153]
	s_mov_b32 m0, s41
	s_nop 0
	global_load_lds_dwordx4 v[242:243], off
	s_mov_b32 m0, s42
	s_nop 0
	global_load_lds_dwordx4 v[244:245], off
	s_waitcnt vmcnt(9)
	s_waitcnt lgkmcnt(0)
	s_barrier
; #define PG8_STAGE(bufoff, gbase, voff) do { _Pragma("unroll") for (int _i = 0; _i < 2; ++_i) \
;         __builtin_amdgcn_global_load_lds((const unsigned*)((const char*)(gbase) + (voff)[_i]), (PG8_LAS unsigned*)(lds + (bufoff) + ldsw + _i * 8192), 16, 0, 0); } while (0)
; #define PG8_LDA(dst, b, h) do { _Pragma("unroll") for (int m = 0; m < 4; ++m) _Pragma("unroll") for (int k = 0; k < 2; ++k) dst[m][k] = *(const PG8_LAS bf16x8*)(lds + PG8_SA(b, h) + aoff + m * 2048 + k * 1024); } while (0)
; #define PG8_LDB(dst, b, h) do { _Pragma("unroll") for (int n = 0; n < 2; ++n) _Pragma("unroll") for (int k = 0; k < 2; ++k) dst[n][k] = *(const PG8_LAS bf16x8*)(lds + PG8_SB(b, h) + boff + n * 2048 + k * 1024); } while (0)
; #define PG8_MMA(ai, bj, At, Bt) do { __builtin_amdgcn_s_setprio(1); _Pragma("unroll") for (int m = 0; m < 4; ++m) _Pragma("unroll") for (int n = 0; n < 2; ++n) _Pragma("unroll") for (int k = 0; k < 2; ++k) \
;         acc[ai][bj][m][n] = __builtin_amdgcn_mfma_f32_16x16x32_bf16(Bt[n][k], At[m][k], acc[ai][bj][m][n], 0, 0, 0); __builtin_amdgcn_s_setprio(0); } while (0)
; #define PG8_WAIT_V(n) asm volatile("s_waitcnt vmcnt(" #n ")" ::: "memory")
; #define PG8_WAIT_L(n) asm volatile("s_waitcnt lgkmcnt(" #n ")" ::: "memory")
; #define PG8_BAR __builtin_amdgcn_s_barrier()
; #define PG8_SCHED __builtin_amdgcn_sched_barrier(0)
; template <class Epi, class Sched, bool ALIGN_EPI = false, bool SP2 = false>
; __device__ __forceinline__ void gemm_phase(PG8_LAS unsigned char* lds, const Gemm g, const Sched& S, const Epi& E) {
;     ...
;             PG8_WAIT_V(8); PG8_WAIT_L(0); PG8_BAR; PG8_MMA(1, 0, At, B0); PG8_MMA(1, 1, At, B1); PG8_BAR; PG8_SCHED;
;             PG8_LDB(B0, 1, 0); PG8_LDB(B1, 1, 1); PG8_SCHED; PG8_LDA(At, 1, 0); PG8_STAGE(PG8_SA(0, 1), a2 + hstep, voffA);
;             PG8_WAIT_V(8); PG8_WAIT_L(0); PG8_BAR; PG8_MMA(0, 0, At, B0); PG8_MMA(0, 1, At, B1); PG8_BAR; PG8_SCHED;
	s_setprio 1
	v_mfma_f32_16x16x32_bf16 v[62:65], v[158:161], v[206:209], v[62:65]
	v_mfma_f32_16x16x32_bf16 v[58:61], v[170:173], v[206:209], v[58:61]
	v_mfma_f32_16x16x32_bf16 v[46:49], v[158:161], v[214:217], v[46:49]
	v_mfma_f32_16x16x32_bf16 v[42:45], v[170:173], v[214:217], v[42:45]
	v_mfma_f32_16x16x32_bf16 v[30:33], v[158:161], v[222:225], v[30:33]
	v_mfma_f32_16x16x32_bf16 v[26:29], v[170:173], v[222:225], v[26:29]
	v_mfma_f32_16x16x32_bf16 v[14:17], v[158:161], v[230:233], v[14:17]
	v_mfma_f32_16x16x32_bf16 v[10:13], v[170:173], v[230:233], v[10:13]
	v_mfma_f32_16x16x32_bf16 v[62:65], v[166:169], v[210:213], v[62:65]
	v_mfma_f32_16x16x32_bf16 v[58:61], v[174:177], v[210:213], v[58:61]
	v_mfma_f32_16x16x32_bf16 v[46:49], v[166:169], v[218:221], v[46:49]
	v_mfma_f32_16x16x32_bf16 v[42:45], v[174:177], v[218:221], v[42:45]
	v_mfma_f32_16x16x32_bf16 v[30:33], v[166:169], v[226:229], v[30:33]
	v_mfma_f32_16x16x32_bf16 v[26:29], v[174:177], v[226:229], v[26:29]
	v_mfma_f32_16x16x32_bf16 v[14:17], v[166:169], v[234:237], v[14:17]
	v_mfma_f32_16x16x32_bf16 v[10:13], v[174:177], v[234:237], v[10:13]
	v_mfma_f32_16x16x32_bf16 v[54:57], v[178:181], v[206:209], v[54:57]
	v_mfma_f32_16x16x32_bf16 v[50:53], v[186:189], v[206:209], v[50:53]
	v_mfma_f32_16x16x32_bf16 v[38:41], v[178:181], v[214:217], v[38:41]
	v_mfma_f32_16x16x32_bf16 v[34:37], v[186:189], v[214:217], v[34:37]
	v_mfma_f32_16x16x32_bf16 v[22:25], v[178:181], v[222:225], v[22:25]
	v_mfma_f32_16x16x32_bf16 v[18:21], v[186:189], v[222:225], v[18:21]
	v_mfma_f32_16x16x32_bf16 v[6:9], v[178:181], v[230:233], v[6:9]
	v_mfma_f32_16x16x32_bf16 v[2:5], v[186:189], v[230:233], v[2:5]
	v_mfma_f32_16x16x32_bf16 v[54:57], v[182:185], v[210:213], v[54:57]
	v_mfma_f32_16x16x32_bf16 v[50:53], v[202:205], v[210:213], v[50:53]
	v_mfma_f32_16x16x32_bf16 v[38:41], v[182:185], v[218:221], v[38:41]
	v_mfma_f32_16x16x32_bf16 v[34:37], v[202:205], v[218:221], v[34:37]
	v_mfma_f32_16x16x32_bf16 v[22:25], v[182:185], v[226:229], v[22:25]
	v_mfma_f32_16x16x32_bf16 v[18:21], v[202:205], v[226:229], v[18:21]
	v_mfma_f32_16x16x32_bf16 v[6:9], v[182:185], v[234:237], v[6:9]
	v_mfma_f32_16x16x32_bf16 v[2:5], v[202:205], v[234:237], v[2:5]
	s_setprio 0
	s_barrier
	s_add_i32 s28, 0, 0x18000
	v_add_u32_e32 v165, s28, v162
	s_add_i32 s29, 0, 0x1c000
	ds_read_b128 v[158:161], v165
	ds_read_b128 v[166:169], v165 offset:1024
	ds_read_b128 v[170:173], v165 offset:2048
	ds_read_b128 v[174:177], v165 offset:3072
	v_add_u32_e32 v165, s29, v162
	ds_read_b128 v[178:181], v165
	ds_read_b128 v[182:185], v165 offset:1024
	ds_read_b128 v[186:189], v165 offset:2048
	ds_read_b128 v[202:205], v165 offset:3072
	s_add_u32 s4, s36, 0x40000
	s_addc_u32 s5, s37, 0
	s_mov_b32 m0, s43
	v_lshl_add_u64 v[246:247], s[4:5], 0, v[152:153]
	ds_read_b128 v[206:209], v164 offset:32768
	ds_read_b128 v[210:213], v164 offset:33792
	ds_read_b128 v[214:217], v164 offset:34816
	ds_read_b128 v[218:221], v164 offset:35840
	ds_read_b128 v[222:225], v164 offset:36864
	ds_read_b128 v[226:229], v164 offset:37888
	ds_read_b128 v[230:233], v164 offset:38912
	ds_read_b128 v[234:237], v164 offset:39936
	global_load_lds_dwordx4 v[246:247], off
	v_lshl_add_u64 v[246:247], s[4:5], 0, v[150:151]
	s_mov_b32 m0, s44
	s_nop 0
	global_load_lds_dwordx4 v[246:247], off
	s_waitcnt vmcnt(9)
	s_waitcnt lgkmcnt(0)
	s_barrier
	s_setprio 1
	v_mfma_f32_16x16x32_bf16 v[126:129], v[158:161], v[206:209], v[126:129]
	v_mfma_f32_16x16x32_bf16 v[122:125], v[170:173], v[206:209], v[122:125]
	v_mfma_f32_16x16x32_bf16 v[110:113], v[158:161], v[214:217], v[110:113]
	v_mfma_f32_16x16x32_bf16 v[106:109], v[170:173], v[214:217], v[106:109]
	v_mfma_f32_16x16x32_bf16 v[94:97], v[158:161], v[222:225], v[94:97]
	v_mfma_f32_16x16x32_bf16 v[90:93], v[170:173], v[222:225], v[90:93]
	v_mfma_f32_16x16x32_bf16 v[78:81], v[158:161], v[230:233], v[78:81]
	v_mfma_f32_16x16x32_bf16 v[74:77], v[170:173], v[230:233], v[74:77]
	v_mfma_f32_16x16x32_bf16 v[126:129], v[166:169], v[210:213], v[126:129]
	v_mfma_f32_16x16x32_bf16 v[122:125], v[174:177], v[210:213], v[122:125]
	v_mfma_f32_16x16x32_bf16 v[110:113], v[166:169], v[218:221], v[110:113]
	v_mfma_f32_16x16x32_bf16 v[106:109], v[174:177], v[218:221], v[106:109]
	v_mfma_f32_16x16x32_bf16 v[94:97], v[166:169], v[226:229], v[94:97]
	v_mfma_f32_16x16x32_bf16 v[90:93], v[174:177], v[226:229], v[90:93]
	v_mfma_f32_16x16x32_bf16 v[78:81], v[166:169], v[234:237], v[78:81]
	v_mfma_f32_16x16x32_bf16 v[74:77], v[174:177], v[234:237], v[74:77]
	v_mfma_f32_16x16x32_bf16 v[118:121], v[178:181], v[206:209], v[118:121]
	v_mfma_f32_16x16x32_bf16 v[114:117], v[186:189], v[206:209], v[114:117]
	v_mfma_f32_16x16x32_bf16 v[102:105], v[178:181], v[214:217], v[102:105]
	v_mfma_f32_16x16x32_bf16 v[98:101], v[186:189], v[214:217], v[98:101]
	v_mfma_f32_16x16x32_bf16 v[86:89], v[178:181], v[222:225], v[86:89]
	v_mfma_f32_16x16x32_bf16 v[82:85], v[186:189], v[222:225], v[82:85]
	v_mfma_f32_16x16x32_bf16 v[70:73], v[178:181], v[230:233], v[70:73]
	v_mfma_f32_16x16x32_bf16 v[66:69], v[186:189], v[230:233], v[66:69]
	v_mfma_f32_16x16x32_bf16 v[118:121], v[182:185], v[210:213], v[118:121]
	v_mfma_f32_16x16x32_bf16 v[114:117], v[202:205], v[210:213], v[114:117]
	v_mfma_f32_16x16x32_bf16 v[102:105], v[182:185], v[218:221], v[102:105]
	v_mfma_f32_16x16x32_bf16 v[98:101], v[202:205], v[218:221], v[98:101]
	v_mfma_f32_16x16x32_bf16 v[86:89], v[182:185], v[226:229], v[86:89]
	v_mfma_f32_16x16x32_bf16 v[82:85], v[202:205], v[226:229], v[82:85]
	v_mfma_f32_16x16x32_bf16 v[70:73], v[182:185], v[234:237], v[70:73]
	v_mfma_f32_16x16x32_bf16 v[66:69], v[202:205], v[234:237], v[66:69]
	s_setprio 0
	s_barrier
; #define PG8_STAGE(bufoff, gbase, voff) do { _Pragma("unroll") for (int _i = 0; _i < 2; ++_i) \
;         __builtin_amdgcn_global_load_lds((const unsigned*)((const char*)(gbase) + (voff)[_i]), (PG8_LAS unsigned*)(lds + (bufoff) + ldsw + _i * 8192), 16, 0, 0); } while (0)
; #define PG8_LDA(dst, b, h) do { _Pragma("unroll") for (int m = 0; m < 4; ++m) _Pragma("unroll") for (int k = 0; k < 2; ++k) dst[m][k] = *(const PG8_LAS bf16x8*)(lds + PG8_SA(b, h) + aoff + m * 2048 + k * 1024); } while (0)
; #define PG8_WAIT_V(n) asm volatile("s_waitcnt vmcnt(" #n ")" ::: "memory")
; template <class Epi, class Sched, bool ALIGN_EPI = false, bool SP2 = false>
; __device__ __forceinline__ void gemm_phase(PG8_LAS unsigned char* lds, const Gemm g, const Sched& S, const Epi& E) {
;     ...
;             PG8_LDA(At, 1, 1); PG8_STAGE(PG8_SB(1, 0), b3, voffB); PG8_STAGE(PG8_SB(1, 1), b3 + hstep, voffB); PG8_STAGE(PG8_SA(1, 0), a3, voffA);
;             PG8_WAIT_V(8); PG8_WAIT_L(0); PG8_BAR; PG8_MMA(1, 0, At, B0); PG8_MMA(1, 1, At, B1); PG8_BAR; PG8_SCHED;
;             } else {
;             PG8_LDB(B0, 0, 0); PG8_SCHED; PG8_LDA(At, 0, 0); PG8_STAGE(PG8_SA(1, 1), a1 + hstep, voffA);
;             PG8_WAIT_L(8); PG8_BAR; PG8_WAIT_L(0); PG8_MMA(0, 0, At, B0); PG8_BAR; PG8_SCHED;
;             PG8_LDB(B1, 0, 1); PG8_STAGE(PG8_SB(0, 0), b2, voffB);
;             PG8_BAR; PG8_WAIT_L(0); PG8_MMA(0, 1, At, B1); PG8_BAR;
;             PG8_LDA(At, 0, 1); PG8_STAGE(PG8_SA(0, 0), a2, voffA);
;             PG8_BAR; PG8_WAIT_L(0); PG8_MMA(1, 0, At, B0); PG8_BAR; PG8_SCHED;
;             PG8_STAGE(PG8_SB(0, 1), b2 + hstep, voffB);
;             PG8_WAIT_V(6); PG8_BAR; PG8_MMA(1, 1, At, B1); PG8_BAR;
;             PG8_LDB(B0, 1, 0); PG8_SCHED; PG8_LDA(At, 1, 0); PG8_STAGE(PG8_SA(0, 1), a2 + hstep, voffA);
;             PG8_WAIT_L(8); PG8_BAR; PG8_WAIT_L(0); PG8_MMA(0, 0, At, B0); PG8_BAR; PG8_SCHED;
;             PG8_LDB(B1, 1, 1); PG8_STAGE(PG8_SB(1, 0), b3, voffB);
;             PG8_BAR; PG8_WAIT_L(0); PG8_MMA(0, 1, At, B1); PG8_BAR;
;             PG8_LDA(At, 1, 1); PG8_STAGE(PG8_SA(1, 0), a3, voffA);
;             PG8_BAR; PG8_WAIT_L(0); PG8_MMA(1, 0, At, B0); PG8_BAR; PG8_SCHED;
;             PG8_STAGE(PG8_SB(1, 1), b3 + hstep, voffB);
;             PG8_WAIT_V(6); PG8_BAR; PG8_MMA(1, 1, At, B1); PG8_BAR;
;             }
;         }
;         if constexpr (ALIGN_EPI) { if (wr == 0) PG8_BAR; }
	s_add_i32 s4, s28, s40
	v_lshl_add_u64 v[238:239], v[238:239], 0, s[62:63]
	s_mov_b32 m0, s4
	ds_read_b128 v[206:209], v164 offset:49152
	ds_read_b128 v[210:213], v164 offset:50176
	ds_read_b128 v[214:217], v164 offset:51200
	ds_read_b128 v[218:221], v164 offset:52224
	ds_read_b128 v[222:225], v164 offset:53248
	ds_read_b128 v[226:229], v164 offset:54272
	ds_read_b128 v[230:233], v164 offset:55296
	ds_read_b128 v[234:237], v164 offset:56320
	global_load_lds_dwordx4 v[238:239], off
	s_add_i32 m0, s4, 0x2000
	s_add_u32 s4, s34, 0x40080
	v_lshl_add_u64 v[238:239], v[240:241], 0, s[62:63]
	s_addc_u32 s5, s35, 0
	s_add_i32 s28, s29, s40
	global_load_lds_dwordx4 v[238:239], off
	v_lshl_add_u64 v[238:239], s[4:5], 0, v[152:153]
	s_mov_b32 m0, s28
	s_nop 0
	global_load_lds_dwordx4 v[238:239], off
	v_lshl_add_u64 v[238:239], s[4:5], 0, v[150:151]
	s_add_i32 m0, s28, 0x2000
	s_nop 0
	global_load_lds_dwordx4 v[238:239], off
	v_lshl_add_u64 v[238:239], v[242:243], 0, s[62:63]
	s_mov_b32 m0, s47
	s_nop 0
	global_load_lds_dwordx4 v[238:239], off
	v_lshl_add_u64 v[238:239], v[244:245], 0, s[62:63]
	s_mov_b32 m0, s48
	s_nop 0
	global_load_lds_dwordx4 v[238:239], off
	s_waitcnt vmcnt(8)
	s_waitcnt lgkmcnt(0)
	s_barrier
	s_setprio 1
	v_mfma_f32_16x16x32_bf16 v[62:65], v[158:161], v[206:209], v[62:65]
	v_mfma_f32_16x16x32_bf16 v[58:61], v[170:173], v[206:209], v[58:61]
	v_mfma_f32_16x16x32_bf16 v[46:49], v[158:161], v[214:217], v[46:49]
	v_mfma_f32_16x16x32_bf16 v[42:45], v[170:173], v[214:217], v[42:45]
	v_mfma_f32_16x16x32_bf16 v[30:33], v[158:161], v[222:225], v[30:33]
	v_mfma_f32_16x16x32_bf16 v[26:29], v[170:173], v[222:225], v[26:29]
	v_mfma_f32_16x16x32_bf16 v[14:17], v[158:161], v[230:233], v[14:17]
	v_mfma_f32_16x16x32_bf16 v[10:13], v[170:173], v[230:233], v[10:13]
	v_mfma_f32_16x16x32_bf16 v[62:65], v[166:169], v[210:213], v[62:65]
	v_mfma_f32_16x16x32_bf16 v[58:61], v[174:177], v[210:213], v[58:61]
	v_mfma_f32_16x16x32_bf16 v[46:49], v[166:169], v[218:221], v[46:49]
	v_mfma_f32_16x16x32_bf16 v[42:45], v[174:177], v[218:221], v[42:45]
	v_mfma_f32_16x16x32_bf16 v[30:33], v[166:169], v[226:229], v[30:33]
	v_mfma_f32_16x16x32_bf16 v[26:29], v[174:177], v[226:229], v[26:29]
	v_mfma_f32_16x16x32_bf16 v[14:17], v[166:169], v[234:237], v[14:17]
	v_mfma_f32_16x16x32_bf16 v[10:13], v[174:177], v[234:237], v[10:13]
	v_mfma_f32_16x16x32_bf16 v[54:57], v[178:181], v[206:209], v[54:57]
	v_mfma_f32_16x16x32_bf16 v[50:53], v[186:189], v[206:209], v[50:53]
	v_mfma_f32_16x16x32_bf16 v[38:41], v[178:181], v[214:217], v[38:41]
	v_mfma_f32_16x16x32_bf16 v[34:37], v[186:189], v[214:217], v[34:37]
	v_mfma_f32_16x16x32_bf16 v[22:25], v[178:181], v[222:225], v[22:25]
	v_mfma_f32_16x16x32_bf16 v[18:21], v[186:189], v[222:225], v[18:21]
	v_mfma_f32_16x16x32_bf16 v[6:9], v[178:181], v[230:233], v[6:9]
	v_mfma_f32_16x16x32_bf16 v[2:5], v[186:189], v[230:233], v[2:5]
	v_mfma_f32_16x16x32_bf16 v[54:57], v[182:185], v[210:213], v[54:57]
	v_mfma_f32_16x16x32_bf16 v[50:53], v[202:205], v[210:213], v[50:53]
	v_mfma_f32_16x16x32_bf16 v[38:41], v[182:185], v[218:221], v[38:41]
	v_mfma_f32_16x16x32_bf16 v[34:37], v[202:205], v[218:221], v[34:37]
	v_mfma_f32_16x16x32_bf16 v[22:25], v[182:185], v[226:229], v[22:25]
	v_mfma_f32_16x16x32_bf16 v[18:21], v[202:205], v[226:229], v[18:21]
	v_mfma_f32_16x16x32_bf16 v[6:9], v[182:185], v[234:237], v[6:9]
	v_mfma_f32_16x16x32_bf16 v[2:5], v[202:205], v[234:237], v[2:5]
	s_setprio 0
	s_barrier
	s_add_i32 s64, s64, 2
	s_add_u32 s54, s54, 0x100
	s_addc_u32 s55, s55, 0
	s_cmp_gt_u32 s64, 13
	s_mov_b64 s[28:29], s[30:31]
	s_cbranch_scc0 .LBB0_1680
	s_and_b64 vcc, exec, s[18:19]
	s_cbranch_vccz .LBB0_1683
	s_barrier

; #define PG8_STAGE(bufoff, gbase, voff) do { _Pragma("unroll") for (int _i = 0; _i < 2; ++_i) \
;         __builtin_amdgcn_global_load_lds((const unsigned*)((const char*)(gbase) + (voff)[_i]), (PG8_LAS unsigned*)(lds + (bufoff) + ldsw + _i * 8192), 16, 0, 0); } while (0)
; #define PG8_LDA(dst, b, h) do { _Pragma("unroll") for (int m = 0; m < 4; ++m) _Pragma("unroll") for (int k = 0; k < 2; ++k) dst[m][k] = *(const PG8_LAS bf16x8*)(lds + PG8_SA(b, h) + aoff + m * 2048 + k * 1024); } while (0)
; #define PG8_LDB(dst, b, h) do { _Pragma("unroll") for (int n = 0; n < 2; ++n) _Pragma("unroll") for (int k = 0; k < 2; ++k) dst[n][k] = *(const PG8_LAS bf16x8*)(lds + PG8_SB(b, h) + boff + n * 2048 + k * 1024); } while (0)
; #define PG8_MMA(ai, bj, At, Bt) do { __builtin_amdgcn_s_setprio(1); _Pragma("unroll") for (int m = 0; m < 4; ++m) _Pragma("unroll") for (int n = 0; n < 2; ++n) _Pragma("unroll") for (int k = 0; k < 2; ++k) \
;         acc[ai][bj][m][n] = __builtin_amdgcn_mfma_f32_16x16x32_bf16(Bt[n][k], At[m][k], acc[ai][bj][m][n], 0, 0, 0); __builtin_amdgcn_s_setprio(0); } while (0)
; #define PG8_WAIT_V(n) asm volatile("s_waitcnt vmcnt(" #n ")" ::: "memory")
; #define PG8_WAIT_L(n) asm volatile("s_waitcnt lgkmcnt(" #n ")" ::: "memory")
; template <class Epi, class Sched, bool ALIGN_EPI = false, bool SP2 = false>
; __device__ __forceinline__ void gemm_phase(PG8_LAS unsigned char* lds, const Gemm g, const Sched& S, const Epi& E) {
;     ...
;             const bool last = (t == nt - 2);
;             const char* a1 = cA + (size_t)(t + 1) * kstep;
;             const char* a2 = last ? nA : cA + (size_t)(t + 2) * kstep; const char* b2 = last ? nB : cB + (size_t)(t + 2) * kstep;
;             const char* a3 = a2 + kstep; const char* b3 = b2 + kstep;
;             if (last && has_next) S.a_ready(nxt);
;             if constexpr (SP2) {
;             PG8_LDB(B0, 0, 0); PG8_LDB(B1, 0, 1); PG8_SCHED; PG8_LDA(At, 0, 0); PG8_STAGE(PG8_SA(1, 1), a1 + hstep, voffA);
;             PG8_WAIT_V(8); PG8_WAIT_L(0); PG8_BAR; PG8_MMA(0, 0, At, B0); PG8_MMA(0, 1, At, B1); PG8_BAR; PG8_SCHED;
;             PG8_LDA(At, 0, 1); PG8_STAGE(PG8_SB(0, 0), b2, voffB); PG8_STAGE(PG8_SB(0, 1), b2 + hstep, voffB); PG8_STAGE(PG8_SA(0, 0), a2, voffA);
;             PG8_WAIT_V(8); PG8_WAIT_L(0); PG8_BAR; PG8_MMA(1, 0, At, B0); PG8_MMA(1, 1, At, B1); PG8_BAR; PG8_SCHED;
.LBB0_1764:
	s_add_u32 s4, s12, 0xfffc0080
	s_addc_u32 s5, s13, -1
	s_add_i32 s55, 0, 0x10000
	s_cmp_eq_u32 s54, 12
	s_cselect_b32 s31, s23, s5
	s_cselect_b32 s30, s50, s4
	v_add_u32_e32 v171, s55, v168
	s_cselect_b32 s29, s21, s53
	s_cselect_b32 s28, s51, s52
	s_add_i32 s64, 0, 0x14000
	ds_read_b128 v[164:167], v171
	ds_read_b128 v[172:175], v171 offset:1024
	ds_read_b128 v[176:179], v171 offset:2048
	ds_read_b128 v[180:183], v171 offset:3072
	v_add_u32_e32 v171, s64, v168
	ds_read_b128 v[184:187], v171
	ds_read_b128 v[202:205], v171 offset:1024
	ds_read_b128 v[206:209], v171 offset:2048
	ds_read_b128 v[210:213], v171 offset:3072
	v_lshl_add_u64 v[188:189], s[12:13], 0, v[160:161]
	s_add_i32 m0, s37, 0xc000
	ds_read_b128 v[214:217], v170
	ds_read_b128 v[218:221], v170 offset:1024
	ds_read_b128 v[222:225], v170 offset:2048
	ds_read_b128 v[226:229], v170 offset:3072
	ds_read_b128 v[230:233], v170 offset:4096
	ds_read_b128 v[234:237], v170 offset:5120
	ds_read_b128 v[238:241], v170 offset:6144
	ds_read_b128 v[242:245], v170 offset:7168
	global_load_lds_dwordx4 v[188:189], off
	v_lshl_add_u64 v[188:189], s[12:13], 0, v[162:163]
	s_add_i32 m0, s37, 0xe000
	s_nop 0
	global_load_lds_dwordx4 v[188:189], off
	s_waitcnt vmcnt(8)
	s_waitcnt lgkmcnt(0)
	s_barrier
	s_setprio 1
	v_mfma_f32_16x16x32_bf16 v[126:129], v[164:167], v[214:217], v[126:129]
	v_mfma_f32_16x16x32_bf16 v[114:117], v[176:179], v[214:217], v[114:117]
	v_mfma_f32_16x16x32_bf16 v[110:113], v[164:167], v[222:225], v[110:113]
	v_mfma_f32_16x16x32_bf16 v[98:101], v[176:179], v[222:225], v[98:101]
	v_mfma_f32_16x16x32_bf16 v[94:97], v[164:167], v[230:233], v[94:97]
	v_mfma_f32_16x16x32_bf16 v[82:85], v[176:179], v[230:233], v[82:85]
	v_mfma_f32_16x16x32_bf16 v[78:81], v[164:167], v[238:241], v[78:81]
	v_mfma_f32_16x16x32_bf16 v[66:69], v[176:179], v[238:241], v[66:69]
	v_mfma_f32_16x16x32_bf16 v[126:129], v[172:175], v[218:221], v[126:129]
	v_mfma_f32_16x16x32_bf16 v[114:117], v[180:183], v[218:221], v[114:117]
	v_mfma_f32_16x16x32_bf16 v[110:113], v[172:175], v[226:229], v[110:113]
	v_mfma_f32_16x16x32_bf16 v[98:101], v[180:183], v[226:229], v[98:101]
	v_mfma_f32_16x16x32_bf16 v[94:97], v[172:175], v[234:237], v[94:97]
	v_mfma_f32_16x16x32_bf16 v[82:85], v[180:183], v[234:237], v[82:85]
	v_mfma_f32_16x16x32_bf16 v[78:81], v[172:175], v[242:245], v[78:81]
	v_mfma_f32_16x16x32_bf16 v[66:69], v[180:183], v[242:245], v[66:69]
	v_mfma_f32_16x16x32_bf16 v[122:125], v[184:187], v[214:217], v[122:125]
	v_mfma_f32_16x16x32_bf16 v[118:121], v[206:209], v[214:217], v[118:121]
	v_mfma_f32_16x16x32_bf16 v[106:109], v[184:187], v[222:225], v[106:109]
	v_mfma_f32_16x16x32_bf16 v[102:105], v[206:209], v[222:225], v[102:105]
	v_mfma_f32_16x16x32_bf16 v[90:93], v[184:187], v[230:233], v[90:93]
	v_mfma_f32_16x16x32_bf16 v[86:89], v[206:209], v[230:233], v[86:89]
	v_mfma_f32_16x16x32_bf16 v[74:77], v[184:187], v[238:241], v[74:77]
	v_mfma_f32_16x16x32_bf16 v[70:73], v[206:209], v[238:241], v[70:73]
	v_mfma_f32_16x16x32_bf16 v[122:125], v[202:205], v[218:221], v[122:125]
	v_mfma_f32_16x16x32_bf16 v[118:121], v[210:213], v[218:221], v[118:121]
	v_mfma_f32_16x16x32_bf16 v[106:109], v[202:205], v[226:229], v[106:109]
	v_mfma_f32_16x16x32_bf16 v[102:105], v[210:213], v[226:229], v[102:105]
	v_mfma_f32_16x16x32_bf16 v[90:93], v[202:205], v[234:237], v[90:93]
	v_mfma_f32_16x16x32_bf16 v[86:89], v[210:213], v[234:237], v[86:89]
	v_mfma_f32_16x16x32_bf16 v[74:77], v[202:205], v[242:245], v[74:77]
	v_mfma_f32_16x16x32_bf16 v[70:73], v[210:213], v[242:245], v[70:73]
	s_setprio 0
	s_barrier
	s_add_i32 s4, s55, s36
	v_lshl_add_u64 v[188:189], s[28:29], 0, v[154:155]
	s_mov_b32 m0, s4
	ds_read_b128 v[214:217], v170 offset:16384
	ds_read_b128 v[218:221], v170 offset:17408
	ds_read_b128 v[222:225], v170 offset:18432
	ds_read_b128 v[226:229], v170 offset:19456
	ds_read_b128 v[230:233], v170 offset:20480
	ds_read_b128 v[234:237], v170 offset:21504
	ds_read_b128 v[238:241], v170 offset:22528
	ds_read_b128 v[242:245], v170 offset:23552
	global_load_lds_dwordx4 v[188:189], off
	s_add_i32 m0, s4, 0x2000
	s_add_u32 s4, s28, 0x40000
	v_lshl_add_u64 v[246:247], s[28:29], 0, v[150:151]
	s_addc_u32 s5, s29, 0
	s_add_i32 s55, s64, s36
	global_load_lds_dwordx4 v[246:247], off
	v_lshl_add_u64 v[248:249], s[4:5], 0, v[154:155]
	s_mov_b32 m0, s55
	v_lshl_add_u64 v[250:251], s[30:31], 0, v[152:153]
	global_load_lds_dwordx4 v[248:249], off
	v_lshl_add_u64 v[248:249], s[4:5], 0, v[150:151]
	s_add_i32 m0, s55, 0x2000
	s_nop 0
	global_load_lds_dwordx4 v[248:249], off
	v_lshl_add_u64 v[248:249], s[30:31], 0, v[156:157]
	s_mov_b32 m0, s37
	s_nop 0
	global_load_lds_dwordx4 v[248:249], off
	s_mov_b32 m0, s38
	s_nop 0
	global_load_lds_dwordx4 v[250:251], off
	s_waitcnt vmcnt(8)
	s_waitcnt lgkmcnt(0)
	s_barrier
; #define PG8_STAGE(bufoff, gbase, voff) do { _Pragma("unroll") for (int _i = 0; _i < 2; ++_i) \
;         __builtin_amdgcn_global_load_lds((const unsigned*)((const char*)(gbase) + (voff)[_i]), (PG8_LAS unsigned*)(lds + (bufoff) + ldsw + _i * 8192), 16, 0, 0); } while (0)
; #define PG8_LDA(dst, b, h) do { _Pragma("unroll") for (int m = 0; m < 4; ++m) _Pragma("unroll") for (int k = 0; k < 2; ++k) dst[m][k] = *(const PG8_LAS bf16x8*)(lds + PG8_SA(b, h) + aoff + m * 2048 + k * 1024); } while (0)
; #define PG8_LDB(dst, b, h) do { _Pragma("unroll") for (int n = 0; n < 2; ++n) _Pragma("unroll") for (int k = 0; k < 2; ++k) dst[n][k] = *(const PG8_LAS bf16x8*)(lds + PG8_SB(b, h) + boff + n * 2048 + k * 1024); } while (0)
; #define PG8_MMA(ai, bj, At, Bt) do { __builtin_amdgcn_s_setprio(1); _Pragma("unroll") for (int m = 0; m < 4; ++m) _Pragma("unroll") for (int n = 0; n < 2; ++n) _Pragma("unroll") for (int k = 0; k < 2; ++k) \
;         acc[ai][bj][m][n] = __builtin_amdgcn_mfma_f32_16x16x32_bf16(Bt[n][k], At[m][k], acc[ai][bj][m][n], 0, 0, 0); __builtin_amdgcn_s_setprio(0); } while (0)
; #define PG8_WAIT_V(n) asm volatile("s_waitcnt vmcnt(" #n ")" ::: "memory")
; #define PG8_WAIT_L(n) asm volatile("s_waitcnt lgkmcnt(" #n ")" ::: "memory")
; #define PG8_BAR __builtin_amdgcn_s_barrier()
; #define PG8_SCHED __builtin_amdgcn_sched_barrier(0)
; template <class Epi, class Sched, bool ALIGN_EPI = false, bool SP2 = false>
; __device__ __forceinline__ void gemm_phase(PG8_LAS unsigned char* lds, const Gemm g, const Sched& S, const Epi& E) {
;     ...
;             PG8_WAIT_V(8); PG8_WAIT_L(0); PG8_BAR; PG8_MMA(1, 0, At, B0); PG8_MMA(1, 1, At, B1); PG8_BAR; PG8_SCHED;
;             PG8_LDB(B0, 1, 0); PG8_LDB(B1, 1, 1); PG8_SCHED; PG8_LDA(At, 1, 0); PG8_STAGE(PG8_SA(0, 1), a2 + hstep, voffA);
;             PG8_WAIT_V(8); PG8_WAIT_L(0); PG8_BAR; PG8_MMA(0, 0, At, B0); PG8_MMA(0, 1, At, B1); PG8_BAR; PG8_SCHED;
	s_setprio 1
	v_mfma_f32_16x16x32_bf16 v[62:65], v[164:167], v[214:217], v[62:65]
	v_mfma_f32_16x16x32_bf16 v[50:53], v[176:179], v[214:217], v[50:53]
	v_mfma_f32_16x16x32_bf16 v[46:49], v[164:167], v[222:225], v[46:49]
	v_mfma_f32_16x16x32_bf16 v[34:37], v[176:179], v[222:225], v[34:37]
	v_mfma_f32_16x16x32_bf16 v[30:33], v[164:167], v[230:233], v[30:33]
	v_mfma_f32_16x16x32_bf16 v[18:21], v[176:179], v[230:233], v[18:21]
	v_mfma_f32_16x16x32_bf16 v[14:17], v[164:167], v[238:241], v[14:17]
	v_mfma_f32_16x16x32_bf16 v[6:9], v[176:179], v[238:241], v[6:9]
	v_mfma_f32_16x16x32_bf16 v[62:65], v[172:175], v[218:221], v[62:65]
	v_mfma_f32_16x16x32_bf16 v[50:53], v[180:183], v[218:221], v[50:53]
	v_mfma_f32_16x16x32_bf16 v[46:49], v[172:175], v[226:229], v[46:49]
	v_mfma_f32_16x16x32_bf16 v[34:37], v[180:183], v[226:229], v[34:37]
	v_mfma_f32_16x16x32_bf16 v[30:33], v[172:175], v[234:237], v[30:33]
	v_mfma_f32_16x16x32_bf16 v[18:21], v[180:183], v[234:237], v[18:21]
	v_mfma_f32_16x16x32_bf16 v[14:17], v[172:175], v[242:245], v[14:17]
	v_mfma_f32_16x16x32_bf16 v[6:9], v[180:183], v[242:245], v[6:9]
	v_mfma_f32_16x16x32_bf16 v[58:61], v[184:187], v[214:217], v[58:61]
	v_mfma_f32_16x16x32_bf16 v[54:57], v[206:209], v[214:217], v[54:57]
	v_mfma_f32_16x16x32_bf16 v[42:45], v[184:187], v[222:225], v[42:45]
	v_mfma_f32_16x16x32_bf16 v[38:41], v[206:209], v[222:225], v[38:41]
	v_mfma_f32_16x16x32_bf16 v[26:29], v[184:187], v[230:233], v[26:29]
	v_mfma_f32_16x16x32_bf16 v[22:25], v[206:209], v[230:233], v[22:25]
	v_mfma_f32_16x16x32_bf16 v[10:13], v[184:187], v[238:241], v[10:13]
	v_mfma_f32_16x16x32_bf16 v[2:5], v[206:209], v[238:241], v[2:5]
	v_mfma_f32_16x16x32_bf16 v[58:61], v[202:205], v[218:221], v[58:61]
	v_mfma_f32_16x16x32_bf16 v[54:57], v[210:213], v[218:221], v[54:57]
	v_mfma_f32_16x16x32_bf16 v[42:45], v[202:205], v[226:229], v[42:45]
	v_mfma_f32_16x16x32_bf16 v[38:41], v[210:213], v[226:229], v[38:41]
	v_mfma_f32_16x16x32_bf16 v[26:29], v[202:205], v[234:237], v[26:29]
	v_mfma_f32_16x16x32_bf16 v[22:25], v[210:213], v[234:237], v[22:25]
	v_mfma_f32_16x16x32_bf16 v[10:13], v[202:205], v[242:245], v[10:13]
	v_mfma_f32_16x16x32_bf16 v[2:5], v[210:213], v[242:245], v[2:5]
	s_setprio 0
	s_barrier
	s_add_i32 s55, 0, 0x18000
	v_add_u32_e32 v171, s55, v168
	s_add_i32 s64, 0, 0x1c000
	ds_read_b128 v[164:167], v171
	ds_read_b128 v[172:175], v171 offset:1024
	ds_read_b128 v[176:179], v171 offset:2048
	ds_read_b128 v[180:183], v171 offset:3072
	v_add_u32_e32 v171, s64, v168
	ds_read_b128 v[184:187], v171
	ds_read_b128 v[202:205], v171 offset:1024
	ds_read_b128 v[206:209], v171 offset:2048
	ds_read_b128 v[210:213], v171 offset:3072
	s_add_u32 s4, s30, 0x40000
	s_addc_u32 s5, s31, 0
	s_mov_b32 m0, s39
	v_lshl_add_u64 v[252:253], s[4:5], 0, v[156:157]
	ds_read_b128 v[214:217], v170 offset:32768
	ds_read_b128 v[218:221], v170 offset:33792
	ds_read_b128 v[222:225], v170 offset:34816
	ds_read_b128 v[226:229], v170 offset:35840
	ds_read_b128 v[230:233], v170 offset:36864
	ds_read_b128 v[234:237], v170 offset:37888
	ds_read_b128 v[238:241], v170 offset:38912
	ds_read_b128 v[242:245], v170 offset:39936
	global_load_lds_dwordx4 v[252:253], off
	v_lshl_add_u64 v[252:253], s[4:5], 0, v[152:153]
	s_mov_b32 m0, s40
	s_nop 0
	global_load_lds_dwordx4 v[252:253], off
	s_waitcnt vmcnt(8)
	s_waitcnt lgkmcnt(0)
	s_barrier
	s_setprio 1
	v_mfma_f32_16x16x32_bf16 v[126:129], v[164:167], v[214:217], v[126:129]
	v_mfma_f32_16x16x32_bf16 v[114:117], v[176:179], v[214:217], v[114:117]
	v_mfma_f32_16x16x32_bf16 v[110:113], v[164:167], v[222:225], v[110:113]
	v_mfma_f32_16x16x32_bf16 v[98:101], v[176:179], v[222:225], v[98:101]
	v_mfma_f32_16x16x32_bf16 v[94:97], v[164:167], v[230:233], v[94:97]
	v_mfma_f32_16x16x32_bf16 v[82:85], v[176:179], v[230:233], v[82:85]
	v_mfma_f32_16x16x32_bf16 v[78:81], v[164:167], v[238:241], v[78:81]
	v_mfma_f32_16x16x32_bf16 v[66:69], v[176:179], v[238:241], v[66:69]
	v_mfma_f32_16x16x32_bf16 v[126:129], v[172:175], v[218:221], v[126:129]
	v_mfma_f32_16x16x32_bf16 v[114:117], v[180:183], v[218:221], v[114:117]
	v_mfma_f32_16x16x32_bf16 v[110:113], v[172:175], v[226:229], v[110:113]
	v_mfma_f32_16x16x32_bf16 v[98:101], v[180:183], v[226:229], v[98:101]
	v_mfma_f32_16x16x32_bf16 v[94:97], v[172:175], v[234:237], v[94:97]
	v_mfma_f32_16x16x32_bf16 v[82:85], v[180:183], v[234:237], v[82:85]
	v_mfma_f32_16x16x32_bf16 v[78:81], v[172:175], v[242:245], v[78:81]
	v_mfma_f32_16x16x32_bf16 v[66:69], v[180:183], v[242:245], v[66:69]
	v_mfma_f32_16x16x32_bf16 v[122:125], v[184:187], v[214:217], v[122:125]
	v_mfma_f32_16x16x32_bf16 v[118:121], v[206:209], v[214:217], v[118:121]
	v_mfma_f32_16x16x32_bf16 v[106:109], v[184:187], v[222:225], v[106:109]
	v_mfma_f32_16x16x32_bf16 v[102:105], v[206:209], v[222:225], v[102:105]
	v_mfma_f32_16x16x32_bf16 v[90:93], v[184:187], v[230:233], v[90:93]
	v_mfma_f32_16x16x32_bf16 v[86:89], v[206:209], v[230:233], v[86:89]
	v_mfma_f32_16x16x32_bf16 v[74:77], v[184:187], v[238:241], v[74:77]
	v_mfma_f32_16x16x32_bf16 v[70:73], v[206:209], v[238:241], v[70:73]
	v_mfma_f32_16x16x32_bf16 v[122:125], v[202:205], v[218:221], v[122:125]
	v_mfma_f32_16x16x32_bf16 v[118:121], v[210:213], v[218:221], v[118:121]
	v_mfma_f32_16x16x32_bf16 v[106:109], v[202:205], v[226:229], v[106:109]
	v_mfma_f32_16x16x32_bf16 v[102:105], v[210:213], v[226:229], v[102:105]
	v_mfma_f32_16x16x32_bf16 v[90:93], v[202:205], v[234:237], v[90:93]
	v_mfma_f32_16x16x32_bf16 v[86:89], v[210:213], v[234:237], v[86:89]
	v_mfma_f32_16x16x32_bf16 v[74:77], v[202:205], v[242:245], v[74:77]
	v_mfma_f32_16x16x32_bf16 v[70:73], v[210:213], v[242:245], v[70:73]
	s_setprio 0
	s_barrier
; #define PG8_STAGE(bufoff, gbase, voff) do { _Pragma("unroll") for (int _i = 0; _i < 2; ++_i) \
;         __builtin_amdgcn_global_load_lds((const unsigned*)((const char*)(gbase) + (voff)[_i]), (PG8_LAS unsigned*)(lds + (bufoff) + ldsw + _i * 8192), 16, 0, 0); } while (0)
; #define PG8_LDA(dst, b, h) do { _Pragma("unroll") for (int m = 0; m < 4; ++m) _Pragma("unroll") for (int k = 0; k < 2; ++k) dst[m][k] = *(const PG8_LAS bf16x8*)(lds + PG8_SA(b, h) + aoff + m * 2048 + k * 1024); } while (0)
; #define PG8_WAIT_V(n) asm volatile("s_waitcnt vmcnt(" #n ")" ::: "memory")
; template <class Epi, class Sched, bool ALIGN_EPI = false, bool SP2 = false>
; __device__ __forceinline__ void gemm_phase(PG8_LAS unsigned char* lds, const Gemm g, const Sched& S, const Epi& E) {
;     ...
;             PG8_LDA(At, 1, 1); PG8_STAGE(PG8_SB(1, 0), b3, voffB); PG8_STAGE(PG8_SB(1, 1), b3 + hstep, voffB); PG8_STAGE(PG8_SA(1, 0), a3, voffA);
;             PG8_WAIT_V(8); PG8_WAIT_L(0); PG8_BAR; PG8_MMA(1, 0, At, B0); PG8_MMA(1, 1, At, B1); PG8_BAR; PG8_SCHED;
;             } else {
;             PG8_LDB(B0, 0, 0); PG8_SCHED; PG8_LDA(At, 0, 0); PG8_STAGE(PG8_SA(1, 1), a1 + hstep, voffA);
;             PG8_WAIT_L(8); PG8_BAR; PG8_WAIT_L(0); PG8_MMA(0, 0, At, B0); PG8_BAR; PG8_SCHED;
;             PG8_LDB(B1, 0, 1); PG8_STAGE(PG8_SB(0, 0), b2, voffB);
;             PG8_BAR; PG8_WAIT_L(0); PG8_MMA(0, 1, At, B1); PG8_BAR;
;             PG8_LDA(At, 0, 1); PG8_STAGE(PG8_SA(0, 0), a2, voffA);
;             PG8_BAR; PG8_WAIT_L(0); PG8_MMA(1, 0, At, B0); PG8_BAR; PG8_SCHED;
;             PG8_STAGE(PG8_SB(0, 1), b2 + hstep, voffB);
;             PG8_WAIT_V(6); PG8_BAR; PG8_MMA(1, 1, At, B1); PG8_BAR;
;             PG8_LDB(B0, 1, 0); PG8_SCHED; PG8_LDA(At, 1, 0); PG8_STAGE(PG8_SA(0, 1), a2 + hstep, voffA);
;             PG8_WAIT_L(8); PG8_BAR; PG8_WAIT_L(0); PG8_MMA(0, 0, At, B0); PG8_BAR; PG8_SCHED;
;             PG8_LDB(B1, 1, 1); PG8_STAGE(PG8_SB(1, 0), b3, voffB);
;             PG8_BAR; PG8_WAIT_L(0); PG8_MMA(0, 1, At, B1); PG8_BAR;
;             PG8_LDA(At, 1, 1); PG8_STAGE(PG8_SA(1, 0), a3, voffA);
;             PG8_BAR; PG8_WAIT_L(0); PG8_MMA(1, 0, At, B0); PG8_BAR; PG8_SCHED;
;             PG8_STAGE(PG8_SB(1, 1), b3 + hstep, voffB);
;             PG8_WAIT_V(6); PG8_BAR; PG8_MMA(1, 1, At, B1); PG8_BAR;
;             }
;         }
;         if constexpr (ALIGN_EPI) { if (wr == 0) PG8_BAR; }
	s_add_i32 s4, s55, s36
	v_lshl_add_u64 v[188:189], v[188:189], 0, s[62:63]
	s_mov_b32 m0, s4
	ds_read_b128 v[214:217], v170 offset:49152
	ds_read_b128 v[218:221], v170 offset:50176
	ds_read_b128 v[222:225], v170 offset:51200
	ds_read_b128 v[226:229], v170 offset:52224
	ds_read_b128 v[230:233], v170 offset:53248
	ds_read_b128 v[234:237], v170 offset:54272
	ds_read_b128 v[238:241], v170 offset:55296
	ds_read_b128 v[242:245], v170 offset:56320
	global_load_lds_dwordx4 v[188:189], off
	s_add_i32 m0, s4, 0x2000
	s_add_u32 s4, s28, 0x40080
	v_lshl_add_u64 v[188:189], v[246:247], 0, s[62:63]
	s_addc_u32 s5, s29, 0
	s_add_i32 s28, s64, s36
	global_load_lds_dwordx4 v[188:189], off
	v_lshl_add_u64 v[188:189], s[4:5], 0, v[154:155]
	s_mov_b32 m0, s28
	s_nop 0
	global_load_lds_dwordx4 v[188:189], off
	v_lshl_add_u64 v[188:189], s[4:5], 0, v[150:151]
	s_add_i32 m0, s28, 0x2000
	s_nop 0
	global_load_lds_dwordx4 v[188:189], off
	v_lshl_add_u64 v[188:189], v[248:249], 0, s[62:63]
	s_mov_b32 m0, s42
	s_nop 0
	global_load_lds_dwordx4 v[188:189], off
	v_lshl_add_u64 v[188:189], v[250:251], 0, s[62:63]
	s_mov_b32 m0, s43
	s_nop 0
	global_load_lds_dwordx4 v[188:189], off
	s_waitcnt vmcnt(8)
	s_waitcnt lgkmcnt(0)
	s_barrier
	s_setprio 1
	v_mfma_f32_16x16x32_bf16 v[62:65], v[164:167], v[214:217], v[62:65]
	v_mfma_f32_16x16x32_bf16 v[50:53], v[176:179], v[214:217], v[50:53]
	v_mfma_f32_16x16x32_bf16 v[46:49], v[164:167], v[222:225], v[46:49]
	v_mfma_f32_16x16x32_bf16 v[34:37], v[176:179], v[222:225], v[34:37]
	v_mfma_f32_16x16x32_bf16 v[30:33], v[164:167], v[230:233], v[30:33]
	v_mfma_f32_16x16x32_bf16 v[18:21], v[176:179], v[230:233], v[18:21]
	v_mfma_f32_16x16x32_bf16 v[14:17], v[164:167], v[238:241], v[14:17]
	v_mfma_f32_16x16x32_bf16 v[6:9], v[176:179], v[238:241], v[6:9]
	v_mfma_f32_16x16x32_bf16 v[62:65], v[172:175], v[218:221], v[62:65]
	v_mfma_f32_16x16x32_bf16 v[50:53], v[180:183], v[218:221], v[50:53]
	v_mfma_f32_16x16x32_bf16 v[46:49], v[172:175], v[226:229], v[46:49]
	v_mfma_f32_16x16x32_bf16 v[34:37], v[180:183], v[226:229], v[34:37]
	v_mfma_f32_16x16x32_bf16 v[30:33], v[172:175], v[234:237], v[30:33]
	v_mfma_f32_16x16x32_bf16 v[18:21], v[180:183], v[234:237], v[18:21]
	v_mfma_f32_16x16x32_bf16 v[14:17], v[172:175], v[242:245], v[14:17]
	v_mfma_f32_16x16x32_bf16 v[6:9], v[180:183], v[242:245], v[6:9]
	v_mfma_f32_16x16x32_bf16 v[58:61], v[184:187], v[214:217], v[58:61]
	v_mfma_f32_16x16x32_bf16 v[54:57], v[206:209], v[214:217], v[54:57]
	v_mfma_f32_16x16x32_bf16 v[42:45], v[184:187], v[222:225], v[42:45]
	v_mfma_f32_16x16x32_bf16 v[38:41], v[206:209], v[222:225], v[38:41]
	v_mfma_f32_16x16x32_bf16 v[26:29], v[184:187], v[230:233], v[26:29]
	v_mfma_f32_16x16x32_bf16 v[22:25], v[206:209], v[230:233], v[22:25]
	v_mfma_f32_16x16x32_bf16 v[10:13], v[184:187], v[238:241], v[10:13]
	v_mfma_f32_16x16x32_bf16 v[2:5], v[206:209], v[238:241], v[2:5]
	v_mfma_f32_16x16x32_bf16 v[58:61], v[202:205], v[218:221], v[58:61]
	v_mfma_f32_16x16x32_bf16 v[54:57], v[210:213], v[218:221], v[54:57]
	v_mfma_f32_16x16x32_bf16 v[42:45], v[202:205], v[226:229], v[42:45]
	v_mfma_f32_16x16x32_bf16 v[38:41], v[210:213], v[226:229], v[38:41]
	v_mfma_f32_16x16x32_bf16 v[26:29], v[202:205], v[234:237], v[26:29]
	v_mfma_f32_16x16x32_bf16 v[22:25], v[210:213], v[234:237], v[22:25]
	v_mfma_f32_16x16x32_bf16 v[10:13], v[202:205], v[242:245], v[10:13]
	v_mfma_f32_16x16x32_bf16 v[2:5], v[210:213], v[242:245], v[2:5]
	s_setprio 0
	s_barrier
	s_add_i32 s54, s54, 2
	s_add_u32 s12, s12, 0x100
	s_addc_u32 s13, s13, 0
	s_add_u32 s52, s52, 0x100
	s_addc_u32 s53, s53, 0
	s_cmp_gt_u32 s54, 13
	s_cbranch_scc0 .LBB0_1764
	s_and_b64 vcc, exec, s[18:19]
	s_cbranch_vccz .LBB0_1767
	s_barrier

; #define PG8_STAGE(bufoff, gbase, voff) do { _Pragma("unroll") for (int _i = 0; _i < 2; ++_i) \
;         __builtin_amdgcn_global_load_lds((const unsigned*)((const char*)(gbase) + (voff)[_i]), (PG8_LAS unsigned*)(lds + (bufoff) + ldsw + _i * 8192), 16, 0, 0); } while (0)
; #define PG8_LDA(dst, b, h) do { _Pragma("unroll") for (int m = 0; m < 4; ++m) _Pragma("unroll") for (int k = 0; k < 2; ++k) dst[m][k] = *(const PG8_LAS bf16x8*)(lds + PG8_SA(b, h) + aoff + m * 2048 + k * 1024); } while (0)
; #define PG8_LDB(dst, b, h) do { _Pragma("unroll") for (int n = 0; n < 2; ++n) _Pragma("unroll") for (int k = 0; k < 2; ++k) dst[n][k] = *(const PG8_LAS bf16x8*)(lds + PG8_SB(b, h) + boff + n * 2048 + k * 1024); } while (0)
; #define PG8_MMA(ai, bj, At, Bt) do { __builtin_amdgcn_s_setprio(1); _Pragma("unroll") for (int m = 0; m < 4; ++m) _Pragma("unroll") for (int n = 0; n < 2; ++n) _Pragma("unroll") for (int k = 0; k < 2; ++k) \
;         acc[ai][bj][m][n] = __builtin_amdgcn_mfma_f32_16x16x32_bf16(Bt[n][k], At[m][k], acc[ai][bj][m][n], 0, 0, 0); __builtin_amdgcn_s_setprio(0); } while (0)
; #define PG8_WAIT_V(n) asm volatile("s_waitcnt vmcnt(" #n ")" ::: "memory")
; #define PG8_WAIT_L(n) asm volatile("s_waitcnt lgkmcnt(" #n ")" ::: "memory")
; template <class Epi, class Sched, bool ALIGN_EPI = false, bool SP2 = false>
; __device__ __forceinline__ void gemm_phase(PG8_LAS unsigned char* lds, const Gemm g, const Sched& S, const Epi& E) {
;     ...
;             const bool last = (t == nt - 2);
;             const char* a1 = cA + (size_t)(t + 1) * kstep;
;             const char* a2 = last ? nA : cA + (size_t)(t + 2) * kstep; const char* b2 = last ? nB : cB + (size_t)(t + 2) * kstep;
;             const char* a3 = a2 + kstep; const char* b3 = b2 + kstep;
;             if (last && has_next) S.a_ready(nxt);
;             if constexpr (SP2) {
;             PG8_LDB(B0, 0, 0); PG8_LDB(B1, 0, 1); PG8_SCHED; PG8_LDA(At, 0, 0); PG8_STAGE(PG8_SA(1, 1), a1 + hstep, voffA);
;             PG8_WAIT_V(8); PG8_WAIT_L(0); PG8_BAR; PG8_MMA(0, 0, At, B0); PG8_MMA(0, 1, At, B1); PG8_BAR; PG8_SCHED;
;             PG8_LDA(At, 0, 1); PG8_STAGE(PG8_SB(0, 0), b2, voffB); PG8_STAGE(PG8_SB(0, 1), b2 + hstep, voffB); PG8_STAGE(PG8_SA(0, 0), a2, voffA);
;             PG8_WAIT_V(8); PG8_WAIT_L(0); PG8_BAR; PG8_MMA(1, 0, At, B0); PG8_MMA(1, 1, At, B1); PG8_BAR; PG8_SCHED;
.LBB0_1890:
	s_add_u32 s24, s22, 0x100
	s_addc_u32 s25, s23, 0
	s_add_i32 s4, 0, 0x10000
	s_cmp_eq_u32 s50, 40
	s_cselect_b32 s29, s11, s25
	s_cselect_b32 s28, s10, s24
	v_add_u32_e32 v165, s4, v162
	s_cselect_b32 s27, s21, s49
	s_cselect_b32 s26, s20, s48
	s_add_i32 s51, 0, 0x14000
	ds_read_b128 v[158:161], v165
	ds_read_b128 v[166:169], v165 offset:1024
	ds_read_b128 v[170:173], v165 offset:2048
	ds_read_b128 v[174:177], v165 offset:3072
	v_add_u32_e32 v165, s51, v162
	ds_read_b128 v[178:181], v165
	ds_read_b128 v[182:185], v165 offset:1024
	ds_read_b128 v[186:189], v165 offset:2048
	ds_read_b128 v[202:205], v165 offset:3072
	v_lshl_add_u64 v[238:239], s[22:23], 0, v[154:155]
	s_add_i32 m0, s35, 0xc000
	ds_read_b128 v[206:209], v164
	ds_read_b128 v[210:213], v164 offset:1024
	ds_read_b128 v[214:217], v164 offset:2048
	ds_read_b128 v[218:221], v164 offset:3072
	ds_read_b128 v[222:225], v164 offset:4096
	ds_read_b128 v[226:229], v164 offset:5120
	ds_read_b128 v[230:233], v164 offset:6144
	ds_read_b128 v[234:237], v164 offset:7168
	global_load_lds_dwordx4 v[238:239], off
	v_lshl_add_u64 v[238:239], s[22:23], 0, v[156:157]
	s_add_i32 m0, s35, 0xe000
	s_nop 0
	global_load_lds_dwordx4 v[238:239], off
	s_bfe_u32 s100, s50, 0x30001
	s_lshl_b32 s100, s100, 16
	v_add_u32_e32 v250, s100, v249
	global_load_dword v248, v250, s[14:15]
	s_waitcnt vmcnt(9)
	s_waitcnt lgkmcnt(0)
	s_barrier
	s_setprio 1
	v_mfma_f32_16x16x32_bf16 v[126:129], v[158:161], v[206:209], v[126:129]
	v_mfma_f32_16x16x32_bf16 v[122:125], v[170:173], v[206:209], v[122:125]
	v_mfma_f32_16x16x32_bf16 v[110:113], v[158:161], v[214:217], v[110:113]
	v_mfma_f32_16x16x32_bf16 v[106:109], v[170:173], v[214:217], v[106:109]
	v_mfma_f32_16x16x32_bf16 v[94:97], v[158:161], v[222:225], v[94:97]
	v_mfma_f32_16x16x32_bf16 v[90:93], v[170:173], v[222:225], v[90:93]
	v_mfma_f32_16x16x32_bf16 v[78:81], v[158:161], v[230:233], v[78:81]
	v_mfma_f32_16x16x32_bf16 v[74:77], v[170:173], v[230:233], v[74:77]
	v_mfma_f32_16x16x32_bf16 v[126:129], v[166:169], v[210:213], v[126:129]
	v_mfma_f32_16x16x32_bf16 v[122:125], v[174:177], v[210:213], v[122:125]
	v_mfma_f32_16x16x32_bf16 v[110:113], v[166:169], v[218:221], v[110:113]
	v_mfma_f32_16x16x32_bf16 v[106:109], v[174:177], v[218:221], v[106:109]
	v_mfma_f32_16x16x32_bf16 v[94:97], v[166:169], v[226:229], v[94:97]
	v_mfma_f32_16x16x32_bf16 v[90:93], v[174:177], v[226:229], v[90:93]
	v_mfma_f32_16x16x32_bf16 v[78:81], v[166:169], v[234:237], v[78:81]
	v_mfma_f32_16x16x32_bf16 v[74:77], v[174:177], v[234:237], v[74:77]
	v_mfma_f32_16x16x32_bf16 v[118:121], v[178:181], v[206:209], v[118:121]
	v_mfma_f32_16x16x32_bf16 v[114:117], v[186:189], v[206:209], v[114:117]
	v_mfma_f32_16x16x32_bf16 v[102:105], v[178:181], v[214:217], v[102:105]
	v_mfma_f32_16x16x32_bf16 v[98:101], v[186:189], v[214:217], v[98:101]
	v_mfma_f32_16x16x32_bf16 v[86:89], v[178:181], v[222:225], v[86:89]
	v_mfma_f32_16x16x32_bf16 v[82:85], v[186:189], v[222:225], v[82:85]
	v_mfma_f32_16x16x32_bf16 v[70:73], v[178:181], v[230:233], v[70:73]
	v_mfma_f32_16x16x32_bf16 v[66:69], v[186:189], v[230:233], v[66:69]
	v_mfma_f32_16x16x32_bf16 v[118:121], v[182:185], v[210:213], v[118:121]
	v_mfma_f32_16x16x32_bf16 v[114:117], v[202:205], v[210:213], v[114:117]
	v_mfma_f32_16x16x32_bf16 v[102:105], v[182:185], v[218:221], v[102:105]
	v_mfma_f32_16x16x32_bf16 v[98:101], v[202:205], v[218:221], v[98:101]
	v_mfma_f32_16x16x32_bf16 v[86:89], v[182:185], v[226:229], v[86:89]
	v_mfma_f32_16x16x32_bf16 v[82:85], v[202:205], v[226:229], v[82:85]
	v_mfma_f32_16x16x32_bf16 v[70:73], v[182:185], v[234:237], v[70:73]
	v_mfma_f32_16x16x32_bf16 v[66:69], v[202:205], v[234:237], v[66:69]
	s_setprio 0
	s_barrier
	s_add_i32 s4, s4, s34
	v_lshl_add_u64 v[238:239], s[26:27], 0, v[152:153]
	s_mov_b32 m0, s4
	ds_read_b128 v[206:209], v164 offset:16384
	ds_read_b128 v[210:213], v164 offset:17408
	ds_read_b128 v[214:217], v164 offset:18432
	ds_read_b128 v[218:221], v164 offset:19456
	ds_read_b128 v[222:225], v164 offset:20480
	ds_read_b128 v[226:229], v164 offset:21504
	ds_read_b128 v[230:233], v164 offset:22528
	ds_read_b128 v[234:237], v164 offset:23552
	global_load_lds_dwordx4 v[238:239], off
	s_add_i32 m0, s4, 0x2000
	s_add_u32 s4, s26, 0xb0000
	v_lshl_add_u64 v[240:241], s[26:27], 0, v[150:151]
	s_addc_u32 s5, s27, 0
	s_add_i32 s22, s51, s34
	global_load_lds_dwordx4 v[240:241], off
	v_lshl_add_u64 v[242:243], s[4:5], 0, v[152:153]
	s_mov_b32 m0, s22
	v_lshl_add_u64 v[244:245], s[28:29], 0, v[150:151]
	global_load_lds_dwordx4 v[242:243], off
	v_lshl_add_u64 v[242:243], s[4:5], 0, v[150:151]
	s_add_i32 m0, s22, 0x2000
	s_nop 0
	global_load_lds_dwordx4 v[242:243], off
	v_lshl_add_u64 v[242:243], s[28:29], 0, v[152:153]
	s_mov_b32 m0, s35
	s_nop 0
	global_load_lds_dwordx4 v[242:243], off
	s_mov_b32 m0, s36
	s_nop 0
	global_load_lds_dwordx4 v[244:245], off
	s_waitcnt vmcnt(9)
	s_waitcnt lgkmcnt(0)
	s_barrier
; #define PG8_STAGE(bufoff, gbase, voff) do { _Pragma("unroll") for (int _i = 0; _i < 2; ++_i) \
;         __builtin_amdgcn_global_load_lds((const unsigned*)((const char*)(gbase) + (voff)[_i]), (PG8_LAS unsigned*)(lds + (bufoff) + ldsw + _i * 8192), 16, 0, 0); } while (0)
; #define PG8_LDA(dst, b, h) do { _Pragma("unroll") for (int m = 0; m < 4; ++m) _Pragma("unroll") for (int k = 0; k < 2; ++k) dst[m][k] = *(const PG8_LAS bf16x8*)(lds + PG8_SA(b, h) + aoff + m * 2048 + k * 1024); } while (0)
; #define PG8_LDB(dst, b, h) do { _Pragma("unroll") for (int n = 0; n < 2; ++n) _Pragma("unroll") for (int k = 0; k < 2; ++k) dst[n][k] = *(const PG8_LAS bf16x8*)(lds + PG8_SB(b, h) + boff + n * 2048 + k * 1024); } while (0)
; #define PG8_MMA(ai, bj, At, Bt) do { __builtin_amdgcn_s_setprio(1); _Pragma("unroll") for (int m = 0; m < 4; ++m) _Pragma("unroll") for (int n = 0; n < 2; ++n) _Pragma("unroll") for (int k = 0; k < 2; ++k) \
;         acc[ai][bj][m][n] = __builtin_amdgcn_mfma_f32_16x16x32_bf16(Bt[n][k], At[m][k], acc[ai][bj][m][n], 0, 0, 0); __builtin_amdgcn_s_setprio(0); } while (0)
; #define PG8_WAIT_V(n) asm volatile("s_waitcnt vmcnt(" #n ")" ::: "memory")
; #define PG8_WAIT_L(n) asm volatile("s_waitcnt lgkmcnt(" #n ")" ::: "memory")
; #define PG8_BAR __builtin_amdgcn_s_barrier()
; #define PG8_SCHED __builtin_amdgcn_sched_barrier(0)
; template <class Epi, class Sched, bool ALIGN_EPI = false, bool SP2 = false>
; __device__ __forceinline__ void gemm_phase(PG8_LAS unsigned char* lds, const Gemm g, const Sched& S, const Epi& E) {
;     ...
;             PG8_WAIT_V(8); PG8_WAIT_L(0); PG8_BAR; PG8_MMA(1, 0, At, B0); PG8_MMA(1, 1, At, B1); PG8_BAR; PG8_SCHED;
;             PG8_LDB(B0, 1, 0); PG8_LDB(B1, 1, 1); PG8_SCHED; PG8_LDA(At, 1, 0); PG8_STAGE(PG8_SA(0, 1), a2 + hstep, voffA);
;             PG8_WAIT_V(8); PG8_WAIT_L(0); PG8_BAR; PG8_MMA(0, 0, At, B0); PG8_MMA(0, 1, At, B1); PG8_BAR; PG8_SCHED;
	s_setprio 1
	v_mfma_f32_16x16x32_bf16 v[62:65], v[158:161], v[206:209], v[62:65]
	v_mfma_f32_16x16x32_bf16 v[58:61], v[170:173], v[206:209], v[58:61]
	v_mfma_f32_16x16x32_bf16 v[46:49], v[158:161], v[214:217], v[46:49]
	v_mfma_f32_16x16x32_bf16 v[42:45], v[170:173], v[214:217], v[42:45]
	v_mfma_f32_16x16x32_bf16 v[30:33], v[158:161], v[222:225], v[30:33]
	v_mfma_f32_16x16x32_bf16 v[26:29], v[170:173], v[222:225], v[26:29]
	v_mfma_f32_16x16x32_bf16 v[14:17], v[158:161], v[230:233], v[14:17]
	v_mfma_f32_16x16x32_bf16 v[10:13], v[170:173], v[230:233], v[10:13]
	v_mfma_f32_16x16x32_bf16 v[62:65], v[166:169], v[210:213], v[62:65]
	v_mfma_f32_16x16x32_bf16 v[58:61], v[174:177], v[210:213], v[58:61]
	v_mfma_f32_16x16x32_bf16 v[46:49], v[166:169], v[218:221], v[46:49]
	v_mfma_f32_16x16x32_bf16 v[42:45], v[174:177], v[218:221], v[42:45]
	v_mfma_f32_16x16x32_bf16 v[30:33], v[166:169], v[226:229], v[30:33]
	v_mfma_f32_16x16x32_bf16 v[26:29], v[174:177], v[226:229], v[26:29]
	v_mfma_f32_16x16x32_bf16 v[14:17], v[166:169], v[234:237], v[14:17]
	v_mfma_f32_16x16x32_bf16 v[10:13], v[174:177], v[234:237], v[10:13]
	v_mfma_f32_16x16x32_bf16 v[54:57], v[178:181], v[206:209], v[54:57]
	v_mfma_f32_16x16x32_bf16 v[50:53], v[186:189], v[206:209], v[50:53]
	v_mfma_f32_16x16x32_bf16 v[38:41], v[178:181], v[214:217], v[38:41]
	v_mfma_f32_16x16x32_bf16 v[34:37], v[186:189], v[214:217], v[34:37]
	v_mfma_f32_16x16x32_bf16 v[22:25], v[178:181], v[222:225], v[22:25]
	v_mfma_f32_16x16x32_bf16 v[18:21], v[186:189], v[222:225], v[18:21]
	v_mfma_f32_16x16x32_bf16 v[6:9], v[178:181], v[230:233], v[6:9]
	v_mfma_f32_16x16x32_bf16 v[2:5], v[186:189], v[230:233], v[2:5]
	v_mfma_f32_16x16x32_bf16 v[54:57], v[182:185], v[210:213], v[54:57]
	v_mfma_f32_16x16x32_bf16 v[50:53], v[202:205], v[210:213], v[50:53]
	v_mfma_f32_16x16x32_bf16 v[38:41], v[182:185], v[218:221], v[38:41]
	v_mfma_f32_16x16x32_bf16 v[34:37], v[202:205], v[218:221], v[34:37]
	v_mfma_f32_16x16x32_bf16 v[22:25], v[182:185], v[226:229], v[22:25]
	v_mfma_f32_16x16x32_bf16 v[18:21], v[202:205], v[226:229], v[18:21]
	v_mfma_f32_16x16x32_bf16 v[6:9], v[182:185], v[234:237], v[6:9]
	v_mfma_f32_16x16x32_bf16 v[2:5], v[202:205], v[234:237], v[2:5]
	s_setprio 0
	s_barrier
	s_add_i32 s22, 0, 0x18000
	v_add_u32_e32 v165, s22, v162
	s_add_i32 s23, 0, 0x1c000
	ds_read_b128 v[158:161], v165
	ds_read_b128 v[166:169], v165 offset:1024
	ds_read_b128 v[170:173], v165 offset:2048
	ds_read_b128 v[174:177], v165 offset:3072
	v_add_u32_e32 v165, s23, v162
	ds_read_b128 v[178:181], v165
	ds_read_b128 v[182:185], v165 offset:1024
	ds_read_b128 v[186:189], v165 offset:2048
	ds_read_b128 v[202:205], v165 offset:3072
	s_add_u32 s4, s28, 0xb0000
	s_addc_u32 s5, s29, 0
	s_mov_b32 m0, s37
	v_lshl_add_u64 v[246:247], s[4:5], 0, v[152:153]
	ds_read_b128 v[206:209], v164 offset:32768
	ds_read_b128 v[210:213], v164 offset:33792
	ds_read_b128 v[214:217], v164 offset:34816
	ds_read_b128 v[218:221], v164 offset:35840
	ds_read_b128 v[222:225], v164 offset:36864
	ds_read_b128 v[226:229], v164 offset:37888
	ds_read_b128 v[230:233], v164 offset:38912
	ds_read_b128 v[234:237], v164 offset:39936
	global_load_lds_dwordx4 v[246:247], off
	v_lshl_add_u64 v[246:247], s[4:5], 0, v[150:151]
	s_mov_b32 m0, s38
	s_nop 0
	global_load_lds_dwordx4 v[246:247], off
	s_waitcnt vmcnt(9)
	s_waitcnt lgkmcnt(0)
	s_barrier
	s_setprio 1
	v_mfma_f32_16x16x32_bf16 v[126:129], v[158:161], v[206:209], v[126:129]
	v_mfma_f32_16x16x32_bf16 v[122:125], v[170:173], v[206:209], v[122:125]
	v_mfma_f32_16x16x32_bf16 v[110:113], v[158:161], v[214:217], v[110:113]
	v_mfma_f32_16x16x32_bf16 v[106:109], v[170:173], v[214:217], v[106:109]
	v_mfma_f32_16x16x32_bf16 v[94:97], v[158:161], v[222:225], v[94:97]
	v_mfma_f32_16x16x32_bf16 v[90:93], v[170:173], v[222:225], v[90:93]
	v_mfma_f32_16x16x32_bf16 v[78:81], v[158:161], v[230:233], v[78:81]
	v_mfma_f32_16x16x32_bf16 v[74:77], v[170:173], v[230:233], v[74:77]
	v_mfma_f32_16x16x32_bf16 v[126:129], v[166:169], v[210:213], v[126:129]
	v_mfma_f32_16x16x32_bf16 v[122:125], v[174:177], v[210:213], v[122:125]
	v_mfma_f32_16x16x32_bf16 v[110:113], v[166:169], v[218:221], v[110:113]
	v_mfma_f32_16x16x32_bf16 v[106:109], v[174:177], v[218:221], v[106:109]
	v_mfma_f32_16x16x32_bf16 v[94:97], v[166:169], v[226:229], v[94:97]
	v_mfma_f32_16x16x32_bf16 v[90:93], v[174:177], v[226:229], v[90:93]
	v_mfma_f32_16x16x32_bf16 v[78:81], v[166:169], v[234:237], v[78:81]
	v_mfma_f32_16x16x32_bf16 v[74:77], v[174:177], v[234:237], v[74:77]
	v_mfma_f32_16x16x32_bf16 v[118:121], v[178:181], v[206:209], v[118:121]
	v_mfma_f32_16x16x32_bf16 v[114:117], v[186:189], v[206:209], v[114:117]
	v_mfma_f32_16x16x32_bf16 v[102:105], v[178:181], v[214:217], v[102:105]
	v_mfma_f32_16x16x32_bf16 v[98:101], v[186:189], v[214:217], v[98:101]
	v_mfma_f32_16x16x32_bf16 v[86:89], v[178:181], v[222:225], v[86:89]
	v_mfma_f32_16x16x32_bf16 v[82:85], v[186:189], v[222:225], v[82:85]
	v_mfma_f32_16x16x32_bf16 v[70:73], v[178:181], v[230:233], v[70:73]
	v_mfma_f32_16x16x32_bf16 v[66:69], v[186:189], v[230:233], v[66:69]
	v_mfma_f32_16x16x32_bf16 v[118:121], v[182:185], v[210:213], v[118:121]
	v_mfma_f32_16x16x32_bf16 v[114:117], v[202:205], v[210:213], v[114:117]
	v_mfma_f32_16x16x32_bf16 v[102:105], v[182:185], v[218:221], v[102:105]
	v_mfma_f32_16x16x32_bf16 v[98:101], v[202:205], v[218:221], v[98:101]
	v_mfma_f32_16x16x32_bf16 v[86:89], v[182:185], v[226:229], v[86:89]
	v_mfma_f32_16x16x32_bf16 v[82:85], v[202:205], v[226:229], v[82:85]
	v_mfma_f32_16x16x32_bf16 v[70:73], v[182:185], v[234:237], v[70:73]
	v_mfma_f32_16x16x32_bf16 v[66:69], v[202:205], v[234:237], v[66:69]
	s_setprio 0
	s_barrier
; #define PG8_STAGE(bufoff, gbase, voff) do { _Pragma("unroll") for (int _i = 0; _i < 2; ++_i) \
;         __builtin_amdgcn_global_load_lds((const unsigned*)((const char*)(gbase) + (voff)[_i]), (PG8_LAS unsigned*)(lds + (bufoff) + ldsw + _i * 8192), 16, 0, 0); } while (0)
; #define PG8_LDA(dst, b, h) do { _Pragma("unroll") for (int m = 0; m < 4; ++m) _Pragma("unroll") for (int k = 0; k < 2; ++k) dst[m][k] = *(const PG8_LAS bf16x8*)(lds + PG8_SA(b, h) + aoff + m * 2048 + k * 1024); } while (0)
; #define PG8_WAIT_V(n) asm volatile("s_waitcnt vmcnt(" #n ")" ::: "memory")
; template <class Epi, class Sched, bool ALIGN_EPI = false, bool SP2 = false>
; __device__ __forceinline__ void gemm_phase(PG8_LAS unsigned char* lds, const Gemm g, const Sched& S, const Epi& E) {
;     ...
;             PG8_LDA(At, 1, 1); PG8_STAGE(PG8_SB(1, 0), b3, voffB); PG8_STAGE(PG8_SB(1, 1), b3 + hstep, voffB); PG8_STAGE(PG8_SA(1, 0), a3, voffA);
;             PG8_WAIT_V(8); PG8_WAIT_L(0); PG8_BAR; PG8_MMA(1, 0, At, B0); PG8_MMA(1, 1, At, B1); PG8_BAR; PG8_SCHED;
;             } else {
;             PG8_LDB(B0, 0, 0); PG8_SCHED; PG8_LDA(At, 0, 0); PG8_STAGE(PG8_SA(1, 1), a1 + hstep, voffA);
;             PG8_WAIT_L(8); PG8_BAR; PG8_WAIT_L(0); PG8_MMA(0, 0, At, B0); PG8_BAR; PG8_SCHED;
;             PG8_LDB(B1, 0, 1); PG8_STAGE(PG8_SB(0, 0), b2, voffB);
;             PG8_BAR; PG8_WAIT_L(0); PG8_MMA(0, 1, At, B1); PG8_BAR;
;             PG8_LDA(At, 0, 1); PG8_STAGE(PG8_SA(0, 0), a2, voffA);
;             PG8_BAR; PG8_WAIT_L(0); PG8_MMA(1, 0, At, B0); PG8_BAR; PG8_SCHED;
;             PG8_STAGE(PG8_SB(0, 1), b2 + hstep, voffB);
;             PG8_WAIT_V(6); PG8_BAR; PG8_MMA(1, 1, At, B1); PG8_BAR;
;             PG8_LDB(B0, 1, 0); PG8_SCHED; PG8_LDA(At, 1, 0); PG8_STAGE(PG8_SA(0, 1), a2 + hstep, voffA);
;             PG8_WAIT_L(8); PG8_BAR; PG8_WAIT_L(0); PG8_MMA(0, 0, At, B0); PG8_BAR; PG8_SCHED;
;             PG8_LDB(B1, 1, 1); PG8_STAGE(PG8_SB(1, 0), b3, voffB);
;             PG8_BAR; PG8_WAIT_L(0); PG8_MMA(0, 1, At, B1); PG8_BAR;
;             PG8_LDA(At, 1, 1); PG8_STAGE(PG8_SA(1, 0), a3, voffA);
;             PG8_BAR; PG8_WAIT_L(0); PG8_MMA(1, 0, At, B0); PG8_BAR; PG8_SCHED;
;             PG8_STAGE(PG8_SB(1, 1), b3 + hstep, voffB);
;             PG8_WAIT_V(6); PG8_BAR; PG8_MMA(1, 1, At, B1); PG8_BAR;
;             }
;         }
;         if constexpr (ALIGN_EPI) { if (wr == 0) PG8_BAR; }
	s_add_i32 s4, s22, s34
	v_lshl_add_u64 v[238:239], v[238:239], 0, s[62:63]
	s_mov_b32 m0, s4
	ds_read_b128 v[206:209], v164 offset:49152
	ds_read_b128 v[210:213], v164 offset:50176
	ds_read_b128 v[214:217], v164 offset:51200
	ds_read_b128 v[218:221], v164 offset:52224
	ds_read_b128 v[222:225], v164 offset:53248
	ds_read_b128 v[226:229], v164 offset:54272
	ds_read_b128 v[230:233], v164 offset:55296
	ds_read_b128 v[234:237], v164 offset:56320
	global_load_lds_dwordx4 v[238:239], off
	s_add_i32 m0, s4, 0x2000
	s_add_u32 s4, s26, 0xb0080
	v_lshl_add_u64 v[238:239], v[240:241], 0, s[62:63]
	s_addc_u32 s5, s27, 0
	s_add_i32 s22, s23, s34
	global_load_lds_dwordx4 v[238:239], off
	v_lshl_add_u64 v[238:239], s[4:5], 0, v[152:153]
	s_mov_b32 m0, s22
	s_nop 0
	global_load_lds_dwordx4 v[238:239], off
	v_lshl_add_u64 v[238:239], s[4:5], 0, v[150:151]
	s_add_i32 m0, s22, 0x2000
	s_nop 0
	global_load_lds_dwordx4 v[238:239], off
	v_lshl_add_u64 v[238:239], v[242:243], 0, s[62:63]
	s_mov_b32 m0, s41
	s_nop 0
	global_load_lds_dwordx4 v[238:239], off
	v_lshl_add_u64 v[238:239], v[244:245], 0, s[62:63]
	s_mov_b32 m0, s42
	s_nop 0
	global_load_lds_dwordx4 v[238:239], off
	s_waitcnt vmcnt(8)
	s_waitcnt lgkmcnt(0)
	s_barrier
	s_setprio 1
	v_mfma_f32_16x16x32_bf16 v[62:65], v[158:161], v[206:209], v[62:65]
	v_mfma_f32_16x16x32_bf16 v[58:61], v[170:173], v[206:209], v[58:61]
	v_mfma_f32_16x16x32_bf16 v[46:49], v[158:161], v[214:217], v[46:49]
	v_mfma_f32_16x16x32_bf16 v[42:45], v[170:173], v[214:217], v[42:45]
	v_mfma_f32_16x16x32_bf16 v[30:33], v[158:161], v[222:225], v[30:33]
	v_mfma_f32_16x16x32_bf16 v[26:29], v[170:173], v[222:225], v[26:29]
	v_mfma_f32_16x16x32_bf16 v[14:17], v[158:161], v[230:233], v[14:17]
	v_mfma_f32_16x16x32_bf16 v[10:13], v[170:173], v[230:233], v[10:13]
	v_mfma_f32_16x16x32_bf16 v[62:65], v[166:169], v[210:213], v[62:65]
	v_mfma_f32_16x16x32_bf16 v[58:61], v[174:177], v[210:213], v[58:61]
	v_mfma_f32_16x16x32_bf16 v[46:49], v[166:169], v[218:221], v[46:49]
	v_mfma_f32_16x16x32_bf16 v[42:45], v[174:177], v[218:221], v[42:45]
	v_mfma_f32_16x16x32_bf16 v[30:33], v[166:169], v[226:229], v[30:33]
	v_mfma_f32_16x16x32_bf16 v[26:29], v[174:177], v[226:229], v[26:29]
	v_mfma_f32_16x16x32_bf16 v[14:17], v[166:169], v[234:237], v[14:17]
	v_mfma_f32_16x16x32_bf16 v[10:13], v[174:177], v[234:237], v[10:13]
	v_mfma_f32_16x16x32_bf16 v[54:57], v[178:181], v[206:209], v[54:57]
	v_mfma_f32_16x16x32_bf16 v[50:53], v[186:189], v[206:209], v[50:53]
	v_mfma_f32_16x16x32_bf16 v[38:41], v[178:181], v[214:217], v[38:41]
	v_mfma_f32_16x16x32_bf16 v[34:37], v[186:189], v[214:217], v[34:37]
	v_mfma_f32_16x16x32_bf16 v[22:25], v[178:181], v[222:225], v[22:25]
	v_mfma_f32_16x16x32_bf16 v[18:21], v[186:189], v[222:225], v[18:21]
	v_mfma_f32_16x16x32_bf16 v[6:9], v[178:181], v[230:233], v[6:9]
	v_mfma_f32_16x16x32_bf16 v[2:5], v[186:189], v[230:233], v[2:5]
	v_mfma_f32_16x16x32_bf16 v[54:57], v[182:185], v[210:213], v[54:57]
	v_mfma_f32_16x16x32_bf16 v[50:53], v[202:205], v[210:213], v[50:53]
	v_mfma_f32_16x16x32_bf16 v[38:41], v[182:185], v[218:221], v[38:41]
	v_mfma_f32_16x16x32_bf16 v[34:37], v[202:205], v[218:221], v[34:37]
	v_mfma_f32_16x16x32_bf16 v[22:25], v[182:185], v[226:229], v[22:25]
	v_mfma_f32_16x16x32_bf16 v[18:21], v[202:205], v[226:229], v[18:21]
	v_mfma_f32_16x16x32_bf16 v[6:9], v[182:185], v[234:237], v[6:9]
	v_mfma_f32_16x16x32_bf16 v[2:5], v[202:205], v[234:237], v[2:5]
	s_setprio 0
	s_barrier
	s_add_i32 s50, s50, 2
	s_add_u32 s48, s48, 0x100
	s_addc_u32 s49, s49, 0
	s_cmp_gt_u32 s50, 41
	s_mov_b64 s[22:23], s[24:25]
	s_cbranch_scc0 .LBB0_1890
	s_and_b64 vcc, exec, s[18:19]
	s_cbranch_vccz .LBB0_1893
	s_barrier

; #define PG8_STAGE(bufoff, gbase, voff) do { _Pragma("unroll") for (int _i = 0; _i < 2; ++_i) \
;         __builtin_amdgcn_global_load_lds((const unsigned*)((const char*)(gbase) + (voff)[_i]), (PG8_LAS unsigned*)(lds + (bufoff) + ldsw + _i * 8192), 16, 0, 0); } while (0)
; #define PG8_LDA(dst, b, h) do { _Pragma("unroll") for (int m = 0; m < 4; ++m) _Pragma("unroll") for (int k = 0; k < 2; ++k) dst[m][k] = *(const PG8_LAS bf16x8*)(lds + PG8_SA(b, h) + aoff + m * 2048 + k * 1024); } while (0)
; #define PG8_LDB(dst, b, h) do { _Pragma("unroll") for (int n = 0; n < 2; ++n) _Pragma("unroll") for (int k = 0; k < 2; ++k) dst[n][k] = *(const PG8_LAS bf16x8*)(lds + PG8_SB(b, h) + boff + n * 2048 + k * 1024); } while (0)
; #define PG8_MMA(ai, bj, At, Bt) do { __builtin_amdgcn_s_setprio(1); _Pragma("unroll") for (int m = 0; m < 4; ++m) _Pragma("unroll") for (int n = 0; n < 2; ++n) _Pragma("unroll") for (int k = 0; k < 2; ++k) \
;         acc[ai][bj][m][n] = __builtin_amdgcn_mfma_f32_16x16x32_bf16(Bt[n][k], At[m][k], acc[ai][bj][m][n], 0, 0, 0); __builtin_amdgcn_s_setprio(0); } while (0)
; #define PG8_WAIT_V(n) asm volatile("s_waitcnt vmcnt(" #n ")" ::: "memory")
; #define PG8_WAIT_L(n) asm volatile("s_waitcnt lgkmcnt(" #n ")" ::: "memory")
; template <class Epi, class Sched, bool ALIGN_EPI = false, bool SP2 = false>
; __device__ __forceinline__ void gemm_phase(PG8_LAS unsigned char* lds, const Gemm g, const Sched& S, const Epi& E) {
;     ...
;             const bool last = (t == nt - 2);
;             const char* a1 = cA + (size_t)(t + 1) * kstep;
;             const char* a2 = last ? nA : cA + (size_t)(t + 2) * kstep; const char* b2 = last ? nB : cB + (size_t)(t + 2) * kstep;
;             const char* a3 = a2 + kstep; const char* b3 = b2 + kstep;
;             if (last && has_next) S.a_ready(nxt);
;             if constexpr (SP2) {
;             PG8_LDB(B0, 0, 0); PG8_LDB(B1, 0, 1); PG8_SCHED; PG8_LDA(At, 0, 0); PG8_STAGE(PG8_SA(1, 1), a1 + hstep, voffA);
;             PG8_WAIT_V(8); PG8_WAIT_L(0); PG8_BAR; PG8_MMA(0, 0, At, B0); PG8_MMA(0, 1, At, B1); PG8_BAR; PG8_SCHED;
;             PG8_LDA(At, 0, 1); PG8_STAGE(PG8_SB(0, 0), b2, voffB); PG8_STAGE(PG8_SB(0, 1), b2 + hstep, voffB); PG8_STAGE(PG8_SA(0, 0), a2, voffA);
;             PG8_WAIT_V(8); PG8_WAIT_L(0); PG8_BAR; PG8_MMA(1, 0, At, B0); PG8_MMA(1, 1, At, B1); PG8_BAR; PG8_SCHED;
.LBB0_1969:
	ds_read_b128 v[150:153], v144
	ds_read_b128 v[154:157], v144 offset:1024
	ds_read_b128 v[158:161], v144 offset:2048
	ds_read_b128 v[162:165], v144 offset:3072
	ds_read_b128 v[166:169], v145
	ds_read_b128 v[170:173], v145 offset:1024
	ds_read_b128 v[174:177], v145 offset:2048
	ds_read_b128 v[178:181], v145 offset:3072
	s_add_u32 s16, s12, s14
	s_addc_u32 s17, s13, s15
	s_add_u32 s16, s16, 0x3d00100
	s_addc_u32 s17, s17, 0
	s_add_u32 s43, s28, s14
	s_addc_u32 s44, s29, s15
	s_cmpk_eq_i32 s14, 0xa00
	s_cselect_b32 s19, s7, s17
	s_cselect_b32 s18, s6, s16
	s_cselect_b32 s17, s9, s44
	s_cselect_b32 s16, s8, s43
	s_mov_b32 m0, s31
	v_lshl_add_u64 v[220:221], v[138:139], 0, s[14:15]
	ds_read_b128 v[182:185], v146
	ds_read_b128 v[186:189], v146 offset:1024
	ds_read_b128 v[196:199], v146 offset:2048
	ds_read_b128 v[200:203], v146 offset:3072
	ds_read_b128 v[204:207], v146 offset:4096
	ds_read_b128 v[208:211], v146 offset:5120
	ds_read_b128 v[212:215], v146 offset:6144
	ds_read_b128 v[216:219], v146 offset:7168
	global_load_lds_dwordx4 v[220:221], off
	v_lshl_add_u64 v[220:221], v[140:141], 0, s[14:15]
	s_mov_b32 m0, s34
	s_nop 0
	global_load_lds_dwordx4 v[220:221], off
	s_waitcnt vmcnt(8)
	s_waitcnt lgkmcnt(0)
	s_barrier
	s_setprio 1
	v_mfma_f32_16x16x32_bf16 v[124:127], v[150:153], v[182:185], v[124:127]
	v_mfma_f32_16x16x32_bf16 v[120:123], v[158:161], v[182:185], v[120:123]
	v_mfma_f32_16x16x32_bf16 v[116:119], v[150:153], v[196:199], v[116:119]
	v_mfma_f32_16x16x32_bf16 v[112:115], v[158:161], v[196:199], v[112:115]
	v_mfma_f32_16x16x32_bf16 v[104:107], v[150:153], v[204:207], v[104:107]
	v_mfma_f32_16x16x32_bf16 v[96:99], v[158:161], v[204:207], v[96:99]
	v_mfma_f32_16x16x32_bf16 v[88:91], v[150:153], v[212:215], v[88:91]
	v_mfma_f32_16x16x32_bf16 v[80:83], v[158:161], v[212:215], v[80:83]
	v_mfma_f32_16x16x32_bf16 v[124:127], v[154:157], v[186:189], v[124:127]
	v_mfma_f32_16x16x32_bf16 v[120:123], v[162:165], v[186:189], v[120:123]
	v_mfma_f32_16x16x32_bf16 v[116:119], v[154:157], v[200:203], v[116:119]
	v_mfma_f32_16x16x32_bf16 v[112:115], v[162:165], v[200:203], v[112:115]
	v_mfma_f32_16x16x32_bf16 v[104:107], v[154:157], v[208:211], v[104:107]
	v_mfma_f32_16x16x32_bf16 v[96:99], v[162:165], v[208:211], v[96:99]
	v_mfma_f32_16x16x32_bf16 v[88:91], v[154:157], v[216:219], v[88:91]
	v_mfma_f32_16x16x32_bf16 v[80:83], v[162:165], v[216:219], v[80:83]
	v_mfma_f32_16x16x32_bf16 v[108:111], v[166:169], v[182:185], v[108:111]
	v_mfma_f32_16x16x32_bf16 v[100:103], v[174:177], v[182:185], v[100:103]
	v_mfma_f32_16x16x32_bf16 v[92:95], v[166:169], v[196:199], v[92:95]
	v_mfma_f32_16x16x32_bf16 v[84:87], v[174:177], v[196:199], v[84:87]
	v_mfma_f32_16x16x32_bf16 v[76:79], v[166:169], v[204:207], v[76:79]
	v_mfma_f32_16x16x32_bf16 v[72:75], v[174:177], v[204:207], v[72:75]
	v_mfma_f32_16x16x32_bf16 v[68:71], v[166:169], v[212:215], v[68:71]
	v_mfma_f32_16x16x32_bf16 v[64:67], v[174:177], v[212:215], v[64:67]
	v_mfma_f32_16x16x32_bf16 v[108:111], v[170:173], v[186:189], v[108:111]
	v_mfma_f32_16x16x32_bf16 v[100:103], v[178:181], v[186:189], v[100:103]
	v_mfma_f32_16x16x32_bf16 v[92:95], v[170:173], v[200:203], v[92:95]
	v_mfma_f32_16x16x32_bf16 v[84:87], v[178:181], v[200:203], v[84:87]
	v_mfma_f32_16x16x32_bf16 v[76:79], v[170:173], v[208:211], v[76:79]
	v_mfma_f32_16x16x32_bf16 v[72:75], v[178:181], v[208:211], v[72:75]
	v_mfma_f32_16x16x32_bf16 v[68:71], v[170:173], v[216:219], v[68:71]
	v_mfma_f32_16x16x32_bf16 v[64:67], v[178:181], v[216:219], v[64:67]
	s_setprio 0
	s_barrier
	s_mov_b32 m0, s35
	v_lshl_add_u64 v[220:221], s[16:17], 0, v[136:137]
	s_add_u32 s44, s16, 0x58000
	ds_read_b128 v[182:185], v146 offset:16384
	ds_read_b128 v[186:189], v146 offset:17408
	ds_read_b128 v[196:199], v146 offset:18432
	ds_read_b128 v[200:203], v146 offset:19456
	ds_read_b128 v[204:207], v146 offset:20480
	ds_read_b128 v[208:211], v146 offset:21504
	ds_read_b128 v[212:215], v146 offset:22528
	ds_read_b128 v[216:219], v146 offset:23552
	global_load_lds_dwordx4 v[220:221], off
	v_lshl_add_u64 v[222:223], s[16:17], 0, v[128:129]
	s_mov_b32 m0, s36
	s_addc_u32 s45, s17, 0
	global_load_lds_dwordx4 v[222:223], off
	v_lshl_add_u64 v[224:225], s[44:45], 0, v[136:137]
	s_mov_b32 m0, s37
	v_lshl_add_u64 v[226:227], s[18:19], 0, v[128:129]
	global_load_lds_dwordx4 v[224:225], off
	v_lshl_add_u64 v[224:225], s[44:45], 0, v[128:129]
	s_mov_b32 m0, s38
	s_nop 0
	global_load_lds_dwordx4 v[224:225], off
	v_lshl_add_u64 v[224:225], s[18:19], 0, v[136:137]
	s_mov_b32 m0, s5
	s_nop 0
	global_load_lds_dwordx4 v[224:225], off
	s_mov_b32 m0, s20
	s_nop 0
	global_load_lds_dwordx4 v[226:227], off
	s_waitcnt vmcnt(8)
	s_waitcnt lgkmcnt(0)
	s_barrier
; #define PG8_STAGE(bufoff, gbase, voff) do { _Pragma("unroll") for (int _i = 0; _i < 2; ++_i) \
;         __builtin_amdgcn_global_load_lds((const unsigned*)((const char*)(gbase) + (voff)[_i]), (PG8_LAS unsigned*)(lds + (bufoff) + ldsw + _i * 8192), 16, 0, 0); } while (0)
; #define PG8_LDA(dst, b, h) do { _Pragma("unroll") for (int m = 0; m < 4; ++m) _Pragma("unroll") for (int k = 0; k < 2; ++k) dst[m][k] = *(const PG8_LAS bf16x8*)(lds + PG8_SA(b, h) + aoff + m * 2048 + k * 1024); } while (0)
; #define PG8_LDB(dst, b, h) do { _Pragma("unroll") for (int n = 0; n < 2; ++n) _Pragma("unroll") for (int k = 0; k < 2; ++k) dst[n][k] = *(const PG8_LAS bf16x8*)(lds + PG8_SB(b, h) + boff + n * 2048 + k * 1024); } while (0)
; #define PG8_MMA(ai, bj, At, Bt) do { __builtin_amdgcn_s_setprio(1); _Pragma("unroll") for (int m = 0; m < 4; ++m) _Pragma("unroll") for (int n = 0; n < 2; ++n) _Pragma("unroll") for (int k = 0; k < 2; ++k) \
;         acc[ai][bj][m][n] = __builtin_amdgcn_mfma_f32_16x16x32_bf16(Bt[n][k], At[m][k], acc[ai][bj][m][n], 0, 0, 0); __builtin_amdgcn_s_setprio(0); } while (0)
; #define PG8_WAIT_V(n) asm volatile("s_waitcnt vmcnt(" #n ")" ::: "memory")
; #define PG8_WAIT_L(n) asm volatile("s_waitcnt lgkmcnt(" #n ")" ::: "memory")
; #define PG8_BAR __builtin_amdgcn_s_barrier()
; #define PG8_SCHED __builtin_amdgcn_sched_barrier(0)
; template <class Epi, class Sched, bool ALIGN_EPI = false, bool SP2 = false>
; __device__ __forceinline__ void gemm_phase(PG8_LAS unsigned char* lds, const Gemm g, const Sched& S, const Epi& E) {
;     ...
;             PG8_WAIT_V(8); PG8_WAIT_L(0); PG8_BAR; PG8_MMA(1, 0, At, B0); PG8_MMA(1, 1, At, B1); PG8_BAR; PG8_SCHED;
;             PG8_LDB(B0, 1, 0); PG8_LDB(B1, 1, 1); PG8_SCHED; PG8_LDA(At, 1, 0); PG8_STAGE(PG8_SA(0, 1), a2 + hstep, voffA);
;             PG8_WAIT_V(8); PG8_WAIT_L(0); PG8_BAR; PG8_MMA(0, 0, At, B0); PG8_MMA(0, 1, At, B1); PG8_BAR; PG8_SCHED;
	s_setprio 1
	v_mfma_f32_16x16x32_bf16 v[60:63], v[150:153], v[182:185], v[60:63]
	v_mfma_f32_16x16x32_bf16 v[56:59], v[158:161], v[182:185], v[56:59]
	v_mfma_f32_16x16x32_bf16 v[52:55], v[150:153], v[196:199], v[52:55]
	v_mfma_f32_16x16x32_bf16 v[48:51], v[158:161], v[196:199], v[48:51]
	v_mfma_f32_16x16x32_bf16 v[40:43], v[150:153], v[204:207], v[40:43]
	v_mfma_f32_16x16x32_bf16 v[32:35], v[158:161], v[204:207], v[32:35]
	v_mfma_f32_16x16x32_bf16 v[24:27], v[150:153], v[212:215], v[24:27]
	v_mfma_f32_16x16x32_bf16 v[16:19], v[158:161], v[212:215], v[16:19]
	v_mfma_f32_16x16x32_bf16 v[60:63], v[154:157], v[186:189], v[60:63]
	v_mfma_f32_16x16x32_bf16 v[56:59], v[162:165], v[186:189], v[56:59]
	v_mfma_f32_16x16x32_bf16 v[52:55], v[154:157], v[200:203], v[52:55]
	v_mfma_f32_16x16x32_bf16 v[48:51], v[162:165], v[200:203], v[48:51]
	v_mfma_f32_16x16x32_bf16 v[40:43], v[154:157], v[208:211], v[40:43]
	v_mfma_f32_16x16x32_bf16 v[32:35], v[162:165], v[208:211], v[32:35]
	v_mfma_f32_16x16x32_bf16 v[24:27], v[154:157], v[216:219], v[24:27]
	v_mfma_f32_16x16x32_bf16 v[16:19], v[162:165], v[216:219], v[16:19]
	v_mfma_f32_16x16x32_bf16 v[44:47], v[166:169], v[182:185], v[44:47]
	v_mfma_f32_16x16x32_bf16 v[36:39], v[174:177], v[182:185], v[36:39]
	v_mfma_f32_16x16x32_bf16 v[28:31], v[166:169], v[196:199], v[28:31]
	v_mfma_f32_16x16x32_bf16 v[20:23], v[174:177], v[196:199], v[20:23]
	v_mfma_f32_16x16x32_bf16 v[12:15], v[166:169], v[204:207], v[12:15]
	v_mfma_f32_16x16x32_bf16 v[8:11], v[174:177], v[204:207], v[8:11]
	v_mfma_f32_16x16x32_bf16 v[4:7], v[166:169], v[212:215], v[4:7]
	v_mfma_f32_16x16x32_bf16 v[0:3], v[174:177], v[212:215], v[0:3]
	v_mfma_f32_16x16x32_bf16 v[44:47], v[170:173], v[186:189], v[44:47]
	v_mfma_f32_16x16x32_bf16 v[36:39], v[178:181], v[186:189], v[36:39]
	v_mfma_f32_16x16x32_bf16 v[28:31], v[170:173], v[200:203], v[28:31]
	v_mfma_f32_16x16x32_bf16 v[20:23], v[178:181], v[200:203], v[20:23]
	v_mfma_f32_16x16x32_bf16 v[12:15], v[170:173], v[208:211], v[12:15]
	v_mfma_f32_16x16x32_bf16 v[8:11], v[178:181], v[208:211], v[8:11]
	v_mfma_f32_16x16x32_bf16 v[4:7], v[170:173], v[216:219], v[4:7]
	v_mfma_f32_16x16x32_bf16 v[0:3], v[178:181], v[216:219], v[0:3]
	s_setprio 0
	s_barrier
	ds_read_b128 v[150:153], v147
	ds_read_b128 v[154:157], v147 offset:1024
	ds_read_b128 v[158:161], v147 offset:2048
	ds_read_b128 v[162:165], v147 offset:3072
	ds_read_b128 v[166:169], v148
	ds_read_b128 v[170:173], v148 offset:1024
	ds_read_b128 v[174:177], v148 offset:2048
	ds_read_b128 v[178:181], v148 offset:3072
	s_add_u32 s18, s18, 0x58000
	s_addc_u32 s19, s19, 0
	s_mov_b32 m0, s21
	v_lshl_add_u64 v[228:229], s[18:19], 0, v[136:137]
	ds_read_b128 v[182:185], v146 offset:32768
	ds_read_b128 v[186:189], v146 offset:33792
	ds_read_b128 v[196:199], v146 offset:34816
	ds_read_b128 v[200:203], v146 offset:35840
	ds_read_b128 v[204:207], v146 offset:36864
	ds_read_b128 v[208:211], v146 offset:37888
	ds_read_b128 v[212:215], v146 offset:38912
	ds_read_b128 v[216:219], v146 offset:39936
	global_load_lds_dwordx4 v[228:229], off
	v_lshl_add_u64 v[228:229], s[18:19], 0, v[128:129]
	s_mov_b32 m0, s22
	s_nop 0
	global_load_lds_dwordx4 v[228:229], off
	s_waitcnt vmcnt(8)
	s_waitcnt lgkmcnt(0)
	s_barrier
	s_setprio 1
	v_mfma_f32_16x16x32_bf16 v[124:127], v[150:153], v[182:185], v[124:127]
	v_mfma_f32_16x16x32_bf16 v[120:123], v[158:161], v[182:185], v[120:123]
	v_mfma_f32_16x16x32_bf16 v[116:119], v[150:153], v[196:199], v[116:119]
	v_mfma_f32_16x16x32_bf16 v[112:115], v[158:161], v[196:199], v[112:115]
	v_mfma_f32_16x16x32_bf16 v[104:107], v[150:153], v[204:207], v[104:107]
	v_mfma_f32_16x16x32_bf16 v[96:99], v[158:161], v[204:207], v[96:99]
	v_mfma_f32_16x16x32_bf16 v[88:91], v[150:153], v[212:215], v[88:91]
	v_mfma_f32_16x16x32_bf16 v[80:83], v[158:161], v[212:215], v[80:83]
	v_mfma_f32_16x16x32_bf16 v[124:127], v[154:157], v[186:189], v[124:127]
	v_mfma_f32_16x16x32_bf16 v[120:123], v[162:165], v[186:189], v[120:123]
	v_mfma_f32_16x16x32_bf16 v[116:119], v[154:157], v[200:203], v[116:119]
	v_mfma_f32_16x16x32_bf16 v[112:115], v[162:165], v[200:203], v[112:115]
	v_mfma_f32_16x16x32_bf16 v[104:107], v[154:157], v[208:211], v[104:107]
	v_mfma_f32_16x16x32_bf16 v[96:99], v[162:165], v[208:211], v[96:99]
	v_mfma_f32_16x16x32_bf16 v[88:91], v[154:157], v[216:219], v[88:91]
	v_mfma_f32_16x16x32_bf16 v[80:83], v[162:165], v[216:219], v[80:83]
	v_mfma_f32_16x16x32_bf16 v[108:111], v[166:169], v[182:185], v[108:111]
	v_mfma_f32_16x16x32_bf16 v[100:103], v[174:177], v[182:185], v[100:103]
	v_mfma_f32_16x16x32_bf16 v[92:95], v[166:169], v[196:199], v[92:95]
	v_mfma_f32_16x16x32_bf16 v[84:87], v[174:177], v[196:199], v[84:87]
	v_mfma_f32_16x16x32_bf16 v[76:79], v[166:169], v[204:207], v[76:79]
	v_mfma_f32_16x16x32_bf16 v[72:75], v[174:177], v[204:207], v[72:75]
	v_mfma_f32_16x16x32_bf16 v[68:71], v[166:169], v[212:215], v[68:71]
	v_mfma_f32_16x16x32_bf16 v[64:67], v[174:177], v[212:215], v[64:67]
	v_mfma_f32_16x16x32_bf16 v[108:111], v[170:173], v[186:189], v[108:111]
	v_mfma_f32_16x16x32_bf16 v[100:103], v[178:181], v[186:189], v[100:103]
	v_mfma_f32_16x16x32_bf16 v[92:95], v[170:173], v[200:203], v[92:95]
	v_mfma_f32_16x16x32_bf16 v[84:87], v[178:181], v[200:203], v[84:87]
	v_mfma_f32_16x16x32_bf16 v[76:79], v[170:173], v[208:211], v[76:79]
	v_mfma_f32_16x16x32_bf16 v[72:75], v[178:181], v[208:211], v[72:75]
	v_mfma_f32_16x16x32_bf16 v[68:71], v[170:173], v[216:219], v[68:71]
	v_mfma_f32_16x16x32_bf16 v[64:67], v[178:181], v[216:219], v[64:67]
	s_setprio 0
	s_barrier
; #define PG8_STAGE(bufoff, gbase, voff) do { _Pragma("unroll") for (int _i = 0; _i < 2; ++_i) \
;         __builtin_amdgcn_global_load_lds((const unsigned*)((const char*)(gbase) + (voff)[_i]), (PG8_LAS unsigned*)(lds + (bufoff) + ldsw + _i * 8192), 16, 0, 0); } while (0)
; #define PG8_LDA(dst, b, h) do { _Pragma("unroll") for (int m = 0; m < 4; ++m) _Pragma("unroll") for (int k = 0; k < 2; ++k) dst[m][k] = *(const PG8_LAS bf16x8*)(lds + PG8_SA(b, h) + aoff + m * 2048 + k * 1024); } while (0)
; #define PG8_WAIT_V(n) asm volatile("s_waitcnt vmcnt(" #n ")" ::: "memory")
; template <class Epi, class Sched, bool ALIGN_EPI = false, bool SP2 = false>
; __device__ __forceinline__ void gemm_phase(PG8_LAS unsigned char* lds, const Gemm g, const Sched& S, const Epi& E) {
;     ...
;             PG8_LDA(At, 1, 1); PG8_STAGE(PG8_SB(1, 0), b3, voffB); PG8_STAGE(PG8_SB(1, 1), b3 + hstep, voffB); PG8_STAGE(PG8_SA(1, 0), a3, voffA);
;             PG8_WAIT_V(8); PG8_WAIT_L(0); PG8_BAR; PG8_MMA(1, 0, At, B0); PG8_MMA(1, 1, At, B1); PG8_BAR; PG8_SCHED;
;             } else {
;             PG8_LDB(B0, 0, 0); PG8_SCHED; PG8_LDA(At, 0, 0); PG8_STAGE(PG8_SA(1, 1), a1 + hstep, voffA);
;             PG8_WAIT_L(8); PG8_BAR; PG8_WAIT_L(0); PG8_MMA(0, 0, At, B0); PG8_BAR; PG8_SCHED;
;             PG8_LDB(B1, 0, 1); PG8_STAGE(PG8_SB(0, 0), b2, voffB);
;             PG8_BAR; PG8_WAIT_L(0); PG8_MMA(0, 1, At, B1); PG8_BAR;
;             PG8_LDA(At, 0, 1); PG8_STAGE(PG8_SA(0, 0), a2, voffA);
;             PG8_BAR; PG8_WAIT_L(0); PG8_MMA(1, 0, At, B0); PG8_BAR; PG8_SCHED;
;             PG8_STAGE(PG8_SB(0, 1), b2 + hstep, voffB);
;             PG8_WAIT_V(6); PG8_BAR; PG8_MMA(1, 1, At, B1); PG8_BAR;
;             PG8_LDB(B0, 1, 0); PG8_SCHED; PG8_LDA(At, 1, 0); PG8_STAGE(PG8_SA(0, 1), a2 + hstep, voffA);
;             PG8_WAIT_L(8); PG8_BAR; PG8_WAIT_L(0); PG8_MMA(0, 0, At, B0); PG8_BAR; PG8_SCHED;
;             PG8_LDB(B1, 1, 1); PG8_STAGE(PG8_SB(1, 0), b3, voffB);
;             PG8_BAR; PG8_WAIT_L(0); PG8_MMA(0, 1, At, B1); PG8_BAR;
;             PG8_LDA(At, 1, 1); PG8_STAGE(PG8_SA(1, 0), a3, voffA);
;             PG8_BAR; PG8_WAIT_L(0); PG8_MMA(1, 0, At, B0); PG8_BAR; PG8_SCHED;
;             PG8_STAGE(PG8_SB(1, 1), b3 + hstep, voffB);
;             PG8_WAIT_V(6); PG8_BAR; PG8_MMA(1, 1, At, B1); PG8_BAR;
;             }
;         }
;         if constexpr (ALIGN_EPI) { if (wr == 0) PG8_BAR; }
	s_mov_b32 m0, s39
	v_lshl_add_u64 v[220:221], v[220:221], 0, s[10:11]
	s_add_u32 s16, s16, 0x58080
	ds_read_b128 v[182:185], v146 offset:49152
	ds_read_b128 v[186:189], v146 offset:50176
	ds_read_b128 v[196:199], v146 offset:51200
	ds_read_b128 v[200:203], v146 offset:52224
	ds_read_b128 v[204:207], v146 offset:53248
	ds_read_b128 v[208:211], v146 offset:54272
	ds_read_b128 v[212:215], v146 offset:55296
	ds_read_b128 v[216:219], v146 offset:56320
	global_load_lds_dwordx4 v[220:221], off
	v_lshl_add_u64 v[220:221], v[222:223], 0, s[10:11]
	s_mov_b32 m0, s40
	s_addc_u32 s17, s17, 0
	global_load_lds_dwordx4 v[220:221], off
	v_lshl_add_u64 v[220:221], s[16:17], 0, v[136:137]
	s_mov_b32 m0, s41
	s_nop 0
	global_load_lds_dwordx4 v[220:221], off
	v_lshl_add_u64 v[220:221], s[16:17], 0, v[128:129]
	s_mov_b32 m0, s42
	s_nop 0
	global_load_lds_dwordx4 v[220:221], off
	v_lshl_add_u64 v[220:221], v[224:225], 0, s[10:11]
	s_mov_b32 m0, s26
	s_nop 0
	global_load_lds_dwordx4 v[220:221], off
	v_lshl_add_u64 v[220:221], v[226:227], 0, s[10:11]
	s_mov_b32 m0, s27
	s_nop 0
	global_load_lds_dwordx4 v[220:221], off
	s_waitcnt vmcnt(8)
	s_waitcnt lgkmcnt(0)
	s_barrier
	s_setprio 1
	v_mfma_f32_16x16x32_bf16 v[60:63], v[150:153], v[182:185], v[60:63]
	v_mfma_f32_16x16x32_bf16 v[56:59], v[158:161], v[182:185], v[56:59]
	v_mfma_f32_16x16x32_bf16 v[52:55], v[150:153], v[196:199], v[52:55]
	v_mfma_f32_16x16x32_bf16 v[48:51], v[158:161], v[196:199], v[48:51]
	v_mfma_f32_16x16x32_bf16 v[40:43], v[150:153], v[204:207], v[40:43]
	v_mfma_f32_16x16x32_bf16 v[32:35], v[158:161], v[204:207], v[32:35]
	v_mfma_f32_16x16x32_bf16 v[24:27], v[150:153], v[212:215], v[24:27]
	v_mfma_f32_16x16x32_bf16 v[16:19], v[158:161], v[212:215], v[16:19]
	v_mfma_f32_16x16x32_bf16 v[60:63], v[154:157], v[186:189], v[60:63]
	v_mfma_f32_16x16x32_bf16 v[56:59], v[162:165], v[186:189], v[56:59]
	v_mfma_f32_16x16x32_bf16 v[52:55], v[154:157], v[200:203], v[52:55]
	v_mfma_f32_16x16x32_bf16 v[48:51], v[162:165], v[200:203], v[48:51]
	v_mfma_f32_16x16x32_bf16 v[40:43], v[154:157], v[208:211], v[40:43]
	v_mfma_f32_16x16x32_bf16 v[32:35], v[162:165], v[208:211], v[32:35]
	v_mfma_f32_16x16x32_bf16 v[24:27], v[154:157], v[216:219], v[24:27]
	v_mfma_f32_16x16x32_bf16 v[16:19], v[162:165], v[216:219], v[16:19]
	v_mfma_f32_16x16x32_bf16 v[44:47], v[166:169], v[182:185], v[44:47]
	v_mfma_f32_16x16x32_bf16 v[36:39], v[174:177], v[182:185], v[36:39]
	v_mfma_f32_16x16x32_bf16 v[28:31], v[166:169], v[196:199], v[28:31]
	v_mfma_f32_16x16x32_bf16 v[20:23], v[174:177], v[196:199], v[20:23]
	v_mfma_f32_16x16x32_bf16 v[12:15], v[166:169], v[204:207], v[12:15]
	v_mfma_f32_16x16x32_bf16 v[8:11], v[174:177], v[204:207], v[8:11]
	v_mfma_f32_16x16x32_bf16 v[4:7], v[166:169], v[212:215], v[4:7]
	v_mfma_f32_16x16x32_bf16 v[0:3], v[174:177], v[212:215], v[0:3]
	v_mfma_f32_16x16x32_bf16 v[44:47], v[170:173], v[186:189], v[44:47]
	v_mfma_f32_16x16x32_bf16 v[36:39], v[178:181], v[186:189], v[36:39]
	v_mfma_f32_16x16x32_bf16 v[28:31], v[170:173], v[200:203], v[28:31]
	v_mfma_f32_16x16x32_bf16 v[20:23], v[178:181], v[200:203], v[20:23]
	v_mfma_f32_16x16x32_bf16 v[12:15], v[170:173], v[208:211], v[12:15]
	v_mfma_f32_16x16x32_bf16 v[8:11], v[178:181], v[208:211], v[8:11]
	v_mfma_f32_16x16x32_bf16 v[4:7], v[170:173], v[216:219], v[4:7]
	v_mfma_f32_16x16x32_bf16 v[0:3], v[178:181], v[216:219], v[0:3]
	s_setprio 0
	s_barrier
	s_add_i32 s30, s30, 2
	s_add_u32 s14, s14, 0x100
	s_addc_u32 s15, s15, 0
	s_cmp_gt_u32 s30, 19
	s_cbranch_scc0 .LBB0_1969
	s_cmpk_lt_u32 s4, 0x100
	s_cbranch_scc0 .LBB0_1972
	s_barrier
